# mixed round: 260 gate-column tiles deferred behind barrier 2 (tile CUs / sample CUs), 4 of them in phase 3 from a copy of their XB rows; P1 = 8 full rounds
# baseline (speedup 1.0000x reference)
; #define TILE_MN(t, M0, N0) do { int pan_ = (t) / (mtiles * 8); if (pan_ >= npan) pan_ = npan - 1; const int pw_ = (pan_ == npan - 1) ? ntiles - 8 * pan_ : 8; const int loc_ = (t) - pan_ * mtiles * 8; \
;         M0 = (loc_ / pw_) * 128; N0 = (8 * pan_ + loc_ % pw_) * 128; } while (0)
; template <class Epi>
; DI void gemm_phase(const u16* __restrict__ A, const u16* __restrict__ B, int mtiles, int ntiles, char* lds, const Epi& epi) {
;     const int ntile = mtiles * ntiles;
;     const int vb = (blockIdx.x & 7) * (gridDim.x >> 3) + (blockIdx.x >> 3);
;     const int npan = ntiles >> 3;
;     int tile = vb; if (tile >= ntile) return;
;     ...
;     int m0, n0; TILE_MN(tile, m0, n0);
;     {
;         const int lane = threadIdx.x & 63, wave = __builtin_amdgcn_readfirstlane(threadIdx.x >> 6);
;         unsigned soff[4];
; #pragma unroll
;         for (int i = 0; i < 4; ++i) { const int row = 8 * (i * 4 + wave) + (lane >> 3); const int ch = (lane & 7) ^ ((row >> 1) & 7); soff[i] = (unsigned)(row * 1024 + ch * 8); }
;         GSTAGE(0, 0, A + (size_t)m0 * 1024, B + (size_t)n0 * 1024);
;     }
.LBB0_94:
	s_mov_b32 s100, 0
	v_writelane_b32 v236, s39, 4
	s_or_b64 exec, exec, s[4:5]
	s_waitcnt lgkmcnt(0)
	s_barrier
	s_load_dword s95, s[0:1], 0xc8
	s_and_b32 s4, s33, 7
	s_add_u32 s0, s0, 0xc8
	s_addc_u32 s1, s1, 0
	v_writelane_b32 v236, s0, 5
	s_nop 1
	v_writelane_b32 v236, s1, 6
	s_waitcnt lgkmcnt(0)
	s_lshr_b32 s0, s95, 3
	s_mul_i32 s0, s0, s4
	s_lshr_b32 s1, s33, 3
	s_add_i32 s0, s0, s1
	v_writelane_b32 v236, s0, 7
	s_cmpk_gt_i32 s0, 0x1103
	v_writelane_b32 v236, s95, 8
	s_cbranch_scc1 .LBB0_144
	v_readlane_b32 s33, v236, 7
	s_mov_b32 s96, s33
	s_cmpk_lt_i32 s33, 0xe97
	s_cbranch_scc1 .Lrm_done_m0
	s_cmpk_lt_i32 s33, 0x1000
	s_cbranch_scc0 .Lrm_def_m0
	s_add_i32 s96, s33, 0x104
	s_cmpk_lt_i32 s33, 0xfdc
	s_cbranch_scc0 .Lrm_done_m0
	s_sub_i32 s97, s33, 0xe97
	s_mul_i32 s97, s97, 0x3334
	s_lshr_b32 s97, s97, 16
	s_lshl_b32 s97, s97, 2
	s_add_i32 s96, s33, s97
	s_branch .Lrm_done_m0
.Lrm_def_m0:
	s_sub_i32 s97, s33, 0x1000
	s_lshr_b32 s98, s97, 2
	s_mul_i32 s98, s98, 9
	s_and_b32 s96, s97, 3
	s_add_i32 s98, s98, s96
	s_add_i32 s98, s98, 0xea5
	s_add_i32 s96, s96, 0xe9c
	s_cmpk_lt_i32 s97, 0x100
	s_cselect_b32 s96, s98, s96
.Lrm_done_m0:
	s_add_u32 s10, s54, 0x2100000
	s_mul_hi_i32 s0, s96, 0x3e0f83e1
	s_addc_u32 s11, s55, 0
	s_lshr_b32 s1, s0, 31
	s_ashr_i32 s0, s0, 8
	s_add_i32 s0, s0, s1
	s_cmpk_lt_i32 s96, 0x1080
	s_cselect_b32 s0, s0, 3
	s_cmp_eq_u32 s0, 3
	s_cselect_b32 s1, 9, 8
	v_cvt_f32_ubyte0_e32 v2, s1
	v_rcp_iflag_f32_e32 v2, v2
	s_sub_i32 s7, 0, s1
	s_mul_i32 s4, s0, 0xfffffbe0
	s_add_i32 s4, s4, s96
	v_mul_f32_e32 v2, 0x4f7ffffe, v2
	v_cvt_u32_f32_e32 v2, v2
	s_abs_i32 s6, s4
	s_ashr_i32 s5, s4, 31
	v_mov_b32_e32 v75, 0
	v_readfirstlane_b32 s8, v2
	s_mul_i32 s7, s7, s8
	s_mul_hi_u32 s7, s8, s7
	s_add_i32 s8, s8, s7
	s_mul_hi_u32 s7, s6, s8
	s_mul_i32 s8, s7, s1
	s_sub_i32 s6, s6, s8
	s_add_i32 s8, s7, 1
	s_sub_i32 s9, s6, s1
	s_cmp_ge_u32 s6, s1
	s_cselect_b32 s7, s8, s7
	s_cselect_b32 s6, s9, s6
	s_add_i32 s8, s7, 1
	s_cmp_ge_u32 s6, s1
	s_cselect_b32 s6, s8, s7
	s_xor_b32 s6, s6, s5
	s_sub_i32 s5, s6, s5
	s_mul_i32 s1, s5, s1
	s_sub_i32 s1, s4, s1
	v_readfirstlane_b32 s4, v0
	s_lshl_b32 s82, s5, 7
	s_lshl_b32 s1, s1, 7
	s_lshr_b32 s6, s4, 6
	v_bfe_u32 v2, v0, 3, 3
	s_lshl_b32 s0, s0, 10
	s_ashr_i32 s83, s82, 31
	v_lshl_or_b32 v2, s6, 3, v2
	s_add_i32 s0, s1, s0
	s_lshl_b64 s[4:5], s[82:83], 11
	v_lshrrev_b32_e32 v3, 1, v2
	s_add_u32 s4, s54, s4
	v_xor_b32_e32 v3, v3, v0
	s_addc_u32 s5, s55, s5
	s_ashr_i32 s1, s0, 31
	s_lshl_b32 s8, s6, 10
	s_lshl_b64 s[6:7], s[0:1], 11
	v_lshlrev_b32_e32 v3, 4, v3
	s_add_u32 s6, s10, s6
	v_and_b32_e32 v3, 0x70, v3
	v_add_u32_e32 v4, 32, v2
	s_addc_u32 s7, s11, s7
	v_lshl_or_b32 v74, v2, 11, v3
	s_add_i32 s1, s8, 0
	v_lshrrev_b32_e32 v5, 1, v4
	v_add_u32_e32 v6, 64, v2
	v_add_u32_e32 v8, 0x60, v2
	v_lshl_add_u64 v[2:3], s[4:5], 0, v[74:75]
	s_mov_b32 m0, s1
	v_xor_b32_e32 v5, v5, v0
	global_load_lds_dwordx4 v[2:3], off
	v_lshl_add_u64 v[2:3], s[6:7], 0, v[74:75]
	s_add_i32 m0, s1, 0x4000
	v_lshrrev_b32_e32 v7, 1, v6
	global_load_lds_dwordx4 v[2:3], off
	v_lshlrev_b32_e32 v2, 4, v5
	v_and_b32_e32 v2, 0x70, v2
	v_lshl_or_b32 v74, v4, 11, v2
	v_lshl_add_u64 v[2:3], s[4:5], 0, v[74:75]
	s_add_i32 m0, s1, 0x1000
	v_xor_b32_e32 v7, v7, v0
	global_load_lds_dwordx4 v[2:3], off
	v_lshl_add_u64 v[2:3], s[6:7], 0, v[74:75]
	s_add_i32 m0, s1, 0x5000
	v_lshrrev_b32_e32 v9, 1, v8
	global_load_lds_dwordx4 v[2:3], off
	v_lshlrev_b32_e32 v2, 4, v7
	v_and_b32_e32 v2, 0x70, v2
	v_lshl_or_b32 v74, v6, 11, v2
	v_lshl_add_u64 v[2:3], s[4:5], 0, v[74:75]
	s_add_i32 m0, s1, 0x2000
	v_xor_b32_e32 v9, v9, v0
	global_load_lds_dwordx4 v[2:3], off
	v_lshl_add_u64 v[2:3], s[6:7], 0, v[74:75]
	s_add_i32 m0, s1, 0x6000
	v_writelane_b32 v236, s10, 9
	global_load_lds_dwordx4 v[2:3], off
	v_lshlrev_b32_e32 v2, 4, v9
	v_and_b32_e32 v2, 0x70, v2
	v_lshl_or_b32 v74, v8, 11, v2
	v_lshl_add_u64 v[2:3], s[4:5], 0, v[74:75]
	s_add_i32 m0, s1, 0x3000
	v_writelane_b32 v236, s11, 11
	global_load_lds_dwordx4 v[2:3], off
	v_lshl_add_u64 v[2:3], s[6:7], 0, v[74:75]
	s_add_i32 m0, s1, 0x7000
	s_add_u32 s1, s54, 0x2bf4800
	global_load_lds_dwordx4 v[2:3], off
	v_writelane_b32 v236, s1, 12
	s_addc_u32 s1, s55, 0
	v_writelane_b32 v236, s1, 13
	s_add_u32 s1, s52, 0x4c43400
	v_writelane_b32 v236, s1, 14
	s_addc_u32 s1, s53, 0
	v_writelane_b32 v236, s1, 15
	s_add_u32 s1, s52, 0x4c40000
	s_mov_b32 s5, 0
	v_writelane_b32 v236, s1, 16
	s_addc_u32 s1, s53, 0
	s_mov_b64 s[8:9], 0x80
	s_mov_b64 s[10:11], 0x100
	s_mov_b64 s[12:13], 0x180
	s_mov_b64 s[14:15], 0x200
	s_mov_b64 s[16:17], 0x280
	s_mov_b64 s[18:19], 0x300
	s_mov_b64 s[20:21], 0x380
	s_mov_b64 s[22:23], 0x400
	s_mov_b64 s[24:25], 0x480
	s_mov_b64 s[26:27], 0x500
	s_mov_b64 s[28:29], 0x580
	s_mov_b64 s[30:31], 0x600
	s_mov_b64 s[36:37], 0x680
	s_mov_b64 s[68:69], 0x700
	s_mov_b64 s[70:71], 0x780
	v_mov_b32_e32 v92, 0x358637bd
	v_writelane_b32 v236, s1, 17
	s_branch .LBB0_97
.LBB0_96:
	s_or_b64 exec, exec, s[0:1]
	s_cmpk_lt_i32 s33, 0x1000
	s_mov_b32 s0, s88
	s_mov_b32 s82, s86
	s_cbranch_scc0 .LBB0_143
; template <class Epi>
; DI void gemm_phase(const u16* __restrict__ A, const u16* __restrict__ B, int mtiles, int ntiles, char* lds, const Epi& epi) {
;     ...
;     for (;;) {
;         int tid = threadIdx.x; asm volatile("" : "+v"(tid));
;         const int lane = tid & 63, wave = __builtin_amdgcn_readfirstlane(tid >> 6); const int wn = wave >> 1, wm = wave & 1; const int r = lane & 31, h = lane >> 5;
;         f32x16 acc[2][2];
; #pragma unroll
;         for (int a = 0; a < 2; ++a)
; #pragma unroll
;             for (int b = 0; b < 2; ++b)
; #pragma unroll
;                 for (int e = 0; e < 16; ++e) acc[a][b][e] = 0.f;
;         unsigned soff[4];
; #pragma unroll
;         for (int i = 0; i < 4; ++i) { const int row = 8 * (i * 4 + wave) + (lane >> 3); const int ch = (lane & 7) ^ ((row >> 1) & 7); soff[i] = (unsigned)(row * 1024 + ch * 8); }
;         const u16* ga = A + (size_t)m0 * 1024; const u16* gb = B + (size_t)n0 * 1024;
;         __syncthreads();
;         for (int kt = 0; kt < 16; ++kt) {
;             if (kt + 1 < 16) GSTAGE((kt + 1) & 1, kt + 1, ga, gb);
;             const char* sa = lds + (kt & 1) * 32768; const char* sb = sa + 16384;
; #pragma unroll
;             for (int ks = 0; ks < 4; ++ks) {
;                 bf16x8 fw[2], fx[2];
; #pragma unroll
;                 for (int ct = 0; ct < 2; ++ct) fw[ct] = *(const bf16x8*)(sb + swz(wn * 64 + ct * 32 + r, 2 * ks + h));
; #pragma unroll
;                 for (int tt = 0; tt < 2; ++tt) fx[tt] = *(const bf16x8*)(sa + swz(wm * 64 + tt * 32 + r, 2 * ks + h));
; #pragma unroll
;                 for (int ct = 0; ct < 2; ++ct)
; #pragma unroll
;                     for (int tt = 0; tt < 2; ++tt) acc[ct][tt] = __builtin_amdgcn_mfma_f32_32x32x16_bf16(fw[ct], fx[tt], acc[ct][tt], 0, 0, 0);
;             }
;             __syncthreads();
;         }
.LBB0_97:
	v_mov_b32_e32 v18, v0
	s_ashr_i32 s83, s82, 31
	v_readfirstlane_b32 s1, v18
	s_ashr_i32 s7, s1, 6
	s_ashr_i32 s4, s1, 7
	s_and_b32 s6, s7, 1
	v_bfe_u32 v2, v18, 3, 3
	s_lshl_b64 s[38:39], s[82:83], 11
	v_lshl_or_b32 v2, s7, 3, v2
	s_add_u32 s38, s54, s38
	v_lshrrev_b32_e32 v3, 1, v2
	s_addc_u32 s39, s55, s39
	s_ashr_i32 s1, s0, 31
	v_xor_b32_e32 v3, v3, v18
	s_lshl_b64 s[50:51], s[0:1], 11
	v_readlane_b32 s1, v236, 9
	v_lshlrev_b32_e32 v2, 10, v2
	v_lshlrev_b32_e32 v3, 3, v3
	s_add_u32 s50, s1, s50
	v_readlane_b32 s1, v236, 11
	v_and_or_b32 v74, v3, 56, v2
	s_addc_u32 s51, s1, s51
	s_lshl_b32 s1, s7, 10
	v_lshlrev_b64 v[66:67], 1, v[74:75]
	s_add_i32 s1, s1, 0
	v_add_u32_e32 v2, 0x8000, v74
	v_bfe_u32 v93, v18, 5, 1
	v_lshrrev_b32_e32 v8, 1, v18
	v_mov_b32_e32 v3, v75
	v_lshl_add_u64 v[76:77], s[38:39], 0, v[66:67]
	s_add_i32 s86, s1, 0x8000
	v_bitop3_b32 v10, v93, v8, 7 bitop3:0x78
	v_lshl_add_u64 v[8:9], v[76:77], 0, s[8:9]
	s_mov_b32 m0, s86
	v_lshl_add_u64 v[78:79], s[50:51], 0, v[66:67]
	s_add_i32 s87, s1, 0xc000
	v_lshlrev_b64 v[68:69], 1, v[2:3]
	v_add_u32_e32 v4, 0x10000, v74
	s_waitcnt vmcnt(0) lgkmcnt(0)
	s_barrier
	v_mov_b32_e32 v5, v75
	global_load_lds_dwordx4 v[8:9], off
	v_lshl_add_u64 v[8:9], v[78:79], 0, s[8:9]
	s_mov_b32 m0, s87
	v_lshl_add_u64 v[80:81], s[38:39], 0, v[68:69]
	s_add_i32 s88, s1, 0x9000
	global_load_lds_dwordx4 v[8:9], off
	v_lshl_add_u64 v[2:3], v[80:81], 0, s[8:9]
	s_mov_b32 m0, s88
	v_lshl_add_u64 v[82:83], s[50:51], 0, v[68:69]
	s_add_i32 s89, s1, 0xd000
	v_lshlrev_b64 v[70:71], 1, v[4:5]
	v_add_u32_e32 v6, 0x18000, v74
	v_mov_b32_e32 v7, v75
	global_load_lds_dwordx4 v[2:3], off
	v_lshl_add_u64 v[2:3], v[82:83], 0, s[8:9]
	s_mov_b32 m0, s89
	v_lshl_add_u64 v[84:85], s[38:39], 0, v[70:71]
	s_add_i32 s91, s1, 0xa000
	global_load_lds_dwordx4 v[2:3], off
	v_lshl_add_u64 v[2:3], v[84:85], 0, s[8:9]
	s_mov_b32 m0, s91
	v_lshl_add_u64 v[86:87], s[50:51], 0, v[70:71]
	s_add_i32 s92, s1, 0xe000
	v_lshlrev_b64 v[72:73], 1, v[6:7]
	global_load_lds_dwordx4 v[2:3], off
	v_lshl_add_u64 v[2:3], v[86:87], 0, s[8:9]
	s_mov_b32 m0, s92
	v_lshl_add_u64 v[88:89], s[38:39], 0, v[72:73]
	s_add_i32 s93, s1, 0xb000
	v_and_b32_e32 v94, 31, v18
	global_load_lds_dwordx4 v[2:3], off
	v_lshl_add_u64 v[2:3], v[88:89], 0, s[8:9]
	s_mov_b32 m0, s93
	v_lshl_add_u64 v[90:91], s[50:51], 0, v[72:73]
	s_add_i32 s94, s1, 0xf000
	s_lshl_b32 s7, s4, 13
	v_lshlrev_b32_e32 v116, 7, v94
	global_load_lds_dwordx4 v[2:3], off
	v_lshl_add_u64 v[2:3], v[90:91], 0, s[8:9]
	s_mov_b32 m0, s94
	v_lshl_add_u32 v6, v10, 4, 0
	global_load_lds_dwordx4 v[2:3], off
	v_add3_u32 v74, v6, s7, v116
	ds_read_b128 v[2:5], v74 offset:16384
	s_lshl_b32 s38, s6, 13
	v_add3_u32 v96, v6, s38, v116
	v_bfe_u32 v117, v18, 1, 3
	ds_read_b128 v[6:9], v96
	ds_read_b128 v[10:13], v96 offset:4096
	ds_read_b128 v[14:17], v74 offset:20480
	v_bitop3_b32 v18, v93, v117, 2 bitop3:0x36
	v_lshl_add_u32 v18, v18, 4, 0
	v_add3_u32 v95, v18, s7, v116
	ds_read_b128 v[50:53], v95 offset:16384
	s_waitcnt lgkmcnt(0)
	v_mfma_f32_32x32x16_bf16 v[34:49], v[2:5], v[6:9], 0
	v_add3_u32 v97, v18, s38, v116
	ds_read_b128 v[98:101], v97
	ds_read_b128 v[102:105], v97 offset:4096
	ds_read_b128 v[106:109], v95 offset:20480
	s_mov_b32 m0, s1
	s_add_i32 s39, s1, 0x5000
	s_add_i32 s50, s1, 0x2000
	s_add_i32 s51, s1, 0x6000
	s_add_i32 s83, s1, 0x3000
	v_mfma_f32_32x32x16_bf16 v[18:33], v[2:5], v[10:13], 0
	s_add_i32 s90, s1, 0x7000
	s_add_i32 s33, s33, s95
	s_waitcnt lgkmcnt(0)
	v_mfma_f32_32x32x16_bf16 v[34:49], v[50:53], v[98:101], v[34:49]
	v_mfma_f32_32x32x16_bf16 v[18:33], v[50:53], v[102:105], v[18:33]
	v_mfma_f32_32x32x16_bf16 v[50:65], v[14:17], v[6:9], 0
	v_mfma_f32_32x32x16_bf16 v[2:17], v[14:17], v[10:13], 0
	v_mfma_f32_32x32x16_bf16 v[50:65], v[106:109], v[98:101], v[50:65]
	v_bitop3_b32 v98, v93, v117, 4 bitop3:0x36
	v_lshl_add_u32 v99, v98, 4, 0
	v_add3_u32 v98, v99, s7, v116
	v_add3_u32 v99, v99, s38, v116
	v_mfma_f32_32x32x16_bf16 v[2:17], v[106:109], v[102:105], v[2:17]
	ds_read_b128 v[100:103], v98 offset:16384
	ds_read_b128 v[104:107], v99
	ds_read_b128 v[108:111], v99 offset:4096
	ds_read_b128 v[112:115], v98 offset:20480
	s_waitcnt lgkmcnt(0)
	v_mfma_f32_32x32x16_bf16 v[34:49], v[100:103], v[104:107], v[34:49]
	v_mfma_f32_32x32x16_bf16 v[18:33], v[100:103], v[108:111], v[18:33]
	v_bitop3_b32 v100, v93, v117, 6 bitop3:0x36
	v_lshl_add_u32 v101, v100, 4, 0
	v_add3_u32 v100, v101, s7, v116
	v_add3_u32 v101, v101, s38, v116
	s_add_i32 s7, s1, 0x4000
	s_add_i32 s38, s1, 0x1000
	s_cmpk_gt_i32 s33, 0xfff
	v_mfma_f32_32x32x16_bf16 v[50:65], v[112:115], v[104:107], v[50:65]
	v_mfma_f32_32x32x16_bf16 v[2:17], v[112:115], v[108:111], v[2:17]
	ds_read_b128 v[238:241], v100 offset:16384
	ds_read_b128 v[242:245], v101
	ds_read_b128 v[246:249], v101 offset:4096
	ds_read_b128 v[250:253], v100 offset:20480
	s_waitcnt vmcnt(0) lgkmcnt(0)
	s_barrier
; template <class Epi>
; DI void gemm_phase(const u16* __restrict__ A, const u16* __restrict__ B, int mtiles, int ntiles, char* lds, const Epi& epi) {
;     ...
;         for (int kt = 0; kt < 16; ++kt) {
;             if (kt + 1 < 16) GSTAGE((kt + 1) & 1, kt + 1, ga, gb);
;             const char* sa = lds + (kt & 1) * 32768; const char* sb = sa + 16384;
; #pragma unroll
;             for (int ks = 0; ks < 4; ++ks) {
;                 bf16x8 fw[2], fx[2];
; #pragma unroll
;                 for (int ct = 0; ct < 2; ++ct) fw[ct] = *(const bf16x8*)(sb + swz(wn * 64 + ct * 32 + r, 2 * ks + h));
; #pragma unroll
;                 for (int tt = 0; tt < 2; ++tt) fx[tt] = *(const bf16x8*)(sa + swz(wm * 64 + tt * 32 + r, 2 * ks + h));
; #pragma unroll
;                 for (int ct = 0; ct < 2; ++ct)
; #pragma unroll
;                     for (int tt = 0; tt < 2; ++tt) acc[ct][tt] = __builtin_amdgcn_mfma_f32_32x32x16_bf16(fw[ct], fx[tt], acc[ct][tt], 0, 0, 0);
;             }
;             __syncthreads();
	ds_read_b128 v[102:105], v74 offset:49152
	ds_read_b128 v[106:109], v96 offset:32768
	ds_read_b128 v[110:113], v96 offset:36864
	ds_read_b128 v[114:117], v74 offset:53248
	v_mfma_f32_32x32x16_bf16 v[34:49], v[238:241], v[242:245], v[34:49]
	v_mfma_f32_32x32x16_bf16 v[18:33], v[238:241], v[246:249], v[18:33]
	v_lshl_add_u64 v[254:255], v[76:77], 0, s[10:11]
	global_load_lds_dwordx4 v[254:255], off
	v_lshl_add_u64 v[254:255], v[78:79], 0, s[10:11]
	s_mov_b32 m0, s7
	s_nop 0
	global_load_lds_dwordx4 v[254:255], off
	v_mfma_f32_32x32x16_bf16 v[50:65], v[250:253], v[242:245], v[50:65]
	v_lshl_add_u64 v[254:255], v[80:81], 0, s[10:11]
	s_mov_b32 m0, s38
	s_nop 0
	global_load_lds_dwordx4 v[254:255], off
	v_mfma_f32_32x32x16_bf16 v[2:17], v[250:253], v[246:249], v[2:17]
	s_waitcnt lgkmcnt(0)
	ds_read_b128 v[238:241], v95 offset:49152
	ds_read_b128 v[242:245], v97 offset:32768
	ds_read_b128 v[246:249], v97 offset:36864
	ds_read_b128 v[250:253], v95 offset:53248
	v_mfma_f32_32x32x16_bf16 v[34:49], v[102:105], v[106:109], v[34:49]
	v_lshl_add_u64 v[254:255], v[82:83], 0, s[10:11]
	s_mov_b32 m0, s39
	s_nop 0
	global_load_lds_dwordx4 v[254:255], off
	v_mfma_f32_32x32x16_bf16 v[18:33], v[102:105], v[110:113], v[18:33]
	v_lshl_add_u64 v[254:255], v[84:85], 0, s[10:11]
	s_mov_b32 m0, s50
	s_nop 0
	global_load_lds_dwordx4 v[254:255], off
	v_mfma_f32_32x32x16_bf16 v[50:65], v[114:117], v[106:109], v[50:65]
	v_mfma_f32_32x32x16_bf16 v[2:17], v[114:117], v[110:113], v[2:17]
	s_waitcnt lgkmcnt(0)
	ds_read_b128 v[102:105], v98 offset:49152
	ds_read_b128 v[106:109], v99 offset:32768
	ds_read_b128 v[110:113], v99 offset:36864
	ds_read_b128 v[114:117], v98 offset:53248
	v_mfma_f32_32x32x16_bf16 v[34:49], v[238:241], v[242:245], v[34:49]
	v_lshl_add_u64 v[254:255], v[86:87], 0, s[10:11]
	s_mov_b32 m0, s51
	s_nop 0
	global_load_lds_dwordx4 v[254:255], off
	v_mfma_f32_32x32x16_bf16 v[18:33], v[238:241], v[246:249], v[18:33]
	v_lshl_add_u64 v[254:255], v[88:89], 0, s[10:11]
	s_mov_b32 m0, s83
	s_nop 0
	global_load_lds_dwordx4 v[254:255], off
	v_mfma_f32_32x32x16_bf16 v[50:65], v[250:253], v[242:245], v[50:65]
	v_mfma_f32_32x32x16_bf16 v[2:17], v[250:253], v[246:249], v[2:17]
	s_waitcnt lgkmcnt(0)
	ds_read_b128 v[238:241], v100 offset:49152
	ds_read_b128 v[242:245], v101 offset:32768
	ds_read_b128 v[246:249], v101 offset:36864
	ds_read_b128 v[250:253], v100 offset:53248
	v_mfma_f32_32x32x16_bf16 v[34:49], v[102:105], v[106:109], v[34:49]
	v_lshl_add_u64 v[254:255], v[90:91], 0, s[10:11]
	s_mov_b32 m0, s90
	s_nop 0
	global_load_lds_dwordx4 v[254:255], off
	v_mfma_f32_32x32x16_bf16 v[18:33], v[102:105], v[110:113], v[18:33]
	v_mfma_f32_32x32x16_bf16 v[50:65], v[114:117], v[106:109], v[50:65]
	v_mfma_f32_32x32x16_bf16 v[2:17], v[114:117], v[110:113], v[2:17]
	s_mov_b32 m0, s86
	s_waitcnt vmcnt(0) lgkmcnt(0)
	s_barrier
	ds_read_b128 v[102:105], v74 offset:16384
	ds_read_b128 v[106:109], v96
	ds_read_b128 v[110:113], v96 offset:4096
	ds_read_b128 v[114:117], v74 offset:20480
	v_mfma_f32_32x32x16_bf16 v[34:49], v[238:241], v[242:245], v[34:49]
	v_mfma_f32_32x32x16_bf16 v[18:33], v[238:241], v[246:249], v[18:33]
	v_lshl_add_u64 v[254:255], v[76:77], 0, s[12:13]
	global_load_lds_dwordx4 v[254:255], off
	v_lshl_add_u64 v[254:255], v[78:79], 0, s[12:13]
	s_mov_b32 m0, s87
	s_nop 0
	global_load_lds_dwordx4 v[254:255], off
	v_mfma_f32_32x32x16_bf16 v[50:65], v[250:253], v[242:245], v[50:65]
	v_lshl_add_u64 v[254:255], v[80:81], 0, s[12:13]
	s_mov_b32 m0, s88
	s_nop 0
	global_load_lds_dwordx4 v[254:255], off
	v_mfma_f32_32x32x16_bf16 v[2:17], v[250:253], v[246:249], v[2:17]
	s_waitcnt lgkmcnt(0)
	ds_read_b128 v[238:241], v95 offset:16384
	ds_read_b128 v[242:245], v97
	ds_read_b128 v[246:249], v97 offset:4096
	ds_read_b128 v[250:253], v95 offset:20480
	v_mfma_f32_32x32x16_bf16 v[34:49], v[102:105], v[106:109], v[34:49]
	v_lshl_add_u64 v[254:255], v[82:83], 0, s[12:13]
	s_mov_b32 m0, s89
	s_nop 0
	global_load_lds_dwordx4 v[254:255], off
	v_mfma_f32_32x32x16_bf16 v[18:33], v[102:105], v[110:113], v[18:33]
	v_lshl_add_u64 v[254:255], v[84:85], 0, s[12:13]
	s_mov_b32 m0, s91
	s_nop 0
	global_load_lds_dwordx4 v[254:255], off
	v_mfma_f32_32x32x16_bf16 v[50:65], v[114:117], v[106:109], v[50:65]
	v_mfma_f32_32x32x16_bf16 v[2:17], v[114:117], v[110:113], v[2:17]
	s_waitcnt lgkmcnt(0)
	ds_read_b128 v[102:105], v98 offset:16384
	ds_read_b128 v[106:109], v99
	ds_read_b128 v[110:113], v99 offset:4096
	ds_read_b128 v[114:117], v98 offset:20480
	v_mfma_f32_32x32x16_bf16 v[34:49], v[238:241], v[242:245], v[34:49]
	v_lshl_add_u64 v[254:255], v[86:87], 0, s[12:13]
	s_mov_b32 m0, s92
	s_nop 0
	global_load_lds_dwordx4 v[254:255], off
	v_mfma_f32_32x32x16_bf16 v[18:33], v[238:241], v[246:249], v[18:33]
	v_lshl_add_u64 v[254:255], v[88:89], 0, s[12:13]
	s_mov_b32 m0, s93
	s_nop 0
	global_load_lds_dwordx4 v[254:255], off
	v_mfma_f32_32x32x16_bf16 v[50:65], v[250:253], v[242:245], v[50:65]
	v_mfma_f32_32x32x16_bf16 v[2:17], v[250:253], v[246:249], v[2:17]
	s_waitcnt lgkmcnt(0)
	ds_read_b128 v[238:241], v100 offset:16384
	ds_read_b128 v[242:245], v101
	ds_read_b128 v[246:249], v101 offset:4096
	ds_read_b128 v[250:253], v100 offset:20480
	v_mfma_f32_32x32x16_bf16 v[34:49], v[102:105], v[106:109], v[34:49]
	v_lshl_add_u64 v[254:255], v[90:91], 0, s[12:13]
	s_mov_b32 m0, s94
	s_nop 0
	global_load_lds_dwordx4 v[254:255], off
	v_mfma_f32_32x32x16_bf16 v[18:33], v[102:105], v[110:113], v[18:33]
	v_mfma_f32_32x32x16_bf16 v[50:65], v[114:117], v[106:109], v[50:65]
	v_mfma_f32_32x32x16_bf16 v[2:17], v[114:117], v[110:113], v[2:17]
	s_mov_b32 m0, s1
	s_waitcnt vmcnt(0) lgkmcnt(0)
	s_barrier
; template <class Epi>
; DI void gemm_phase(const u16* __restrict__ A, const u16* __restrict__ B, int mtiles, int ntiles, char* lds, const Epi& epi) {
;     ...
;         for (int kt = 0; kt < 16; ++kt) {
;             if (kt + 1 < 16) GSTAGE((kt + 1) & 1, kt + 1, ga, gb);
;             const char* sa = lds + (kt & 1) * 32768; const char* sb = sa + 16384;
; #pragma unroll
;             for (int ks = 0; ks < 4; ++ks) {
;                 bf16x8 fw[2], fx[2];
; #pragma unroll
;                 for (int ct = 0; ct < 2; ++ct) fw[ct] = *(const bf16x8*)(sb + swz(wn * 64 + ct * 32 + r, 2 * ks + h));
; #pragma unroll
;                 for (int tt = 0; tt < 2; ++tt) fx[tt] = *(const bf16x8*)(sa + swz(wm * 64 + tt * 32 + r, 2 * ks + h));
; #pragma unroll
;                 for (int ct = 0; ct < 2; ++ct)
; #pragma unroll
;                     for (int tt = 0; tt < 2; ++tt) acc[ct][tt] = __builtin_amdgcn_mfma_f32_32x32x16_bf16(fw[ct], fx[tt], acc[ct][tt], 0, 0, 0);
;             }
;             __syncthreads();
	ds_read_b128 v[102:105], v74 offset:49152
	ds_read_b128 v[106:109], v96 offset:32768
	ds_read_b128 v[110:113], v96 offset:36864
	ds_read_b128 v[114:117], v74 offset:53248
	v_mfma_f32_32x32x16_bf16 v[34:49], v[238:241], v[242:245], v[34:49]
	v_mfma_f32_32x32x16_bf16 v[18:33], v[238:241], v[246:249], v[18:33]
	v_lshl_add_u64 v[254:255], v[76:77], 0, s[14:15]
	global_load_lds_dwordx4 v[254:255], off
	v_lshl_add_u64 v[254:255], v[78:79], 0, s[14:15]
	s_mov_b32 m0, s7
	s_nop 0
	global_load_lds_dwordx4 v[254:255], off
	v_mfma_f32_32x32x16_bf16 v[50:65], v[250:253], v[242:245], v[50:65]
	v_lshl_add_u64 v[254:255], v[80:81], 0, s[14:15]
	s_mov_b32 m0, s38
	s_nop 0
	global_load_lds_dwordx4 v[254:255], off
	v_mfma_f32_32x32x16_bf16 v[2:17], v[250:253], v[246:249], v[2:17]
	s_waitcnt lgkmcnt(0)
	ds_read_b128 v[238:241], v95 offset:49152
	ds_read_b128 v[242:245], v97 offset:32768
	ds_read_b128 v[246:249], v97 offset:36864
	ds_read_b128 v[250:253], v95 offset:53248
	v_mfma_f32_32x32x16_bf16 v[34:49], v[102:105], v[106:109], v[34:49]
	v_lshl_add_u64 v[254:255], v[82:83], 0, s[14:15]
	s_mov_b32 m0, s39
	s_nop 0
	global_load_lds_dwordx4 v[254:255], off
	v_mfma_f32_32x32x16_bf16 v[18:33], v[102:105], v[110:113], v[18:33]
	v_lshl_add_u64 v[254:255], v[84:85], 0, s[14:15]
	s_mov_b32 m0, s50
	s_nop 0
	global_load_lds_dwordx4 v[254:255], off
	v_mfma_f32_32x32x16_bf16 v[50:65], v[114:117], v[106:109], v[50:65]
	v_mfma_f32_32x32x16_bf16 v[2:17], v[114:117], v[110:113], v[2:17]
	s_waitcnt lgkmcnt(0)
	ds_read_b128 v[102:105], v98 offset:49152
	ds_read_b128 v[106:109], v99 offset:32768
	ds_read_b128 v[110:113], v99 offset:36864
	ds_read_b128 v[114:117], v98 offset:53248
	v_mfma_f32_32x32x16_bf16 v[34:49], v[238:241], v[242:245], v[34:49]
	v_lshl_add_u64 v[254:255], v[86:87], 0, s[14:15]
	s_mov_b32 m0, s51
	s_nop 0
	global_load_lds_dwordx4 v[254:255], off
	v_mfma_f32_32x32x16_bf16 v[18:33], v[238:241], v[246:249], v[18:33]
	v_lshl_add_u64 v[254:255], v[88:89], 0, s[14:15]
	s_mov_b32 m0, s83
	s_nop 0
	global_load_lds_dwordx4 v[254:255], off
	v_mfma_f32_32x32x16_bf16 v[50:65], v[250:253], v[242:245], v[50:65]
	v_mfma_f32_32x32x16_bf16 v[2:17], v[250:253], v[246:249], v[2:17]
	s_waitcnt lgkmcnt(0)
	ds_read_b128 v[238:241], v100 offset:49152
	ds_read_b128 v[242:245], v101 offset:32768
	ds_read_b128 v[246:249], v101 offset:36864
	ds_read_b128 v[250:253], v100 offset:53248
	v_mfma_f32_32x32x16_bf16 v[34:49], v[102:105], v[106:109], v[34:49]
	v_lshl_add_u64 v[254:255], v[90:91], 0, s[14:15]
	s_mov_b32 m0, s90
	s_nop 0
	global_load_lds_dwordx4 v[254:255], off
	v_mfma_f32_32x32x16_bf16 v[18:33], v[102:105], v[110:113], v[18:33]
	v_mfma_f32_32x32x16_bf16 v[50:65], v[114:117], v[106:109], v[50:65]
	v_mfma_f32_32x32x16_bf16 v[2:17], v[114:117], v[110:113], v[2:17]
	s_mov_b32 m0, s86
	s_waitcnt vmcnt(0) lgkmcnt(0)
	s_barrier
	ds_read_b128 v[102:105], v74 offset:16384
	ds_read_b128 v[106:109], v96
	ds_read_b128 v[110:113], v96 offset:4096
	ds_read_b128 v[114:117], v74 offset:20480
	v_mfma_f32_32x32x16_bf16 v[34:49], v[238:241], v[242:245], v[34:49]
	v_mfma_f32_32x32x16_bf16 v[18:33], v[238:241], v[246:249], v[18:33]
	v_lshl_add_u64 v[254:255], v[76:77], 0, s[16:17]
	global_load_lds_dwordx4 v[254:255], off
	v_lshl_add_u64 v[254:255], v[78:79], 0, s[16:17]
	s_mov_b32 m0, s87
	s_nop 0
	global_load_lds_dwordx4 v[254:255], off
	v_mfma_f32_32x32x16_bf16 v[50:65], v[250:253], v[242:245], v[50:65]
	v_lshl_add_u64 v[254:255], v[80:81], 0, s[16:17]
	s_mov_b32 m0, s88
	s_nop 0
	global_load_lds_dwordx4 v[254:255], off
	v_mfma_f32_32x32x16_bf16 v[2:17], v[250:253], v[246:249], v[2:17]
	s_waitcnt lgkmcnt(0)
	ds_read_b128 v[238:241], v95 offset:16384
	ds_read_b128 v[242:245], v97
	ds_read_b128 v[246:249], v97 offset:4096
	ds_read_b128 v[250:253], v95 offset:20480
	v_mfma_f32_32x32x16_bf16 v[34:49], v[102:105], v[106:109], v[34:49]
	v_lshl_add_u64 v[254:255], v[82:83], 0, s[16:17]
	s_mov_b32 m0, s89
	s_nop 0
	global_load_lds_dwordx4 v[254:255], off
	v_mfma_f32_32x32x16_bf16 v[18:33], v[102:105], v[110:113], v[18:33]
	v_lshl_add_u64 v[254:255], v[84:85], 0, s[16:17]
	s_mov_b32 m0, s91
	s_nop 0
	global_load_lds_dwordx4 v[254:255], off
	v_mfma_f32_32x32x16_bf16 v[50:65], v[114:117], v[106:109], v[50:65]
	v_mfma_f32_32x32x16_bf16 v[2:17], v[114:117], v[110:113], v[2:17]
	s_waitcnt lgkmcnt(0)
	ds_read_b128 v[102:105], v98 offset:16384
	ds_read_b128 v[106:109], v99
	ds_read_b128 v[110:113], v99 offset:4096
	ds_read_b128 v[114:117], v98 offset:20480
	v_mfma_f32_32x32x16_bf16 v[34:49], v[238:241], v[242:245], v[34:49]
	v_lshl_add_u64 v[254:255], v[86:87], 0, s[16:17]
	s_mov_b32 m0, s92
	s_nop 0
	global_load_lds_dwordx4 v[254:255], off
	v_mfma_f32_32x32x16_bf16 v[18:33], v[238:241], v[246:249], v[18:33]
	v_lshl_add_u64 v[254:255], v[88:89], 0, s[16:17]
	s_mov_b32 m0, s93
	s_nop 0
	global_load_lds_dwordx4 v[254:255], off
	v_mfma_f32_32x32x16_bf16 v[50:65], v[250:253], v[242:245], v[50:65]
	v_mfma_f32_32x32x16_bf16 v[2:17], v[250:253], v[246:249], v[2:17]
	s_waitcnt lgkmcnt(0)
	ds_read_b128 v[238:241], v100 offset:16384
	ds_read_b128 v[242:245], v101
	ds_read_b128 v[246:249], v101 offset:4096
	ds_read_b128 v[250:253], v100 offset:20480
	v_mfma_f32_32x32x16_bf16 v[34:49], v[102:105], v[106:109], v[34:49]
	v_lshl_add_u64 v[254:255], v[90:91], 0, s[16:17]
	s_mov_b32 m0, s94
	s_nop 0
	global_load_lds_dwordx4 v[254:255], off
	v_mfma_f32_32x32x16_bf16 v[18:33], v[102:105], v[110:113], v[18:33]
	v_mfma_f32_32x32x16_bf16 v[50:65], v[114:117], v[106:109], v[50:65]
	v_mfma_f32_32x32x16_bf16 v[2:17], v[114:117], v[110:113], v[2:17]
	s_mov_b32 m0, s1
	s_waitcnt vmcnt(0) lgkmcnt(0)
	s_barrier
; template <class Epi>
; DI void gemm_phase(const u16* __restrict__ A, const u16* __restrict__ B, int mtiles, int ntiles, char* lds, const Epi& epi) {
;     ...
;         for (int kt = 0; kt < 16; ++kt) {
;             if (kt + 1 < 16) GSTAGE((kt + 1) & 1, kt + 1, ga, gb);
;             const char* sa = lds + (kt & 1) * 32768; const char* sb = sa + 16384;
; #pragma unroll
;             for (int ks = 0; ks < 4; ++ks) {
;                 bf16x8 fw[2], fx[2];
; #pragma unroll
;                 for (int ct = 0; ct < 2; ++ct) fw[ct] = *(const bf16x8*)(sb + swz(wn * 64 + ct * 32 + r, 2 * ks + h));
; #pragma unroll
;                 for (int tt = 0; tt < 2; ++tt) fx[tt] = *(const bf16x8*)(sa + swz(wm * 64 + tt * 32 + r, 2 * ks + h));
; #pragma unroll
;                 for (int ct = 0; ct < 2; ++ct)
; #pragma unroll
;                     for (int tt = 0; tt < 2; ++tt) acc[ct][tt] = __builtin_amdgcn_mfma_f32_32x32x16_bf16(fw[ct], fx[tt], acc[ct][tt], 0, 0, 0);
;             }
;             __syncthreads();
	ds_read_b128 v[102:105], v74 offset:49152
	ds_read_b128 v[106:109], v96 offset:32768
	ds_read_b128 v[110:113], v96 offset:36864
	ds_read_b128 v[114:117], v74 offset:53248
	v_mfma_f32_32x32x16_bf16 v[34:49], v[238:241], v[242:245], v[34:49]
	v_mfma_f32_32x32x16_bf16 v[18:33], v[238:241], v[246:249], v[18:33]
	v_lshl_add_u64 v[254:255], v[76:77], 0, s[18:19]
	global_load_lds_dwordx4 v[254:255], off
	v_lshl_add_u64 v[254:255], v[78:79], 0, s[18:19]
	s_mov_b32 m0, s7
	s_nop 0
	global_load_lds_dwordx4 v[254:255], off
	v_mfma_f32_32x32x16_bf16 v[50:65], v[250:253], v[242:245], v[50:65]
	v_lshl_add_u64 v[254:255], v[80:81], 0, s[18:19]
	s_mov_b32 m0, s38
	s_nop 0
	global_load_lds_dwordx4 v[254:255], off
	v_mfma_f32_32x32x16_bf16 v[2:17], v[250:253], v[246:249], v[2:17]
	s_waitcnt lgkmcnt(0)
	ds_read_b128 v[238:241], v95 offset:49152
	ds_read_b128 v[242:245], v97 offset:32768
	ds_read_b128 v[246:249], v97 offset:36864
	ds_read_b128 v[250:253], v95 offset:53248
	v_mfma_f32_32x32x16_bf16 v[34:49], v[102:105], v[106:109], v[34:49]
	v_lshl_add_u64 v[254:255], v[82:83], 0, s[18:19]
	s_mov_b32 m0, s39
	s_nop 0
	global_load_lds_dwordx4 v[254:255], off
	v_mfma_f32_32x32x16_bf16 v[18:33], v[102:105], v[110:113], v[18:33]
	v_lshl_add_u64 v[254:255], v[84:85], 0, s[18:19]
	s_mov_b32 m0, s50
	s_nop 0
	global_load_lds_dwordx4 v[254:255], off
	v_mfma_f32_32x32x16_bf16 v[50:65], v[114:117], v[106:109], v[50:65]
	v_mfma_f32_32x32x16_bf16 v[2:17], v[114:117], v[110:113], v[2:17]
	s_waitcnt lgkmcnt(0)
	ds_read_b128 v[102:105], v98 offset:49152
	ds_read_b128 v[106:109], v99 offset:32768
	ds_read_b128 v[110:113], v99 offset:36864
	ds_read_b128 v[114:117], v98 offset:53248
	v_mfma_f32_32x32x16_bf16 v[34:49], v[238:241], v[242:245], v[34:49]
	v_lshl_add_u64 v[254:255], v[86:87], 0, s[18:19]
	s_mov_b32 m0, s51
	s_nop 0
	global_load_lds_dwordx4 v[254:255], off
	v_mfma_f32_32x32x16_bf16 v[18:33], v[238:241], v[246:249], v[18:33]
	v_lshl_add_u64 v[254:255], v[88:89], 0, s[18:19]
	s_mov_b32 m0, s83
	s_nop 0
	global_load_lds_dwordx4 v[254:255], off
	v_mfma_f32_32x32x16_bf16 v[50:65], v[250:253], v[242:245], v[50:65]
	v_mfma_f32_32x32x16_bf16 v[2:17], v[250:253], v[246:249], v[2:17]
	s_waitcnt lgkmcnt(0)
	ds_read_b128 v[238:241], v100 offset:49152
	ds_read_b128 v[242:245], v101 offset:32768
	ds_read_b128 v[246:249], v101 offset:36864
	ds_read_b128 v[250:253], v100 offset:53248
	v_mfma_f32_32x32x16_bf16 v[34:49], v[102:105], v[106:109], v[34:49]
	v_lshl_add_u64 v[254:255], v[90:91], 0, s[18:19]
	s_mov_b32 m0, s90
	s_nop 0
	global_load_lds_dwordx4 v[254:255], off
	v_mfma_f32_32x32x16_bf16 v[18:33], v[102:105], v[110:113], v[18:33]
	v_mfma_f32_32x32x16_bf16 v[50:65], v[114:117], v[106:109], v[50:65]
	v_mfma_f32_32x32x16_bf16 v[2:17], v[114:117], v[110:113], v[2:17]
	s_mov_b32 m0, s86
	s_waitcnt vmcnt(0) lgkmcnt(0)
	s_barrier
	ds_read_b128 v[102:105], v74 offset:16384
	ds_read_b128 v[106:109], v96
	ds_read_b128 v[110:113], v96 offset:4096
	ds_read_b128 v[114:117], v74 offset:20480
	v_mfma_f32_32x32x16_bf16 v[34:49], v[238:241], v[242:245], v[34:49]
	v_mfma_f32_32x32x16_bf16 v[18:33], v[238:241], v[246:249], v[18:33]
	v_lshl_add_u64 v[254:255], v[76:77], 0, s[20:21]
	global_load_lds_dwordx4 v[254:255], off
	v_lshl_add_u64 v[254:255], v[78:79], 0, s[20:21]
	s_mov_b32 m0, s87
	s_nop 0
	global_load_lds_dwordx4 v[254:255], off
	v_mfma_f32_32x32x16_bf16 v[50:65], v[250:253], v[242:245], v[50:65]
	v_lshl_add_u64 v[254:255], v[80:81], 0, s[20:21]
	s_mov_b32 m0, s88
	s_nop 0
	global_load_lds_dwordx4 v[254:255], off
	v_mfma_f32_32x32x16_bf16 v[2:17], v[250:253], v[246:249], v[2:17]
	s_waitcnt lgkmcnt(0)
	ds_read_b128 v[238:241], v95 offset:16384
	ds_read_b128 v[242:245], v97
	ds_read_b128 v[246:249], v97 offset:4096
	ds_read_b128 v[250:253], v95 offset:20480
	v_mfma_f32_32x32x16_bf16 v[34:49], v[102:105], v[106:109], v[34:49]
	v_lshl_add_u64 v[254:255], v[82:83], 0, s[20:21]
	s_mov_b32 m0, s89
	s_nop 0
	global_load_lds_dwordx4 v[254:255], off
	v_mfma_f32_32x32x16_bf16 v[18:33], v[102:105], v[110:113], v[18:33]
	v_lshl_add_u64 v[254:255], v[84:85], 0, s[20:21]
	s_mov_b32 m0, s91
	s_nop 0
	global_load_lds_dwordx4 v[254:255], off
	v_mfma_f32_32x32x16_bf16 v[50:65], v[114:117], v[106:109], v[50:65]
	v_mfma_f32_32x32x16_bf16 v[2:17], v[114:117], v[110:113], v[2:17]
	s_waitcnt lgkmcnt(0)
	ds_read_b128 v[102:105], v98 offset:16384
	ds_read_b128 v[106:109], v99
	ds_read_b128 v[110:113], v99 offset:4096
	ds_read_b128 v[114:117], v98 offset:20480
	v_mfma_f32_32x32x16_bf16 v[34:49], v[238:241], v[242:245], v[34:49]
	v_lshl_add_u64 v[254:255], v[86:87], 0, s[20:21]
	s_mov_b32 m0, s92
	s_nop 0
	global_load_lds_dwordx4 v[254:255], off
	v_mfma_f32_32x32x16_bf16 v[18:33], v[238:241], v[246:249], v[18:33]
	v_lshl_add_u64 v[254:255], v[88:89], 0, s[20:21]
	s_mov_b32 m0, s93
	s_nop 0
	global_load_lds_dwordx4 v[254:255], off
	v_mfma_f32_32x32x16_bf16 v[50:65], v[250:253], v[242:245], v[50:65]
	v_mfma_f32_32x32x16_bf16 v[2:17], v[250:253], v[246:249], v[2:17]
	s_waitcnt lgkmcnt(0)
	ds_read_b128 v[238:241], v100 offset:16384
	ds_read_b128 v[242:245], v101
	ds_read_b128 v[246:249], v101 offset:4096
	ds_read_b128 v[250:253], v100 offset:20480
	v_mfma_f32_32x32x16_bf16 v[34:49], v[102:105], v[106:109], v[34:49]
	v_lshl_add_u64 v[254:255], v[90:91], 0, s[20:21]
	s_mov_b32 m0, s94
	s_nop 0
	global_load_lds_dwordx4 v[254:255], off
	v_mfma_f32_32x32x16_bf16 v[18:33], v[102:105], v[110:113], v[18:33]
	v_mfma_f32_32x32x16_bf16 v[50:65], v[114:117], v[106:109], v[50:65]
	v_mfma_f32_32x32x16_bf16 v[2:17], v[114:117], v[110:113], v[2:17]
	s_mov_b32 m0, s1
	s_waitcnt vmcnt(0) lgkmcnt(0)
	s_barrier
; template <class Epi>
; DI void gemm_phase(const u16* __restrict__ A, const u16* __restrict__ B, int mtiles, int ntiles, char* lds, const Epi& epi) {
;     ...
;         for (int kt = 0; kt < 16; ++kt) {
;             if (kt + 1 < 16) GSTAGE((kt + 1) & 1, kt + 1, ga, gb);
;             const char* sa = lds + (kt & 1) * 32768; const char* sb = sa + 16384;
; #pragma unroll
;             for (int ks = 0; ks < 4; ++ks) {
;                 bf16x8 fw[2], fx[2];
; #pragma unroll
;                 for (int ct = 0; ct < 2; ++ct) fw[ct] = *(const bf16x8*)(sb + swz(wn * 64 + ct * 32 + r, 2 * ks + h));
; #pragma unroll
;                 for (int tt = 0; tt < 2; ++tt) fx[tt] = *(const bf16x8*)(sa + swz(wm * 64 + tt * 32 + r, 2 * ks + h));
; #pragma unroll
;                 for (int ct = 0; ct < 2; ++ct)
; #pragma unroll
;                     for (int tt = 0; tt < 2; ++tt) acc[ct][tt] = __builtin_amdgcn_mfma_f32_32x32x16_bf16(fw[ct], fx[tt], acc[ct][tt], 0, 0, 0);
;             }
;             __syncthreads();
	ds_read_b128 v[102:105], v74 offset:49152
	ds_read_b128 v[106:109], v96 offset:32768
	ds_read_b128 v[110:113], v96 offset:36864
	ds_read_b128 v[114:117], v74 offset:53248
	v_mfma_f32_32x32x16_bf16 v[34:49], v[238:241], v[242:245], v[34:49]
	v_mfma_f32_32x32x16_bf16 v[18:33], v[238:241], v[246:249], v[18:33]
	v_lshl_add_u64 v[254:255], v[76:77], 0, s[22:23]
	global_load_lds_dwordx4 v[254:255], off
	v_lshl_add_u64 v[254:255], v[78:79], 0, s[22:23]
	s_mov_b32 m0, s7
	s_nop 0
	global_load_lds_dwordx4 v[254:255], off
	v_mfma_f32_32x32x16_bf16 v[50:65], v[250:253], v[242:245], v[50:65]
	v_lshl_add_u64 v[254:255], v[80:81], 0, s[22:23]
	s_mov_b32 m0, s38
	s_nop 0
	global_load_lds_dwordx4 v[254:255], off
	v_mfma_f32_32x32x16_bf16 v[2:17], v[250:253], v[246:249], v[2:17]
	s_waitcnt lgkmcnt(0)
	ds_read_b128 v[238:241], v95 offset:49152
	ds_read_b128 v[242:245], v97 offset:32768
	ds_read_b128 v[246:249], v97 offset:36864
	ds_read_b128 v[250:253], v95 offset:53248
	v_mfma_f32_32x32x16_bf16 v[34:49], v[102:105], v[106:109], v[34:49]
	v_lshl_add_u64 v[254:255], v[82:83], 0, s[22:23]
	s_mov_b32 m0, s39
	s_nop 0
	global_load_lds_dwordx4 v[254:255], off
	v_mfma_f32_32x32x16_bf16 v[18:33], v[102:105], v[110:113], v[18:33]
	v_lshl_add_u64 v[254:255], v[84:85], 0, s[22:23]
	s_mov_b32 m0, s50
	s_nop 0
	global_load_lds_dwordx4 v[254:255], off
	v_mfma_f32_32x32x16_bf16 v[50:65], v[114:117], v[106:109], v[50:65]
	v_mfma_f32_32x32x16_bf16 v[2:17], v[114:117], v[110:113], v[2:17]
	s_waitcnt lgkmcnt(0)
	ds_read_b128 v[102:105], v98 offset:49152
	ds_read_b128 v[106:109], v99 offset:32768
	ds_read_b128 v[110:113], v99 offset:36864
	ds_read_b128 v[114:117], v98 offset:53248
	v_mfma_f32_32x32x16_bf16 v[34:49], v[238:241], v[242:245], v[34:49]
	v_lshl_add_u64 v[254:255], v[86:87], 0, s[22:23]
	s_mov_b32 m0, s51
	s_nop 0
	global_load_lds_dwordx4 v[254:255], off
	v_mfma_f32_32x32x16_bf16 v[18:33], v[238:241], v[246:249], v[18:33]
	v_lshl_add_u64 v[254:255], v[88:89], 0, s[22:23]
	s_mov_b32 m0, s83
	s_nop 0
	global_load_lds_dwordx4 v[254:255], off
	v_mfma_f32_32x32x16_bf16 v[50:65], v[250:253], v[242:245], v[50:65]
	v_mfma_f32_32x32x16_bf16 v[2:17], v[250:253], v[246:249], v[2:17]
	s_waitcnt lgkmcnt(0)
	ds_read_b128 v[238:241], v100 offset:49152
	ds_read_b128 v[242:245], v101 offset:32768
	ds_read_b128 v[246:249], v101 offset:36864
	ds_read_b128 v[250:253], v100 offset:53248
	v_mfma_f32_32x32x16_bf16 v[34:49], v[102:105], v[106:109], v[34:49]
	v_lshl_add_u64 v[254:255], v[90:91], 0, s[22:23]
	s_mov_b32 m0, s90
	s_nop 0
	global_load_lds_dwordx4 v[254:255], off
	v_mfma_f32_32x32x16_bf16 v[18:33], v[102:105], v[110:113], v[18:33]
	v_mfma_f32_32x32x16_bf16 v[50:65], v[114:117], v[106:109], v[50:65]
	v_mfma_f32_32x32x16_bf16 v[2:17], v[114:117], v[110:113], v[2:17]
	s_mov_b32 m0, s86
	s_waitcnt vmcnt(0) lgkmcnt(0)
	s_barrier
	ds_read_b128 v[102:105], v74 offset:16384
	ds_read_b128 v[106:109], v96
	ds_read_b128 v[110:113], v96 offset:4096
	ds_read_b128 v[114:117], v74 offset:20480
	v_mfma_f32_32x32x16_bf16 v[34:49], v[238:241], v[242:245], v[34:49]
	v_mfma_f32_32x32x16_bf16 v[18:33], v[238:241], v[246:249], v[18:33]
	v_lshl_add_u64 v[254:255], v[76:77], 0, s[24:25]
	global_load_lds_dwordx4 v[254:255], off
	v_lshl_add_u64 v[254:255], v[78:79], 0, s[24:25]
	s_mov_b32 m0, s87
	s_nop 0
	global_load_lds_dwordx4 v[254:255], off
	v_mfma_f32_32x32x16_bf16 v[50:65], v[250:253], v[242:245], v[50:65]
	v_lshl_add_u64 v[254:255], v[80:81], 0, s[24:25]
	s_mov_b32 m0, s88
	s_nop 0
	global_load_lds_dwordx4 v[254:255], off
	v_mfma_f32_32x32x16_bf16 v[2:17], v[250:253], v[246:249], v[2:17]
	s_waitcnt lgkmcnt(0)
	ds_read_b128 v[238:241], v95 offset:16384
	ds_read_b128 v[242:245], v97
	ds_read_b128 v[246:249], v97 offset:4096
	ds_read_b128 v[250:253], v95 offset:20480
	v_mfma_f32_32x32x16_bf16 v[34:49], v[102:105], v[106:109], v[34:49]
	v_lshl_add_u64 v[254:255], v[82:83], 0, s[24:25]
	s_mov_b32 m0, s89
	s_nop 0
	global_load_lds_dwordx4 v[254:255], off
	v_mfma_f32_32x32x16_bf16 v[18:33], v[102:105], v[110:113], v[18:33]
	v_lshl_add_u64 v[254:255], v[84:85], 0, s[24:25]
	s_mov_b32 m0, s91
	s_nop 0
	global_load_lds_dwordx4 v[254:255], off
	v_mfma_f32_32x32x16_bf16 v[50:65], v[114:117], v[106:109], v[50:65]
	v_mfma_f32_32x32x16_bf16 v[2:17], v[114:117], v[110:113], v[2:17]
	s_waitcnt lgkmcnt(0)
	ds_read_b128 v[102:105], v98 offset:16384
	ds_read_b128 v[106:109], v99
	ds_read_b128 v[110:113], v99 offset:4096
	ds_read_b128 v[114:117], v98 offset:20480
	v_mfma_f32_32x32x16_bf16 v[34:49], v[238:241], v[242:245], v[34:49]
	v_lshl_add_u64 v[254:255], v[86:87], 0, s[24:25]
	s_mov_b32 m0, s92
	s_nop 0
	global_load_lds_dwordx4 v[254:255], off
	v_mfma_f32_32x32x16_bf16 v[18:33], v[238:241], v[246:249], v[18:33]
	v_lshl_add_u64 v[254:255], v[88:89], 0, s[24:25]
	s_mov_b32 m0, s93
	s_nop 0
	global_load_lds_dwordx4 v[254:255], off
	v_mfma_f32_32x32x16_bf16 v[50:65], v[250:253], v[242:245], v[50:65]
	v_mfma_f32_32x32x16_bf16 v[2:17], v[250:253], v[246:249], v[2:17]
	s_waitcnt lgkmcnt(0)
	ds_read_b128 v[238:241], v100 offset:16384
	ds_read_b128 v[242:245], v101
	ds_read_b128 v[246:249], v101 offset:4096
	ds_read_b128 v[250:253], v100 offset:20480
	v_mfma_f32_32x32x16_bf16 v[34:49], v[102:105], v[106:109], v[34:49]
	v_lshl_add_u64 v[254:255], v[90:91], 0, s[24:25]
	s_mov_b32 m0, s94
	s_nop 0
	global_load_lds_dwordx4 v[254:255], off
	v_mfma_f32_32x32x16_bf16 v[18:33], v[102:105], v[110:113], v[18:33]
	v_mfma_f32_32x32x16_bf16 v[50:65], v[114:117], v[106:109], v[50:65]
	v_mfma_f32_32x32x16_bf16 v[2:17], v[114:117], v[110:113], v[2:17]
	s_mov_b32 m0, s1
	s_waitcnt vmcnt(0) lgkmcnt(0)
	s_barrier
; template <class Epi>
; DI void gemm_phase(const u16* __restrict__ A, const u16* __restrict__ B, int mtiles, int ntiles, char* lds, const Epi& epi) {
;     ...
;         for (int kt = 0; kt < 16; ++kt) {
;             if (kt + 1 < 16) GSTAGE((kt + 1) & 1, kt + 1, ga, gb);
;             const char* sa = lds + (kt & 1) * 32768; const char* sb = sa + 16384;
; #pragma unroll
;             for (int ks = 0; ks < 4; ++ks) {
;                 bf16x8 fw[2], fx[2];
; #pragma unroll
;                 for (int ct = 0; ct < 2; ++ct) fw[ct] = *(const bf16x8*)(sb + swz(wn * 64 + ct * 32 + r, 2 * ks + h));
; #pragma unroll
;                 for (int tt = 0; tt < 2; ++tt) fx[tt] = *(const bf16x8*)(sa + swz(wm * 64 + tt * 32 + r, 2 * ks + h));
; #pragma unroll
;                 for (int ct = 0; ct < 2; ++ct)
; #pragma unroll
;                     for (int tt = 0; tt < 2; ++tt) acc[ct][tt] = __builtin_amdgcn_mfma_f32_32x32x16_bf16(fw[ct], fx[tt], acc[ct][tt], 0, 0, 0);
;             }
;             __syncthreads();
	ds_read_b128 v[102:105], v74 offset:49152
	ds_read_b128 v[106:109], v96 offset:32768
	ds_read_b128 v[110:113], v96 offset:36864
	ds_read_b128 v[114:117], v74 offset:53248
	v_mfma_f32_32x32x16_bf16 v[34:49], v[238:241], v[242:245], v[34:49]
	v_mfma_f32_32x32x16_bf16 v[18:33], v[238:241], v[246:249], v[18:33]
	v_lshl_add_u64 v[254:255], v[76:77], 0, s[26:27]
	global_load_lds_dwordx4 v[254:255], off
	v_lshl_add_u64 v[254:255], v[78:79], 0, s[26:27]
	s_mov_b32 m0, s7
	s_nop 0
	global_load_lds_dwordx4 v[254:255], off
	v_mfma_f32_32x32x16_bf16 v[50:65], v[250:253], v[242:245], v[50:65]
	v_lshl_add_u64 v[254:255], v[80:81], 0, s[26:27]
	s_mov_b32 m0, s38
	s_nop 0
	global_load_lds_dwordx4 v[254:255], off
	v_mfma_f32_32x32x16_bf16 v[2:17], v[250:253], v[246:249], v[2:17]
	s_waitcnt lgkmcnt(0)
	ds_read_b128 v[238:241], v95 offset:49152
	ds_read_b128 v[242:245], v97 offset:32768
	ds_read_b128 v[246:249], v97 offset:36864
	ds_read_b128 v[250:253], v95 offset:53248
	v_mfma_f32_32x32x16_bf16 v[34:49], v[102:105], v[106:109], v[34:49]
	v_lshl_add_u64 v[254:255], v[82:83], 0, s[26:27]
	s_mov_b32 m0, s39
	s_nop 0
	global_load_lds_dwordx4 v[254:255], off
	v_mfma_f32_32x32x16_bf16 v[18:33], v[102:105], v[110:113], v[18:33]
	v_lshl_add_u64 v[254:255], v[84:85], 0, s[26:27]
	s_mov_b32 m0, s50
	s_nop 0
	global_load_lds_dwordx4 v[254:255], off
	v_mfma_f32_32x32x16_bf16 v[50:65], v[114:117], v[106:109], v[50:65]
	v_mfma_f32_32x32x16_bf16 v[2:17], v[114:117], v[110:113], v[2:17]
	s_waitcnt lgkmcnt(0)
	ds_read_b128 v[102:105], v98 offset:49152
	ds_read_b128 v[106:109], v99 offset:32768
	ds_read_b128 v[110:113], v99 offset:36864
	ds_read_b128 v[114:117], v98 offset:53248
	v_mfma_f32_32x32x16_bf16 v[34:49], v[238:241], v[242:245], v[34:49]
	v_lshl_add_u64 v[254:255], v[86:87], 0, s[26:27]
	s_mov_b32 m0, s51
	s_nop 0
	global_load_lds_dwordx4 v[254:255], off
	v_mfma_f32_32x32x16_bf16 v[18:33], v[238:241], v[246:249], v[18:33]
	v_lshl_add_u64 v[254:255], v[88:89], 0, s[26:27]
	s_mov_b32 m0, s83
	s_nop 0
	global_load_lds_dwordx4 v[254:255], off
	v_mfma_f32_32x32x16_bf16 v[50:65], v[250:253], v[242:245], v[50:65]
	v_mfma_f32_32x32x16_bf16 v[2:17], v[250:253], v[246:249], v[2:17]
	s_waitcnt lgkmcnt(0)
	ds_read_b128 v[238:241], v100 offset:49152
	ds_read_b128 v[242:245], v101 offset:32768
	ds_read_b128 v[246:249], v101 offset:36864
	ds_read_b128 v[250:253], v100 offset:53248
	v_mfma_f32_32x32x16_bf16 v[34:49], v[102:105], v[106:109], v[34:49]
	v_lshl_add_u64 v[254:255], v[90:91], 0, s[26:27]
	s_mov_b32 m0, s90
	s_nop 0
	global_load_lds_dwordx4 v[254:255], off
	v_mfma_f32_32x32x16_bf16 v[18:33], v[102:105], v[110:113], v[18:33]
	v_mfma_f32_32x32x16_bf16 v[50:65], v[114:117], v[106:109], v[50:65]
	v_mfma_f32_32x32x16_bf16 v[2:17], v[114:117], v[110:113], v[2:17]
	s_mov_b32 m0, s86
	s_waitcnt vmcnt(0) lgkmcnt(0)
	s_barrier
	ds_read_b128 v[102:105], v74 offset:16384
	ds_read_b128 v[106:109], v96
	ds_read_b128 v[110:113], v96 offset:4096
	ds_read_b128 v[114:117], v74 offset:20480
	v_mfma_f32_32x32x16_bf16 v[34:49], v[238:241], v[242:245], v[34:49]
	v_mfma_f32_32x32x16_bf16 v[18:33], v[238:241], v[246:249], v[18:33]
	v_lshl_add_u64 v[254:255], v[76:77], 0, s[28:29]
	global_load_lds_dwordx4 v[254:255], off
	v_lshl_add_u64 v[254:255], v[78:79], 0, s[28:29]
	s_mov_b32 m0, s87
	s_nop 0
	global_load_lds_dwordx4 v[254:255], off
	v_mfma_f32_32x32x16_bf16 v[50:65], v[250:253], v[242:245], v[50:65]
	v_lshl_add_u64 v[254:255], v[80:81], 0, s[28:29]
	s_mov_b32 m0, s88
	s_nop 0
	global_load_lds_dwordx4 v[254:255], off
	v_mfma_f32_32x32x16_bf16 v[2:17], v[250:253], v[246:249], v[2:17]
	s_waitcnt lgkmcnt(0)
	ds_read_b128 v[238:241], v95 offset:16384
	ds_read_b128 v[242:245], v97
	ds_read_b128 v[246:249], v97 offset:4096
	ds_read_b128 v[250:253], v95 offset:20480
	v_mfma_f32_32x32x16_bf16 v[34:49], v[102:105], v[106:109], v[34:49]
	v_lshl_add_u64 v[254:255], v[82:83], 0, s[28:29]
	s_mov_b32 m0, s89
	s_nop 0
	global_load_lds_dwordx4 v[254:255], off
	v_mfma_f32_32x32x16_bf16 v[18:33], v[102:105], v[110:113], v[18:33]
	v_lshl_add_u64 v[254:255], v[84:85], 0, s[28:29]
	s_mov_b32 m0, s91
	s_nop 0
	global_load_lds_dwordx4 v[254:255], off
	v_mfma_f32_32x32x16_bf16 v[50:65], v[114:117], v[106:109], v[50:65]
	v_mfma_f32_32x32x16_bf16 v[2:17], v[114:117], v[110:113], v[2:17]
	s_waitcnt lgkmcnt(0)
	ds_read_b128 v[102:105], v98 offset:16384
	ds_read_b128 v[106:109], v99
	ds_read_b128 v[110:113], v99 offset:4096
	ds_read_b128 v[114:117], v98 offset:20480
	v_mfma_f32_32x32x16_bf16 v[34:49], v[238:241], v[242:245], v[34:49]
	v_lshl_add_u64 v[254:255], v[86:87], 0, s[28:29]
	s_mov_b32 m0, s92
	s_nop 0
	global_load_lds_dwordx4 v[254:255], off
	v_mfma_f32_32x32x16_bf16 v[18:33], v[238:241], v[246:249], v[18:33]
	v_lshl_add_u64 v[254:255], v[88:89], 0, s[28:29]
	s_mov_b32 m0, s93
	s_nop 0
	global_load_lds_dwordx4 v[254:255], off
	v_mfma_f32_32x32x16_bf16 v[50:65], v[250:253], v[242:245], v[50:65]
	v_mfma_f32_32x32x16_bf16 v[2:17], v[250:253], v[246:249], v[2:17]
	s_waitcnt lgkmcnt(0)
	ds_read_b128 v[238:241], v100 offset:16384
	ds_read_b128 v[242:245], v101
	ds_read_b128 v[246:249], v101 offset:4096
	ds_read_b128 v[250:253], v100 offset:20480
	v_mfma_f32_32x32x16_bf16 v[34:49], v[102:105], v[106:109], v[34:49]
	v_lshl_add_u64 v[254:255], v[90:91], 0, s[28:29]
	s_mov_b32 m0, s94
	s_nop 0
	global_load_lds_dwordx4 v[254:255], off
	v_mfma_f32_32x32x16_bf16 v[18:33], v[102:105], v[110:113], v[18:33]
	v_mfma_f32_32x32x16_bf16 v[50:65], v[114:117], v[106:109], v[50:65]
	v_mfma_f32_32x32x16_bf16 v[2:17], v[114:117], v[110:113], v[2:17]
	s_mov_b32 m0, s1
	s_waitcnt vmcnt(0) lgkmcnt(0)
	s_barrier
; template <class Epi>
; DI void gemm_phase(const u16* __restrict__ A, const u16* __restrict__ B, int mtiles, int ntiles, char* lds, const Epi& epi) {
;     ...
;         for (int kt = 0; kt < 16; ++kt) {
;             if (kt + 1 < 16) GSTAGE((kt + 1) & 1, kt + 1, ga, gb);
;             const char* sa = lds + (kt & 1) * 32768; const char* sb = sa + 16384;
; #pragma unroll
;             for (int ks = 0; ks < 4; ++ks) {
;                 bf16x8 fw[2], fx[2];
; #pragma unroll
;                 for (int ct = 0; ct < 2; ++ct) fw[ct] = *(const bf16x8*)(sb + swz(wn * 64 + ct * 32 + r, 2 * ks + h));
; #pragma unroll
;                 for (int tt = 0; tt < 2; ++tt) fx[tt] = *(const bf16x8*)(sa + swz(wm * 64 + tt * 32 + r, 2 * ks + h));
; #pragma unroll
;                 for (int ct = 0; ct < 2; ++ct)
; #pragma unroll
;                     for (int tt = 0; tt < 2; ++tt) acc[ct][tt] = __builtin_amdgcn_mfma_f32_32x32x16_bf16(fw[ct], fx[tt], acc[ct][tt], 0, 0, 0);
;             }
;             __syncthreads();
	ds_read_b128 v[102:105], v74 offset:49152
	ds_read_b128 v[106:109], v96 offset:32768
	ds_read_b128 v[110:113], v96 offset:36864
	ds_read_b128 v[114:117], v74 offset:53248
	v_mfma_f32_32x32x16_bf16 v[34:49], v[238:241], v[242:245], v[34:49]
	v_mfma_f32_32x32x16_bf16 v[18:33], v[238:241], v[246:249], v[18:33]
	v_lshl_add_u64 v[254:255], v[76:77], 0, s[30:31]
	global_load_lds_dwordx4 v[254:255], off
	v_lshl_add_u64 v[254:255], v[78:79], 0, s[30:31]
	s_mov_b32 m0, s7
	s_nop 0
	global_load_lds_dwordx4 v[254:255], off
	v_mfma_f32_32x32x16_bf16 v[50:65], v[250:253], v[242:245], v[50:65]
	v_lshl_add_u64 v[254:255], v[80:81], 0, s[30:31]
	s_mov_b32 m0, s38
	s_nop 0
	global_load_lds_dwordx4 v[254:255], off
	v_mfma_f32_32x32x16_bf16 v[2:17], v[250:253], v[246:249], v[2:17]
	s_waitcnt lgkmcnt(0)
	ds_read_b128 v[238:241], v95 offset:49152
	ds_read_b128 v[242:245], v97 offset:32768
	ds_read_b128 v[246:249], v97 offset:36864
	ds_read_b128 v[250:253], v95 offset:53248
	v_mfma_f32_32x32x16_bf16 v[34:49], v[102:105], v[106:109], v[34:49]
	v_lshl_add_u64 v[254:255], v[82:83], 0, s[30:31]
	s_mov_b32 m0, s39
	s_nop 0
	global_load_lds_dwordx4 v[254:255], off
	v_mfma_f32_32x32x16_bf16 v[18:33], v[102:105], v[110:113], v[18:33]
	v_lshl_add_u64 v[254:255], v[84:85], 0, s[30:31]
	s_mov_b32 m0, s50
	s_nop 0
	global_load_lds_dwordx4 v[254:255], off
	v_mfma_f32_32x32x16_bf16 v[50:65], v[114:117], v[106:109], v[50:65]
	v_mfma_f32_32x32x16_bf16 v[2:17], v[114:117], v[110:113], v[2:17]
	s_waitcnt lgkmcnt(0)
	ds_read_b128 v[102:105], v98 offset:49152
	ds_read_b128 v[106:109], v99 offset:32768
	ds_read_b128 v[110:113], v99 offset:36864
	ds_read_b128 v[114:117], v98 offset:53248
	v_mfma_f32_32x32x16_bf16 v[34:49], v[238:241], v[242:245], v[34:49]
	v_lshl_add_u64 v[254:255], v[86:87], 0, s[30:31]
	s_mov_b32 m0, s51
	s_nop 0
	global_load_lds_dwordx4 v[254:255], off
	v_mfma_f32_32x32x16_bf16 v[18:33], v[238:241], v[246:249], v[18:33]
	v_lshl_add_u64 v[254:255], v[88:89], 0, s[30:31]
	s_mov_b32 m0, s83
	s_nop 0
	global_load_lds_dwordx4 v[254:255], off
	v_mfma_f32_32x32x16_bf16 v[50:65], v[250:253], v[242:245], v[50:65]
	v_mfma_f32_32x32x16_bf16 v[2:17], v[250:253], v[246:249], v[2:17]
	s_waitcnt lgkmcnt(0)
	ds_read_b128 v[238:241], v100 offset:49152
	ds_read_b128 v[242:245], v101 offset:32768
	ds_read_b128 v[246:249], v101 offset:36864
	ds_read_b128 v[250:253], v100 offset:53248
	v_mfma_f32_32x32x16_bf16 v[34:49], v[102:105], v[106:109], v[34:49]
	v_lshl_add_u64 v[254:255], v[90:91], 0, s[30:31]
	s_mov_b32 m0, s90
	s_nop 0
	global_load_lds_dwordx4 v[254:255], off
	v_mfma_f32_32x32x16_bf16 v[18:33], v[102:105], v[110:113], v[18:33]
	v_mfma_f32_32x32x16_bf16 v[50:65], v[114:117], v[106:109], v[50:65]
	v_mfma_f32_32x32x16_bf16 v[2:17], v[114:117], v[110:113], v[2:17]
	s_mov_b32 m0, s86
	s_waitcnt vmcnt(0) lgkmcnt(0)
	s_barrier
	ds_read_b128 v[102:105], v74 offset:16384
	ds_read_b128 v[106:109], v96
	ds_read_b128 v[110:113], v96 offset:4096
	ds_read_b128 v[114:117], v74 offset:20480
	v_mfma_f32_32x32x16_bf16 v[34:49], v[238:241], v[242:245], v[34:49]
	v_mfma_f32_32x32x16_bf16 v[18:33], v[238:241], v[246:249], v[18:33]
	v_lshl_add_u64 v[254:255], v[76:77], 0, s[36:37]
	global_load_lds_dwordx4 v[254:255], off
	v_lshl_add_u64 v[254:255], v[78:79], 0, s[36:37]
	s_mov_b32 m0, s87
	s_nop 0
	global_load_lds_dwordx4 v[254:255], off
	v_mfma_f32_32x32x16_bf16 v[50:65], v[250:253], v[242:245], v[50:65]
	v_lshl_add_u64 v[254:255], v[80:81], 0, s[36:37]
	s_mov_b32 m0, s88
	s_nop 0
	global_load_lds_dwordx4 v[254:255], off
	v_mfma_f32_32x32x16_bf16 v[2:17], v[250:253], v[246:249], v[2:17]
	s_waitcnt lgkmcnt(0)
	ds_read_b128 v[238:241], v95 offset:16384
	ds_read_b128 v[242:245], v97
	ds_read_b128 v[246:249], v97 offset:4096
	ds_read_b128 v[250:253], v95 offset:20480
	v_mfma_f32_32x32x16_bf16 v[34:49], v[102:105], v[106:109], v[34:49]
	v_lshl_add_u64 v[254:255], v[82:83], 0, s[36:37]
	s_mov_b32 m0, s89
	s_nop 0
	global_load_lds_dwordx4 v[254:255], off
	v_mfma_f32_32x32x16_bf16 v[18:33], v[102:105], v[110:113], v[18:33]
	v_lshl_add_u64 v[254:255], v[84:85], 0, s[36:37]
	s_mov_b32 m0, s91
	s_nop 0
	global_load_lds_dwordx4 v[254:255], off
	v_mfma_f32_32x32x16_bf16 v[50:65], v[114:117], v[106:109], v[50:65]
	v_mfma_f32_32x32x16_bf16 v[2:17], v[114:117], v[110:113], v[2:17]
	s_waitcnt lgkmcnt(0)
	ds_read_b128 v[102:105], v98 offset:16384
	ds_read_b128 v[106:109], v99
	ds_read_b128 v[110:113], v99 offset:4096
	ds_read_b128 v[114:117], v98 offset:20480
	v_mfma_f32_32x32x16_bf16 v[34:49], v[238:241], v[242:245], v[34:49]
	v_lshl_add_u64 v[254:255], v[86:87], 0, s[36:37]
	s_mov_b32 m0, s92
	s_nop 0
	global_load_lds_dwordx4 v[254:255], off
	v_mfma_f32_32x32x16_bf16 v[18:33], v[238:241], v[246:249], v[18:33]
	v_lshl_add_u64 v[254:255], v[88:89], 0, s[36:37]
	s_mov_b32 m0, s93
	s_nop 0
	global_load_lds_dwordx4 v[254:255], off
	v_mfma_f32_32x32x16_bf16 v[50:65], v[250:253], v[242:245], v[50:65]
	v_mfma_f32_32x32x16_bf16 v[2:17], v[250:253], v[246:249], v[2:17]
	s_waitcnt lgkmcnt(0)
	ds_read_b128 v[238:241], v100 offset:16384
	ds_read_b128 v[242:245], v101
	ds_read_b128 v[246:249], v101 offset:4096
	ds_read_b128 v[250:253], v100 offset:20480
	v_mfma_f32_32x32x16_bf16 v[34:49], v[102:105], v[106:109], v[34:49]
	v_lshl_add_u64 v[254:255], v[90:91], 0, s[36:37]
	s_mov_b32 m0, s94
	s_nop 0
	global_load_lds_dwordx4 v[254:255], off
	v_mfma_f32_32x32x16_bf16 v[18:33], v[102:105], v[110:113], v[18:33]
	v_mfma_f32_32x32x16_bf16 v[50:65], v[114:117], v[106:109], v[50:65]
	v_mfma_f32_32x32x16_bf16 v[2:17], v[114:117], v[110:113], v[2:17]
	s_mov_b32 m0, s1
	s_waitcnt vmcnt(0) lgkmcnt(0)
	s_barrier
; template <class Epi>
; DI void gemm_phase(const u16* __restrict__ A, const u16* __restrict__ B, int mtiles, int ntiles, char* lds, const Epi& epi) {
;     ...
;         for (int kt = 0; kt < 16; ++kt) {
;             if (kt + 1 < 16) GSTAGE((kt + 1) & 1, kt + 1, ga, gb);
;             const char* sa = lds + (kt & 1) * 32768; const char* sb = sa + 16384;
; #pragma unroll
;             for (int ks = 0; ks < 4; ++ks) {
;                 bf16x8 fw[2], fx[2];
; #pragma unroll
;                 for (int ct = 0; ct < 2; ++ct) fw[ct] = *(const bf16x8*)(sb + swz(wn * 64 + ct * 32 + r, 2 * ks + h));
; #pragma unroll
;                 for (int tt = 0; tt < 2; ++tt) fx[tt] = *(const bf16x8*)(sa + swz(wm * 64 + tt * 32 + r, 2 * ks + h));
; #pragma unroll
;                 for (int ct = 0; ct < 2; ++ct)
; #pragma unroll
;                     for (int tt = 0; tt < 2; ++tt) acc[ct][tt] = __builtin_amdgcn_mfma_f32_32x32x16_bf16(fw[ct], fx[tt], acc[ct][tt], 0, 0, 0);
;             }
;             __syncthreads();
	ds_read_b128 v[102:105], v74 offset:49152
	ds_read_b128 v[106:109], v96 offset:32768
	ds_read_b128 v[110:113], v96 offset:36864
	ds_read_b128 v[114:117], v74 offset:53248
	v_mfma_f32_32x32x16_bf16 v[34:49], v[238:241], v[242:245], v[34:49]
	v_mfma_f32_32x32x16_bf16 v[18:33], v[238:241], v[246:249], v[18:33]
	v_lshl_add_u64 v[254:255], v[76:77], 0, s[68:69]
	global_load_lds_dwordx4 v[254:255], off
	v_lshl_add_u64 v[254:255], v[78:79], 0, s[68:69]
	s_mov_b32 m0, s7
	v_lshl_add_u64 v[76:77], v[76:77], 0, s[70:71]
	global_load_lds_dwordx4 v[254:255], off
	v_mfma_f32_32x32x16_bf16 v[50:65], v[250:253], v[242:245], v[50:65]
	v_lshl_add_u64 v[254:255], v[80:81], 0, s[68:69]
	s_mov_b32 m0, s38
	s_nop 0
	global_load_lds_dwordx4 v[254:255], off
	v_mfma_f32_32x32x16_bf16 v[2:17], v[250:253], v[246:249], v[2:17]
	s_waitcnt lgkmcnt(0)
	ds_read_b128 v[238:241], v95 offset:49152
	ds_read_b128 v[242:245], v97 offset:32768
	ds_read_b128 v[246:249], v97 offset:36864
	ds_read_b128 v[250:253], v95 offset:53248
	v_mfma_f32_32x32x16_bf16 v[34:49], v[102:105], v[106:109], v[34:49]
	v_lshl_add_u64 v[254:255], v[82:83], 0, s[68:69]
	s_mov_b32 m0, s39
	s_nop 0
	global_load_lds_dwordx4 v[254:255], off
	v_mfma_f32_32x32x16_bf16 v[18:33], v[102:105], v[110:113], v[18:33]
	v_lshl_add_u64 v[254:255], v[84:85], 0, s[68:69]
	s_mov_b32 m0, s50
	s_nop 0
	global_load_lds_dwordx4 v[254:255], off
	v_mfma_f32_32x32x16_bf16 v[50:65], v[114:117], v[106:109], v[50:65]
	v_mfma_f32_32x32x16_bf16 v[2:17], v[114:117], v[110:113], v[2:17]
	s_waitcnt lgkmcnt(0)
	ds_read_b128 v[102:105], v98 offset:49152
	ds_read_b128 v[106:109], v99 offset:32768
	ds_read_b128 v[110:113], v99 offset:36864
	ds_read_b128 v[114:117], v98 offset:53248
	v_mfma_f32_32x32x16_bf16 v[34:49], v[238:241], v[242:245], v[34:49]
	v_lshl_add_u64 v[254:255], v[86:87], 0, s[68:69]
	s_mov_b32 m0, s51
	s_nop 0
	global_load_lds_dwordx4 v[254:255], off
	v_mfma_f32_32x32x16_bf16 v[18:33], v[238:241], v[246:249], v[18:33]
	v_lshl_add_u64 v[254:255], v[88:89], 0, s[68:69]
	s_mov_b32 m0, s83
	s_nop 0
	global_load_lds_dwordx4 v[254:255], off
	v_mfma_f32_32x32x16_bf16 v[50:65], v[250:253], v[242:245], v[50:65]
	v_mfma_f32_32x32x16_bf16 v[2:17], v[250:253], v[246:249], v[2:17]
	s_waitcnt lgkmcnt(0)
	ds_read_b128 v[238:241], v100 offset:49152
	ds_read_b128 v[242:245], v101 offset:32768
	ds_read_b128 v[246:249], v101 offset:36864
	ds_read_b128 v[250:253], v100 offset:53248
	v_mfma_f32_32x32x16_bf16 v[34:49], v[102:105], v[106:109], v[34:49]
	v_lshl_add_u64 v[254:255], v[90:91], 0, s[68:69]
	s_mov_b32 m0, s90
	s_nop 0
	global_load_lds_dwordx4 v[254:255], off
	v_mfma_f32_32x32x16_bf16 v[18:33], v[102:105], v[110:113], v[18:33]
	v_mfma_f32_32x32x16_bf16 v[50:65], v[114:117], v[106:109], v[50:65]
	v_mfma_f32_32x32x16_bf16 v[2:17], v[114:117], v[110:113], v[2:17]
	s_mov_b32 m0, s86
	s_mov_b32 s86, 0
	s_waitcnt vmcnt(0) lgkmcnt(0)
	s_barrier
; #define TILE_MN(t, M0, N0) do { int pan_ = (t) / (mtiles * 8); if (pan_ >= npan) pan_ = npan - 1; const int pw_ = (pan_ == npan - 1) ? ntiles - 8 * pan_ : 8; const int loc_ = (t) - pan_ * mtiles * 8; \
;         M0 = (loc_ / pw_) * 128; N0 = (8 * pan_ + loc_ % pw_) * 128; } while (0)
; template <class Epi>
; DI void gemm_phase(const u16* __restrict__ A, const u16* __restrict__ B, int mtiles, int ntiles, char* lds, const Epi& epi) {
;     ...
;         for (int kt = 0; kt < 16; ++kt) {
;             if (kt + 1 < 16) GSTAGE((kt + 1) & 1, kt + 1, ga, gb);
;             const char* sa = lds + (kt & 1) * 32768; const char* sb = sa + 16384;
; #pragma unroll
;             for (int ks = 0; ks < 4; ++ks) {
;                 bf16x8 fw[2], fx[2];
; #pragma unroll
;                 for (int ct = 0; ct < 2; ++ct) fw[ct] = *(const bf16x8*)(sb + swz(wn * 64 + ct * 32 + r, 2 * ks + h));
; #pragma unroll
;                 for (int tt = 0; tt < 2; ++tt) fx[tt] = *(const bf16x8*)(sa + swz(wm * 64 + tt * 32 + r, 2 * ks + h));
; #pragma unroll
;                 for (int ct = 0; ct < 2; ++ct)
; #pragma unroll
;                     for (int tt = 0; tt < 2; ++tt) acc[ct][tt] = __builtin_amdgcn_mfma_f32_32x32x16_bf16(fw[ct], fx[tt], acc[ct][tt], 0, 0, 0);
;             }
;             __syncthreads();
;         }
;         const int nxt = tile + (int)gridDim.x; int m1 = 0, n1 = 0;
;         if (nxt < ntile) { TILE_MN(nxt, m1, n1); GSTAGE(0, 0, A + (size_t)m1 * 1024, B + (size_t)n1 * 1024); }
	global_load_lds_dwordx4 v[76:77], off
	v_lshl_add_u64 v[76:77], v[78:79], 0, s[70:71]
	s_mov_b32 m0, s87
	v_mfma_f32_32x32x16_bf16 v[34:49], v[238:241], v[242:245], v[34:49]
	global_load_lds_dwordx4 v[76:77], off
	v_lshl_add_u64 v[76:77], v[80:81], 0, s[70:71]
	s_mov_b32 m0, s88
	s_mov_b32 s88, 0
	global_load_lds_dwordx4 v[76:77], off
	v_lshl_add_u64 v[76:77], v[82:83], 0, s[70:71]
	s_mov_b32 m0, s89
	v_mfma_f32_32x32x16_bf16 v[18:33], v[238:241], v[246:249], v[18:33]
	global_load_lds_dwordx4 v[76:77], off
	v_lshl_add_u64 v[76:77], v[84:85], 0, s[70:71]
	s_mov_b32 m0, s91
	s_nop 0
	global_load_lds_dwordx4 v[76:77], off
	v_lshl_add_u64 v[76:77], v[86:87], 0, s[70:71]
	s_mov_b32 m0, s92
	v_mfma_f32_32x32x16_bf16 v[50:65], v[250:253], v[242:245], v[50:65]
	global_load_lds_dwordx4 v[76:77], off
	v_lshl_add_u64 v[76:77], v[88:89], 0, s[70:71]
	s_mov_b32 m0, s93
	s_nop 0
	global_load_lds_dwordx4 v[76:77], off
	v_lshl_add_u64 v[76:77], v[90:91], 0, s[70:71]
	s_mov_b32 m0, s94
	v_mfma_f32_32x32x16_bf16 v[2:17], v[250:253], v[246:249], v[2:17]
	global_load_lds_dwordx4 v[76:77], off
	ds_read_b128 v[76:79], v74 offset:16384
	ds_read_b128 v[80:83], v96
	ds_read_b128 v[84:87], v96 offset:4096
	ds_read_b128 v[88:91], v74 offset:20480
	s_waitcnt lgkmcnt(0)
	v_mfma_f32_32x32x16_bf16 v[34:49], v[76:79], v[80:83], v[34:49]
	v_mfma_f32_32x32x16_bf16 v[18:33], v[76:79], v[84:87], v[18:33]
	v_mfma_f32_32x32x16_bf16 v[50:65], v[88:91], v[80:83], v[50:65]
	v_mfma_f32_32x32x16_bf16 v[2:17], v[88:91], v[84:87], v[2:17]
	ds_read_b128 v[76:79], v95 offset:16384
	ds_read_b128 v[80:83], v97
	ds_read_b128 v[84:87], v97 offset:4096
	ds_read_b128 v[88:91], v95 offset:20480
	s_waitcnt lgkmcnt(0)
	v_mfma_f32_32x32x16_bf16 v[34:49], v[76:79], v[80:83], v[34:49]
	v_mfma_f32_32x32x16_bf16 v[18:33], v[76:79], v[84:87], v[18:33]
	v_mfma_f32_32x32x16_bf16 v[50:65], v[88:91], v[80:83], v[50:65]
	v_mfma_f32_32x32x16_bf16 v[2:17], v[88:91], v[84:87], v[2:17]
	ds_read_b128 v[76:79], v98 offset:16384
	ds_read_b128 v[80:83], v99
	ds_read_b128 v[84:87], v99 offset:4096
	ds_read_b128 v[88:91], v98 offset:20480
	s_waitcnt lgkmcnt(0)
	v_mfma_f32_32x32x16_bf16 v[34:49], v[76:79], v[80:83], v[34:49]
	v_mfma_f32_32x32x16_bf16 v[18:33], v[76:79], v[84:87], v[18:33]
	v_mfma_f32_32x32x16_bf16 v[50:65], v[88:91], v[80:83], v[50:65]
	v_mfma_f32_32x32x16_bf16 v[2:17], v[88:91], v[84:87], v[2:17]
	ds_read_b128 v[76:79], v100 offset:16384
	ds_read_b128 v[80:83], v101
	ds_read_b128 v[84:87], v101 offset:4096
	ds_read_b128 v[88:91], v100 offset:20480
	s_waitcnt vmcnt(0) lgkmcnt(0)
	s_barrier
	v_mfma_f32_32x32x16_bf16 v[34:49], v[76:79], v[80:83], v[34:49]
	v_mfma_f32_32x32x16_bf16 v[18:33], v[76:79], v[84:87], v[18:33]
	v_mfma_f32_32x32x16_bf16 v[50:65], v[88:91], v[80:83], v[50:65]
	v_mfma_f32_32x32x16_bf16 v[2:17], v[88:91], v[84:87], v[2:17]
	ds_read_b128 v[76:79], v96 offset:32768
	ds_read_b128 v[80:83], v96 offset:36864
	ds_read_b128 v[84:87], v74 offset:49152
	ds_read_b128 v[88:91], v74 offset:53248
	s_waitcnt lgkmcnt(1)
	v_mfma_f32_32x32x16_bf16 v[34:49], v[84:87], v[76:79], v[34:49]
	v_mfma_f32_32x32x16_bf16 v[18:33], v[84:87], v[80:83], v[18:33]
	s_waitcnt lgkmcnt(0)
	v_mfma_f32_32x32x16_bf16 v[50:65], v[88:91], v[76:79], v[50:65]
	v_mfma_f32_32x32x16_bf16 v[2:17], v[88:91], v[80:83], v[2:17]
	ds_read_b128 v[76:79], v95 offset:49152
	ds_read_b128 v[80:83], v97 offset:32768
	ds_read_b128 v[84:87], v97 offset:36864
	ds_read_b128 v[88:91], v95 offset:53248
	s_waitcnt lgkmcnt(2)
	v_mfma_f32_32x32x16_bf16 v[34:49], v[76:79], v[80:83], v[34:49]
	s_waitcnt lgkmcnt(1)
	v_mfma_f32_32x32x16_bf16 v[18:33], v[76:79], v[84:87], v[18:33]
	s_waitcnt lgkmcnt(0)
	v_mfma_f32_32x32x16_bf16 v[50:65], v[88:91], v[80:83], v[50:65]
	v_mfma_f32_32x32x16_bf16 v[2:17], v[88:91], v[84:87], v[2:17]
	ds_read_b128 v[76:79], v98 offset:49152
	ds_read_b128 v[80:83], v99 offset:32768
	ds_read_b128 v[84:87], v99 offset:36864
	ds_read_b128 v[88:91], v98 offset:53248
	s_waitcnt lgkmcnt(2)
	v_mfma_f32_32x32x16_bf16 v[34:49], v[76:79], v[80:83], v[34:49]
	s_waitcnt lgkmcnt(1)
	v_mfma_f32_32x32x16_bf16 v[18:33], v[76:79], v[84:87], v[18:33]
	s_waitcnt lgkmcnt(0)
	v_mfma_f32_32x32x16_bf16 v[50:65], v[88:91], v[80:83], v[50:65]
	v_mfma_f32_32x32x16_bf16 v[2:17], v[88:91], v[84:87], v[2:17]
	ds_read_b128 v[76:79], v100 offset:49152
	ds_read_b128 v[80:83], v101 offset:32768
	ds_read_b128 v[84:87], v101 offset:36864
	ds_read_b128 v[88:91], v100 offset:53248
	s_waitcnt lgkmcnt(0)
	s_barrier
	v_mfma_f32_32x32x16_bf16 v[34:49], v[76:79], v[80:83], v[34:49]
	v_mfma_f32_32x32x16_bf16 v[18:33], v[76:79], v[84:87], v[18:33]
	v_mfma_f32_32x32x16_bf16 v[50:65], v[88:91], v[80:83], v[50:65]
	v_mfma_f32_32x32x16_bf16 v[2:17], v[88:91], v[84:87], v[2:17]
	s_cbranch_scc1 .LBB0_99
	s_mov_b32 m0, s1
	s_mov_b32 s96, s33
	s_cmpk_lt_i32 s33, 0xe97
	s_cbranch_scc1 .Lrm_done_m1
	s_cmpk_lt_i32 s33, 0x1000
	s_cbranch_scc0 .Lrm_def_m1
	s_add_i32 s96, s33, 0x104
	s_cmpk_lt_i32 s33, 0xfdc
	s_cbranch_scc0 .Lrm_done_m1
	s_sub_i32 s97, s33, 0xe97
	s_mul_i32 s97, s97, 0x3334
	s_lshr_b32 s97, s97, 16
	s_lshl_b32 s97, s97, 2
	s_add_i32 s96, s33, s97
	s_branch .Lrm_done_m1

; #define TILE_MN(t, M0, N0) do { int pan_ = (t) / (mtiles * 8); if (pan_ >= npan) pan_ = npan - 1; const int pw_ = (pan_ == npan - 1) ? ntiles - 8 * pan_ : 8; const int loc_ = (t) - pan_ * mtiles * 8; \
;         M0 = (loc_ / pw_) * 128; N0 = (8 * pan_ + loc_ % pw_) * 128; } while (0)
; template <class Epi>
; DI void gemm_phase(const u16* __restrict__ A, const u16* __restrict__ B, int mtiles, int ntiles, char* lds, const Epi& epi) {
;     ...
;         if (nxt < ntile) { TILE_MN(nxt, m1, n1); GSTAGE(0, 0, A + (size_t)m1 * 1024, B + (size_t)n1 * 1024); }
.Lrm_done_m1:
	s_mul_hi_i32 s1, s96, 0x3e0f83e1
	s_lshr_b32 s86, s1, 31
	s_ashr_i32 s1, s1, 8
	s_add_i32 s1, s1, s86
	s_cmpk_lt_i32 s96, 0x1080
	s_cselect_b32 s1, s1, 3
	s_cmp_eq_u32 s1, 3
	s_cselect_b32 s87, 9, 8
	v_cvt_f32_ubyte0_e32 v74, s87
	v_rcp_iflag_f32_e32 v74, v74
	s_sub_i32 s91, 0, s87
	s_mul_i32 s86, s1, 0xfffffbe0
	s_add_i32 s88, s96, s86
	v_mul_f32_e32 v74, 0x4f7ffffe, v74
	v_cvt_u32_f32_e32 v74, v74
	s_abs_i32 s89, s88
	s_ashr_i32 s86, s88, 31
	v_readfirstlane_b32 s92, v74
	s_mul_i32 s91, s91, s92
	s_mul_hi_u32 s91, s92, s91
	s_add_i32 s92, s92, s91
	s_mul_hi_u32 s91, s89, s92
	s_mul_i32 s92, s91, s87
	s_sub_i32 s89, s89, s92
	s_add_i32 s92, s91, 1
	s_sub_i32 s93, s89, s87
	s_cmp_ge_u32 s89, s87
	s_cselect_b32 s91, s92, s91
	s_cselect_b32 s89, s93, s89
	s_add_i32 s92, s91, 1
	s_cmp_ge_u32 s89, s87
	s_cselect_b32 s89, s92, s91
	s_xor_b32 s89, s89, s86
	s_sub_i32 s89, s89, s86
	s_lshl_b32 s86, s89, 7
	s_mul_i32 s89, s89, s87
	s_sub_i32 s87, s88, s89
	s_lshl_b32 s1, s1, 10
	s_lshl_b32 s87, s87, 7
	s_add_i32 s88, s87, s1
	s_ashr_i32 s87, s86, 31
	s_lshl_b64 s[92:93], s[86:87], 11
	s_add_u32 s92, s54, s92
	s_addc_u32 s93, s55, s93
	s_ashr_i32 s89, s88, 31
	s_lshl_b64 s[94:95], s[88:89], 11
	v_readlane_b32 s1, v236, 9
	s_add_u32 s94, s1, s94
	v_readlane_b32 s1, v236, 11
	s_addc_u32 s95, s1, s95
	v_lshl_add_u64 v[76:77], s[92:93], 0, v[66:67]
	global_load_lds_dwordx4 v[76:77], off
	v_lshl_add_u64 v[66:67], s[94:95], 0, v[66:67]
	s_mov_b32 m0, s7
	s_nop 0
	global_load_lds_dwordx4 v[66:67], off
	v_lshl_add_u64 v[66:67], s[92:93], 0, v[68:69]
	s_mov_b32 m0, s38
	s_nop 0
	global_load_lds_dwordx4 v[66:67], off
	v_lshl_add_u64 v[66:67], s[94:95], 0, v[68:69]
	s_mov_b32 m0, s39
	s_nop 0
	global_load_lds_dwordx4 v[66:67], off
	v_lshl_add_u64 v[66:67], s[92:93], 0, v[70:71]
	s_mov_b32 m0, s50
	s_nop 0
	global_load_lds_dwordx4 v[66:67], off
	v_lshl_add_u64 v[66:67], s[94:95], 0, v[70:71]
	s_mov_b32 m0, s51
	s_nop 0
	global_load_lds_dwordx4 v[66:67], off
	v_lshl_add_u64 v[66:67], s[92:93], 0, v[72:73]
	s_mov_b32 m0, s83
	s_nop 0
	global_load_lds_dwordx4 v[66:67], off
	v_lshl_add_u64 v[66:67], s[94:95], 0, v[72:73]
	s_mov_b32 m0, s90
	s_nop 0
	global_load_lds_dwordx4 v[66:67], off

; #define TILE_MN(t, M0, N0) do { int pan_ = (t) / (mtiles * 8); if (pan_ >= npan) pan_ = npan - 1; const int pw_ = (pan_ == npan - 1) ? ntiles - 8 * pan_ : 8; const int loc_ = (t) - pan_ * mtiles * 8; \
;         M0 = (loc_ / pw_) * 128; N0 = (8 * pan_ + loc_ % pw_) * 128; } while (0)
; template <class Epi>
; DI void gemm_phase(const u16* __restrict__ A, const u16* __restrict__ B, int mtiles, int ntiles, char* lds, const Epi& epi) {
;     const int ntile = mtiles * ntiles;
;     const int vb = (blockIdx.x & 7) * (gridDim.x >> 3) + (blockIdx.x >> 3);
;     const int npan = ntiles >> 3;
;     int tile = vb; if (tile >= ntile) return;
;     ...
;     int m0, n0; TILE_MN(tile, m0, n0);
;     {
;         const int lane = threadIdx.x & 63, wave = __builtin_amdgcn_readfirstlane(threadIdx.x >> 6);
;         unsigned soff[4];
; #pragma unroll
;         for (int i = 0; i < 4; ++i) { const int row = 8 * (i * 4 + wave) + (lane >> 3); const int ch = (lane & 7) ^ ((row >> 1) & 7); soff[i] = (unsigned)(row * 1024 + ch * 8); }
;         GSTAGE(0, 0, A + (size_t)m0 * 1024, B + (size_t)n0 * 1024);
.Lp2_entry:
	s_cmp_lg_u32 s100, 0
	s_cbranch_scc1 .Llt_skip
	s_bitcmp0_b32 s33, 7
	s_cbranch_scc1 .Llt_tile
	s_cmp_lt_u32 s33, 0x1fc
	s_cbranch_scc1 .Llt_skip
	s_mov_b32 s100, 1
	s_sub_i32 s2, s33, 0x1fc
	s_lshl_b32 s2, s2, 16
	s_add_u32 s12, s54, 0xfc0000
	s_addc_u32 s13, s55, 0
	s_add_u32 s12, s12, s2
	s_addc_u32 s13, s13, 0
	s_add_u32 s14, s52, s2
	s_addc_u32 s15, s53, 0
	v_lshlrev_b32_e32 v66, 4, v0
	global_load_dwordx4 v[2:5], v66, s[12:13]
	v_add_u32_e32 v66, 0x1000, v66
	global_load_dwordx4 v[6:9], v66, s[12:13]
	v_add_u32_e32 v66, 0x1000, v66
	global_load_dwordx4 v[10:13], v66, s[12:13]
	v_add_u32_e32 v66, 0x1000, v66
	global_load_dwordx4 v[14:17], v66, s[12:13]
	v_add_u32_e32 v66, 0x1000, v66
	global_load_dwordx4 v[18:21], v66, s[12:13]
	v_add_u32_e32 v66, 0x1000, v66
	global_load_dwordx4 v[22:25], v66, s[12:13]
	v_add_u32_e32 v66, 0x1000, v66
	global_load_dwordx4 v[26:29], v66, s[12:13]
	v_add_u32_e32 v66, 0x1000, v66
	global_load_dwordx4 v[30:33], v66, s[12:13]
	v_add_u32_e32 v66, 0x1000, v66
	global_load_dwordx4 v[34:37], v66, s[12:13]
	v_add_u32_e32 v66, 0x1000, v66
	global_load_dwordx4 v[38:41], v66, s[12:13]
	v_add_u32_e32 v66, 0x1000, v66
	global_load_dwordx4 v[42:45], v66, s[12:13]
	v_add_u32_e32 v66, 0x1000, v66
	global_load_dwordx4 v[46:49], v66, s[12:13]
	v_add_u32_e32 v66, 0x1000, v66
	global_load_dwordx4 v[50:53], v66, s[12:13]
	v_add_u32_e32 v66, 0x1000, v66
	global_load_dwordx4 v[54:57], v66, s[12:13]
	v_add_u32_e32 v66, 0x1000, v66
	global_load_dwordx4 v[58:61], v66, s[12:13]
	v_add_u32_e32 v66, 0x1000, v66
	global_load_dwordx4 v[62:65], v66, s[12:13]
	v_add_u32_e32 v66, 0x1000, v66
	v_lshlrev_b32_e32 v66, 4, v0
	s_waitcnt vmcnt(0)
	global_store_dwordx4 v66, v[2:5], s[14:15]
	v_add_u32_e32 v66, 0x1000, v66
	global_store_dwordx4 v66, v[6:9], s[14:15]
	v_add_u32_e32 v66, 0x1000, v66
	global_store_dwordx4 v66, v[10:13], s[14:15]
	v_add_u32_e32 v66, 0x1000, v66
	global_store_dwordx4 v66, v[14:17], s[14:15]
	v_add_u32_e32 v66, 0x1000, v66
	global_store_dwordx4 v66, v[18:21], s[14:15]
	v_add_u32_e32 v66, 0x1000, v66
	global_store_dwordx4 v66, v[22:25], s[14:15]
	v_add_u32_e32 v66, 0x1000, v66
	global_store_dwordx4 v66, v[26:29], s[14:15]
	v_add_u32_e32 v66, 0x1000, v66
	global_store_dwordx4 v66, v[30:33], s[14:15]
	v_add_u32_e32 v66, 0x1000, v66
	global_store_dwordx4 v66, v[34:37], s[14:15]
	v_add_u32_e32 v66, 0x1000, v66
	global_store_dwordx4 v66, v[38:41], s[14:15]
	v_add_u32_e32 v66, 0x1000, v66
	global_store_dwordx4 v66, v[42:45], s[14:15]
	v_add_u32_e32 v66, 0x1000, v66
	global_store_dwordx4 v66, v[46:49], s[14:15]
	v_add_u32_e32 v66, 0x1000, v66
	global_store_dwordx4 v66, v[50:53], s[14:15]
	v_add_u32_e32 v66, 0x1000, v66
	global_store_dwordx4 v66, v[54:57], s[14:15]
	v_add_u32_e32 v66, 0x1000, v66
	global_store_dwordx4 v66, v[58:61], s[14:15]
	v_add_u32_e32 v66, 0x1000, v66
	global_store_dwordx4 v66, v[62:65], s[14:15]
	v_add_u32_e32 v66, 0x1000, v66
	s_waitcnt vmcnt(0)
	s_barrier
	s_and_saveexec_b64 s[0:1], s[34:35]
	s_add_u32 s12, s54, 0xfc14808
	s_addc_u32 s13, s55, 0
	v_mov_b32_e32 v240, 0
	v_mov_b32_e32 v241, 1
	global_atomic_add v240, v241, s[12:13]
	s_or_b64 exec, exec, s[0:1]
	s_branch .Llt_skip
.Llt_tile:
	s_mov_b32 s100, 1
	v_writelane_b32 v237, s54, 4
	v_writelane_b32 v237, s55, 5
	s_and_b32 s4, s33, 0x7f
	s_lshr_b32 s3, s33, 8
	s_lshl_b32 s3, s3, 7
	s_or_b32 s4, s4, s3
	s_and_b32 s2, s33, 7
	s_lshr_b32 s3, s4, 5
	s_lshl3_add_u32 s2, s2, s3
	s_bfe_u32 s3, s4, 0x20003
	s_lshl2_add_u32 s2, s2, s3
	s_add_i32 s33, s2, 0x1000
.Llt_common:
	s_movk_i32 s95, 0x200
	s_add_u32 s2, s54, 0x2b60000
	s_addc_u32 s3, s55, 0
	v_readlane_b32 s4, v236, 5
	v_readlane_b32 s5, v236, 6
	s_sub_u32 s4, s4, 0xc8
	s_subb_u32 s5, s5, 0
	s_load_dwordx16 s[72:87], s[4:5], 0x40
	s_load_dwordx8 s[40:47], s[4:5], 0x80
	s_load_dwordx2 s[48:49], s[4:5], 0xa0
	s_waitcnt lgkmcnt(0)
	s_mov_b32 s96, s33
	s_cmpk_lt_i32 s33, 0xe97
	s_cbranch_scc1 .Lrm_done_l0
	s_cmpk_lt_i32 s33, 0x1000
	s_cbranch_scc0 .Lrm_def_l0
	s_add_i32 s96, s33, 0x104
	s_cmpk_lt_i32 s33, 0xfdc
	s_cbranch_scc0 .Lrm_done_l0
	s_sub_i32 s97, s33, 0xe97
	s_mul_i32 s97, s97, 0x3334
	s_lshr_b32 s97, s97, 16
	s_lshl_b32 s97, s97, 2
	s_add_i32 s96, s33, s97
	s_branch .Lrm_done_l0

; #define TILE_MN(t, M0, N0) do { int pan_ = (t) / (mtiles * 8); if (pan_ >= npan) pan_ = npan - 1; const int pw_ = (pan_ == npan - 1) ? ntiles - 8 * pan_ : 8; const int loc_ = (t) - pan_ * mtiles * 8; \
;         M0 = (loc_ / pw_) * 128; N0 = (8 * pan_ + loc_ % pw_) * 128; } while (0)
; template <class Epi>
; DI void gemm_phase(const u16* __restrict__ A, const u16* __restrict__ B, int mtiles, int ntiles, char* lds, const Epi& epi) {
;     ...
;     int m0, n0; TILE_MN(tile, m0, n0);
;     {
;         const int lane = threadIdx.x & 63, wave = __builtin_amdgcn_readfirstlane(threadIdx.x >> 6);
;         unsigned soff[4];
; #pragma unroll
;         for (int i = 0; i < 4; ++i) { const int row = 8 * (i * 4 + wave) + (lane >> 3); const int ch = (lane & 7) ^ ((row >> 1) & 7); soff[i] = (unsigned)(row * 1024 + ch * 8); }
;         GSTAGE(0, 0, A + (size_t)m0 * 1024, B + (size_t)n0 * 1024);
.Lrm_done_l0:
	s_add_u32 s10, s54, 0x2100000
	s_mul_hi_i32 s0, s96, 0x3e0f83e1
	s_addc_u32 s11, s55, 0
	s_lshr_b32 s1, s0, 31
	s_ashr_i32 s0, s0, 8
	s_add_i32 s0, s0, s1
	s_cmpk_lt_i32 s96, 0x1080
	s_cselect_b32 s0, s0, 3
	s_cmp_eq_u32 s0, 3
	s_cselect_b32 s1, 9, 8
	v_cvt_f32_ubyte0_e32 v2, s1
	v_rcp_iflag_f32_e32 v2, v2
	s_sub_i32 s7, 0, s1
	s_mul_i32 s4, s0, 0xfffffbe0
	s_add_i32 s4, s4, s96
	v_mul_f32_e32 v2, 0x4f7ffffe, v2
	v_cvt_u32_f32_e32 v2, v2
	s_abs_i32 s6, s4
	s_ashr_i32 s5, s4, 31
	v_mov_b32_e32 v75, 0
	v_readfirstlane_b32 s8, v2
	s_mul_i32 s7, s7, s8
	s_mul_hi_u32 s7, s8, s7
	s_add_i32 s8, s8, s7
	s_mul_hi_u32 s7, s6, s8
	s_mul_i32 s8, s7, s1
	s_sub_i32 s6, s6, s8
	s_add_i32 s8, s7, 1
	s_sub_i32 s9, s6, s1
	s_cmp_ge_u32 s6, s1
	s_cselect_b32 s7, s8, s7
	s_cselect_b32 s6, s9, s6
	s_add_i32 s8, s7, 1
	s_cmp_ge_u32 s6, s1
	s_cselect_b32 s6, s8, s7
	s_xor_b32 s6, s6, s5
	s_sub_i32 s5, s6, s5
	s_mul_i32 s1, s5, s1
	s_sub_i32 s1, s4, s1
	v_readfirstlane_b32 s4, v0
	s_lshl_b32 s82, s5, 7
	s_lshl_b32 s1, s1, 7
	s_lshr_b32 s6, s4, 6
	v_bfe_u32 v2, v0, 3, 3
	s_lshl_b32 s0, s0, 10
	s_ashr_i32 s83, s82, 31
	v_lshl_or_b32 v2, s6, 3, v2
	s_add_i32 s0, s1, s0
	s_lshl_b64 s[4:5], s[82:83], 11
	v_lshrrev_b32_e32 v3, 1, v2
	v_readlane_b32 s98, v237, 4
	v_readlane_b32 s99, v237, 5
	s_add_u32 s4, s98, s4
	v_xor_b32_e32 v3, v3, v0
	s_addc_u32 s5, s99, s5
	s_ashr_i32 s1, s0, 31
	s_lshl_b32 s8, s6, 10
	s_lshl_b64 s[6:7], s[0:1], 11
	v_lshlrev_b32_e32 v3, 4, v3
	s_add_u32 s6, s10, s6
	v_and_b32_e32 v3, 0x70, v3
	v_add_u32_e32 v4, 32, v2
	s_addc_u32 s7, s11, s7
	v_lshl_or_b32 v74, v2, 11, v3
	s_add_i32 s1, s8, 0
	v_lshrrev_b32_e32 v5, 1, v4
	v_add_u32_e32 v6, 64, v2
	v_add_u32_e32 v8, 0x60, v2
	v_lshl_add_u64 v[2:3], s[4:5], 0, v[74:75]
	s_mov_b32 m0, s1
	v_xor_b32_e32 v5, v5, v0
	global_load_lds_dwordx4 v[2:3], off
	v_lshl_add_u64 v[2:3], s[6:7], 0, v[74:75]
	s_add_i32 m0, s1, 0x4000
	v_lshrrev_b32_e32 v7, 1, v6
	global_load_lds_dwordx4 v[2:3], off
	v_lshlrev_b32_e32 v2, 4, v5
	v_and_b32_e32 v2, 0x70, v2
	v_lshl_or_b32 v74, v4, 11, v2
	v_lshl_add_u64 v[2:3], s[4:5], 0, v[74:75]
	s_add_i32 m0, s1, 0x1000
	v_xor_b32_e32 v7, v7, v0
	global_load_lds_dwordx4 v[2:3], off
	v_lshl_add_u64 v[2:3], s[6:7], 0, v[74:75]
	s_add_i32 m0, s1, 0x5000
	v_lshrrev_b32_e32 v9, 1, v8
	global_load_lds_dwordx4 v[2:3], off
	v_lshlrev_b32_e32 v2, 4, v7
	v_and_b32_e32 v2, 0x70, v2
	v_lshl_or_b32 v74, v6, 11, v2
	v_lshl_add_u64 v[2:3], s[4:5], 0, v[74:75]
	s_add_i32 m0, s1, 0x2000
	v_xor_b32_e32 v9, v9, v0
	global_load_lds_dwordx4 v[2:3], off
	v_lshl_add_u64 v[2:3], s[6:7], 0, v[74:75]
	s_add_i32 m0, s1, 0x6000
	v_writelane_b32 v236, s10, 9
	global_load_lds_dwordx4 v[2:3], off
	v_lshlrev_b32_e32 v2, 4, v9
	v_and_b32_e32 v2, 0x70, v2
	v_lshl_or_b32 v74, v8, 11, v2
	v_lshl_add_u64 v[2:3], s[4:5], 0, v[74:75]
	s_add_i32 m0, s1, 0x3000
	v_writelane_b32 v236, s11, 11
	global_load_lds_dwordx4 v[2:3], off
	v_lshl_add_u64 v[2:3], s[6:7], 0, v[74:75]
	s_add_i32 m0, s1, 0x7000
	s_add_u32 s1, s54, 0x2bf4800
	global_load_lds_dwordx4 v[2:3], off
	v_writelane_b32 v236, s1, 12
	s_addc_u32 s1, s55, 0
	v_writelane_b32 v236, s1, 13
	s_add_u32 s1, s52, 0x4c43400
	v_writelane_b32 v236, s1, 14
	s_addc_u32 s1, s53, 0
	v_writelane_b32 v236, s1, 15
	s_add_u32 s1, s52, 0x4c40000
	s_mov_b32 s5, 0
	v_writelane_b32 v236, s1, 16
	s_addc_u32 s1, s53, 0
	s_mov_b64 s[8:9], 0x80
	s_mov_b64 s[10:11], 0x100
	s_mov_b64 s[12:13], 0x180
	s_mov_b64 s[14:15], 0x200
	s_mov_b64 s[16:17], 0x280
	s_mov_b64 s[18:19], 0x300
	s_mov_b64 s[20:21], 0x380
	s_mov_b64 s[22:23], 0x400
	s_mov_b64 s[24:25], 0x480
	s_mov_b64 s[26:27], 0x500
	s_mov_b64 s[28:29], 0x580
	s_mov_b64 s[30:31], 0x600
	s_mov_b64 s[36:37], 0x680
	s_mov_b64 s[68:69], 0x700
	s_mov_b64 s[70:71], 0x780
	v_mov_b32_e32 v92, 0x358637bd
	v_writelane_b32 v236, s1, 17
	s_branch .Llt_97

; template <class Epi>
; DI void gemm_phase(const u16* __restrict__ A, const u16* __restrict__ B, int mtiles, int ntiles, char* lds, const Epi& epi) {
;     ...
;     for (;;) {
;         int tid = threadIdx.x; asm volatile("" : "+v"(tid));
;         const int lane = tid & 63, wave = __builtin_amdgcn_readfirstlane(tid >> 6); const int wn = wave >> 1, wm = wave & 1; const int r = lane & 31, h = lane >> 5;
;         f32x16 acc[2][2];
; #pragma unroll
;         for (int a = 0; a < 2; ++a)
; #pragma unroll
;             for (int b = 0; b < 2; ++b)
; #pragma unroll
;                 for (int e = 0; e < 16; ++e) acc[a][b][e] = 0.f;
;         unsigned soff[4];
; #pragma unroll
;         for (int i = 0; i < 4; ++i) { const int row = 8 * (i * 4 + wave) + (lane >> 3); const int ch = (lane & 7) ^ ((row >> 1) & 7); soff[i] = (unsigned)(row * 1024 + ch * 8); }
;         const u16* ga = A + (size_t)m0 * 1024; const u16* gb = B + (size_t)n0 * 1024;
;         __syncthreads();
;         for (int kt = 0; kt < 16; ++kt) {
;             if (kt + 1 < 16) GSTAGE((kt + 1) & 1, kt + 1, ga, gb);
;             const char* sa = lds + (kt & 1) * 32768; const char* sb = sa + 16384;
; #pragma unroll
;             for (int ks = 0; ks < 4; ++ks) {
;                 bf16x8 fw[2], fx[2];
; #pragma unroll
;                 for (int ct = 0; ct < 2; ++ct) fw[ct] = *(const bf16x8*)(sb + swz(wn * 64 + ct * 32 + r, 2 * ks + h));
; #pragma unroll
;                 for (int tt = 0; tt < 2; ++tt) fx[tt] = *(const bf16x8*)(sa + swz(wm * 64 + tt * 32 + r, 2 * ks + h));
; #pragma unroll
;                 for (int ct = 0; ct < 2; ++ct)
; #pragma unroll
;                     for (int tt = 0; tt < 2; ++tt) acc[ct][tt] = __builtin_amdgcn_mfma_f32_32x32x16_bf16(fw[ct], fx[tt], acc[ct][tt], 0, 0, 0);
;             }
;             __syncthreads();
;         }
.Llt_97:
	v_mov_b32_e32 v18, v0
	s_ashr_i32 s83, s82, 31
	v_readfirstlane_b32 s1, v18
	s_ashr_i32 s7, s1, 6
	s_ashr_i32 s4, s1, 7
	s_and_b32 s6, s7, 1
	v_bfe_u32 v2, v18, 3, 3
	s_lshl_b64 s[38:39], s[82:83], 11
	v_lshl_or_b32 v2, s7, 3, v2
	v_readlane_b32 s98, v237, 4
	v_readlane_b32 s99, v237, 5
	s_add_u32 s38, s98, s38
	v_lshrrev_b32_e32 v3, 1, v2
	s_addc_u32 s39, s99, s39
	s_ashr_i32 s1, s0, 31
	v_xor_b32_e32 v3, v3, v18
	s_lshl_b64 s[50:51], s[0:1], 11
	v_readlane_b32 s1, v236, 9
	v_lshlrev_b32_e32 v2, 10, v2
	v_lshlrev_b32_e32 v3, 3, v3
	s_add_u32 s50, s1, s50
	v_readlane_b32 s1, v236, 11
	v_and_or_b32 v74, v3, 56, v2
	s_addc_u32 s51, s1, s51
	s_lshl_b32 s1, s7, 10
	v_lshlrev_b64 v[66:67], 1, v[74:75]
	s_add_i32 s1, s1, 0
	v_add_u32_e32 v2, 0x8000, v74
	v_bfe_u32 v93, v18, 5, 1
	v_lshrrev_b32_e32 v8, 1, v18
	v_mov_b32_e32 v3, v75
	v_lshl_add_u64 v[76:77], s[38:39], 0, v[66:67]
	s_add_i32 s86, s1, 0x8000
	v_bitop3_b32 v10, v93, v8, 7 bitop3:0x78
	v_lshl_add_u64 v[8:9], v[76:77], 0, s[8:9]
	s_mov_b32 m0, s86
	v_lshl_add_u64 v[78:79], s[50:51], 0, v[66:67]
	s_add_i32 s87, s1, 0xc000
	v_lshlrev_b64 v[68:69], 1, v[2:3]
	v_add_u32_e32 v4, 0x10000, v74
	s_waitcnt vmcnt(0) lgkmcnt(0)
	s_barrier
	v_mov_b32_e32 v5, v75
	global_load_lds_dwordx4 v[8:9], off
	v_lshl_add_u64 v[8:9], v[78:79], 0, s[8:9]
	s_mov_b32 m0, s87
	v_lshl_add_u64 v[80:81], s[38:39], 0, v[68:69]
	s_add_i32 s88, s1, 0x9000
	global_load_lds_dwordx4 v[8:9], off
	v_lshl_add_u64 v[2:3], v[80:81], 0, s[8:9]
	s_mov_b32 m0, s88
	v_lshl_add_u64 v[82:83], s[50:51], 0, v[68:69]
	s_add_i32 s89, s1, 0xd000
	v_lshlrev_b64 v[70:71], 1, v[4:5]
	v_add_u32_e32 v6, 0x18000, v74
	v_mov_b32_e32 v7, v75
	global_load_lds_dwordx4 v[2:3], off
	v_lshl_add_u64 v[2:3], v[82:83], 0, s[8:9]
	s_mov_b32 m0, s89
	v_lshl_add_u64 v[84:85], s[38:39], 0, v[70:71]
	s_add_i32 s91, s1, 0xa000
	global_load_lds_dwordx4 v[2:3], off
	v_lshl_add_u64 v[2:3], v[84:85], 0, s[8:9]
	s_mov_b32 m0, s91
	v_lshl_add_u64 v[86:87], s[50:51], 0, v[70:71]
	s_add_i32 s92, s1, 0xe000
	v_lshlrev_b64 v[72:73], 1, v[6:7]
	global_load_lds_dwordx4 v[2:3], off
	v_lshl_add_u64 v[2:3], v[86:87], 0, s[8:9]
	s_mov_b32 m0, s92
	v_lshl_add_u64 v[88:89], s[38:39], 0, v[72:73]
	s_add_i32 s93, s1, 0xb000
	v_and_b32_e32 v94, 31, v18
	global_load_lds_dwordx4 v[2:3], off
	v_lshl_add_u64 v[2:3], v[88:89], 0, s[8:9]
	s_mov_b32 m0, s93
	v_lshl_add_u64 v[90:91], s[50:51], 0, v[72:73]
	s_add_i32 s94, s1, 0xf000
	s_lshl_b32 s7, s4, 13
	v_lshlrev_b32_e32 v116, 7, v94
	global_load_lds_dwordx4 v[2:3], off
	v_lshl_add_u64 v[2:3], v[90:91], 0, s[8:9]
	s_mov_b32 m0, s94
	v_lshl_add_u32 v6, v10, 4, 0
	global_load_lds_dwordx4 v[2:3], off
	v_add3_u32 v74, v6, s7, v116
	ds_read_b128 v[2:5], v74 offset:16384
	s_lshl_b32 s38, s6, 13
	v_add3_u32 v96, v6, s38, v116
	v_bfe_u32 v117, v18, 1, 3
	ds_read_b128 v[6:9], v96
	ds_read_b128 v[10:13], v96 offset:4096
	ds_read_b128 v[14:17], v74 offset:20480
	v_bitop3_b32 v18, v93, v117, 2 bitop3:0x36
	v_lshl_add_u32 v18, v18, 4, 0
	v_add3_u32 v95, v18, s7, v116
	ds_read_b128 v[50:53], v95 offset:16384
	s_waitcnt lgkmcnt(0)
	v_mfma_f32_32x32x16_bf16 v[34:49], v[2:5], v[6:9], 0
	v_add3_u32 v97, v18, s38, v116
	ds_read_b128 v[98:101], v97
	ds_read_b128 v[102:105], v97 offset:4096
	ds_read_b128 v[106:109], v95 offset:20480
	s_mov_b32 m0, s1
	s_add_i32 s39, s1, 0x5000
	s_add_i32 s50, s1, 0x2000
	s_add_i32 s51, s1, 0x6000
	s_add_i32 s83, s1, 0x3000
	v_mfma_f32_32x32x16_bf16 v[18:33], v[2:5], v[10:13], 0
	s_add_i32 s90, s1, 0x7000
	s_add_i32 s33, s33, s95
	s_waitcnt lgkmcnt(0)
	v_mfma_f32_32x32x16_bf16 v[34:49], v[50:53], v[98:101], v[34:49]
	v_mfma_f32_32x32x16_bf16 v[18:33], v[50:53], v[102:105], v[18:33]
	v_mfma_f32_32x32x16_bf16 v[50:65], v[14:17], v[6:9], 0
	v_mfma_f32_32x32x16_bf16 v[2:17], v[14:17], v[10:13], 0
	v_mfma_f32_32x32x16_bf16 v[50:65], v[106:109], v[98:101], v[50:65]
	v_bitop3_b32 v98, v93, v117, 4 bitop3:0x36
	v_lshl_add_u32 v99, v98, 4, 0
	v_add3_u32 v98, v99, s7, v116
	v_add3_u32 v99, v99, s38, v116
	v_mfma_f32_32x32x16_bf16 v[2:17], v[106:109], v[102:105], v[2:17]
	ds_read_b128 v[100:103], v98 offset:16384
	ds_read_b128 v[104:107], v99
	ds_read_b128 v[108:111], v99 offset:4096
	ds_read_b128 v[112:115], v98 offset:20480
	s_waitcnt lgkmcnt(0)
	v_mfma_f32_32x32x16_bf16 v[34:49], v[100:103], v[104:107], v[34:49]
	v_mfma_f32_32x32x16_bf16 v[18:33], v[100:103], v[108:111], v[18:33]
	v_bitop3_b32 v100, v93, v117, 6 bitop3:0x36
	v_lshl_add_u32 v101, v100, 4, 0
	v_add3_u32 v100, v101, s7, v116
	v_add3_u32 v101, v101, s38, v116
	s_add_i32 s7, s1, 0x4000
	s_add_i32 s38, s1, 0x1000
	s_cmpk_gt_i32 s33, 0x1103
	v_mfma_f32_32x32x16_bf16 v[50:65], v[112:115], v[104:107], v[50:65]
	v_mfma_f32_32x32x16_bf16 v[2:17], v[112:115], v[108:111], v[2:17]
	ds_read_b128 v[238:241], v100 offset:16384
	ds_read_b128 v[242:245], v101
	ds_read_b128 v[246:249], v101 offset:4096
	ds_read_b128 v[250:253], v100 offset:20480
	s_waitcnt vmcnt(0) lgkmcnt(0)
	s_barrier
; template <class Epi>
; DI void gemm_phase(const u16* __restrict__ A, const u16* __restrict__ B, int mtiles, int ntiles, char* lds, const Epi& epi) {
;     ...
;         for (int kt = 0; kt < 16; ++kt) {
;             if (kt + 1 < 16) GSTAGE((kt + 1) & 1, kt + 1, ga, gb);
;             const char* sa = lds + (kt & 1) * 32768; const char* sb = sa + 16384;
; #pragma unroll
;             for (int ks = 0; ks < 4; ++ks) {
;                 bf16x8 fw[2], fx[2];
; #pragma unroll
;                 for (int ct = 0; ct < 2; ++ct) fw[ct] = *(const bf16x8*)(sb + swz(wn * 64 + ct * 32 + r, 2 * ks + h));
; #pragma unroll
;                 for (int tt = 0; tt < 2; ++tt) fx[tt] = *(const bf16x8*)(sa + swz(wm * 64 + tt * 32 + r, 2 * ks + h));
; #pragma unroll
;                 for (int ct = 0; ct < 2; ++ct)
; #pragma unroll
;                     for (int tt = 0; tt < 2; ++tt) acc[ct][tt] = __builtin_amdgcn_mfma_f32_32x32x16_bf16(fw[ct], fx[tt], acc[ct][tt], 0, 0, 0);
;             }
;             __syncthreads();
	ds_read_b128 v[102:105], v74 offset:49152
	ds_read_b128 v[106:109], v96 offset:32768
	ds_read_b128 v[110:113], v96 offset:36864
	ds_read_b128 v[114:117], v74 offset:53248
	v_mfma_f32_32x32x16_bf16 v[34:49], v[238:241], v[242:245], v[34:49]
	v_mfma_f32_32x32x16_bf16 v[18:33], v[238:241], v[246:249], v[18:33]
	v_lshl_add_u64 v[254:255], v[76:77], 0, s[10:11]
	global_load_lds_dwordx4 v[254:255], off
	v_lshl_add_u64 v[254:255], v[78:79], 0, s[10:11]
	s_mov_b32 m0, s7
	s_nop 0
	global_load_lds_dwordx4 v[254:255], off
	v_mfma_f32_32x32x16_bf16 v[50:65], v[250:253], v[242:245], v[50:65]
	v_lshl_add_u64 v[254:255], v[80:81], 0, s[10:11]
	s_mov_b32 m0, s38
	s_nop 0
	global_load_lds_dwordx4 v[254:255], off
	v_mfma_f32_32x32x16_bf16 v[2:17], v[250:253], v[246:249], v[2:17]
	s_waitcnt lgkmcnt(0)
	ds_read_b128 v[238:241], v95 offset:49152
	ds_read_b128 v[242:245], v97 offset:32768
	ds_read_b128 v[246:249], v97 offset:36864
	ds_read_b128 v[250:253], v95 offset:53248
	v_mfma_f32_32x32x16_bf16 v[34:49], v[102:105], v[106:109], v[34:49]
	v_lshl_add_u64 v[254:255], v[82:83], 0, s[10:11]
	s_mov_b32 m0, s39
	s_nop 0
	global_load_lds_dwordx4 v[254:255], off
	v_mfma_f32_32x32x16_bf16 v[18:33], v[102:105], v[110:113], v[18:33]
	v_lshl_add_u64 v[254:255], v[84:85], 0, s[10:11]
	s_mov_b32 m0, s50
	s_nop 0
	global_load_lds_dwordx4 v[254:255], off
	v_mfma_f32_32x32x16_bf16 v[50:65], v[114:117], v[106:109], v[50:65]
	v_mfma_f32_32x32x16_bf16 v[2:17], v[114:117], v[110:113], v[2:17]
	s_waitcnt lgkmcnt(0)
	ds_read_b128 v[102:105], v98 offset:49152
	ds_read_b128 v[106:109], v99 offset:32768
	ds_read_b128 v[110:113], v99 offset:36864
	ds_read_b128 v[114:117], v98 offset:53248
	v_mfma_f32_32x32x16_bf16 v[34:49], v[238:241], v[242:245], v[34:49]
	v_lshl_add_u64 v[254:255], v[86:87], 0, s[10:11]
	s_mov_b32 m0, s51
	s_nop 0
	global_load_lds_dwordx4 v[254:255], off
	v_mfma_f32_32x32x16_bf16 v[18:33], v[238:241], v[246:249], v[18:33]
	v_lshl_add_u64 v[254:255], v[88:89], 0, s[10:11]
	s_mov_b32 m0, s83
	s_nop 0
	global_load_lds_dwordx4 v[254:255], off
	v_mfma_f32_32x32x16_bf16 v[50:65], v[250:253], v[242:245], v[50:65]
	v_mfma_f32_32x32x16_bf16 v[2:17], v[250:253], v[246:249], v[2:17]
	s_waitcnt lgkmcnt(0)
	ds_read_b128 v[238:241], v100 offset:49152
	ds_read_b128 v[242:245], v101 offset:32768
	ds_read_b128 v[246:249], v101 offset:36864
	ds_read_b128 v[250:253], v100 offset:53248
	v_mfma_f32_32x32x16_bf16 v[34:49], v[102:105], v[106:109], v[34:49]
	v_lshl_add_u64 v[254:255], v[90:91], 0, s[10:11]
	s_mov_b32 m0, s90
	s_nop 0
	global_load_lds_dwordx4 v[254:255], off
	v_mfma_f32_32x32x16_bf16 v[18:33], v[102:105], v[110:113], v[18:33]
	v_mfma_f32_32x32x16_bf16 v[50:65], v[114:117], v[106:109], v[50:65]
	v_mfma_f32_32x32x16_bf16 v[2:17], v[114:117], v[110:113], v[2:17]
	s_mov_b32 m0, s86
	s_waitcnt vmcnt(0) lgkmcnt(0)
	s_barrier
	ds_read_b128 v[102:105], v74 offset:16384
	ds_read_b128 v[106:109], v96
	ds_read_b128 v[110:113], v96 offset:4096
	ds_read_b128 v[114:117], v74 offset:20480
	v_mfma_f32_32x32x16_bf16 v[34:49], v[238:241], v[242:245], v[34:49]
	v_mfma_f32_32x32x16_bf16 v[18:33], v[238:241], v[246:249], v[18:33]
	v_lshl_add_u64 v[254:255], v[76:77], 0, s[12:13]
	global_load_lds_dwordx4 v[254:255], off
	v_lshl_add_u64 v[254:255], v[78:79], 0, s[12:13]
	s_mov_b32 m0, s87
	s_nop 0
	global_load_lds_dwordx4 v[254:255], off
	v_mfma_f32_32x32x16_bf16 v[50:65], v[250:253], v[242:245], v[50:65]
	v_lshl_add_u64 v[254:255], v[80:81], 0, s[12:13]
	s_mov_b32 m0, s88
	s_nop 0
	global_load_lds_dwordx4 v[254:255], off
	v_mfma_f32_32x32x16_bf16 v[2:17], v[250:253], v[246:249], v[2:17]
	s_waitcnt lgkmcnt(0)
	ds_read_b128 v[238:241], v95 offset:16384
	ds_read_b128 v[242:245], v97
	ds_read_b128 v[246:249], v97 offset:4096
	ds_read_b128 v[250:253], v95 offset:20480
	v_mfma_f32_32x32x16_bf16 v[34:49], v[102:105], v[106:109], v[34:49]
	v_lshl_add_u64 v[254:255], v[82:83], 0, s[12:13]
	s_mov_b32 m0, s89
	s_nop 0
	global_load_lds_dwordx4 v[254:255], off
	v_mfma_f32_32x32x16_bf16 v[18:33], v[102:105], v[110:113], v[18:33]
	v_lshl_add_u64 v[254:255], v[84:85], 0, s[12:13]
	s_mov_b32 m0, s91
	s_nop 0
	global_load_lds_dwordx4 v[254:255], off
	v_mfma_f32_32x32x16_bf16 v[50:65], v[114:117], v[106:109], v[50:65]
	v_mfma_f32_32x32x16_bf16 v[2:17], v[114:117], v[110:113], v[2:17]
	s_waitcnt lgkmcnt(0)
	ds_read_b128 v[102:105], v98 offset:16384
	ds_read_b128 v[106:109], v99
	ds_read_b128 v[110:113], v99 offset:4096
	ds_read_b128 v[114:117], v98 offset:20480
	v_mfma_f32_32x32x16_bf16 v[34:49], v[238:241], v[242:245], v[34:49]
	v_lshl_add_u64 v[254:255], v[86:87], 0, s[12:13]
	s_mov_b32 m0, s92
	s_nop 0
	global_load_lds_dwordx4 v[254:255], off
	v_mfma_f32_32x32x16_bf16 v[18:33], v[238:241], v[246:249], v[18:33]
	v_lshl_add_u64 v[254:255], v[88:89], 0, s[12:13]
	s_mov_b32 m0, s93
	s_nop 0
	global_load_lds_dwordx4 v[254:255], off
	v_mfma_f32_32x32x16_bf16 v[50:65], v[250:253], v[242:245], v[50:65]
	v_mfma_f32_32x32x16_bf16 v[2:17], v[250:253], v[246:249], v[2:17]
	s_waitcnt lgkmcnt(0)
	ds_read_b128 v[238:241], v100 offset:16384
	ds_read_b128 v[242:245], v101
	ds_read_b128 v[246:249], v101 offset:4096
	ds_read_b128 v[250:253], v100 offset:20480
	v_mfma_f32_32x32x16_bf16 v[34:49], v[102:105], v[106:109], v[34:49]
	v_lshl_add_u64 v[254:255], v[90:91], 0, s[12:13]
	s_mov_b32 m0, s94
	s_nop 0
	global_load_lds_dwordx4 v[254:255], off
	v_mfma_f32_32x32x16_bf16 v[18:33], v[102:105], v[110:113], v[18:33]
	v_mfma_f32_32x32x16_bf16 v[50:65], v[114:117], v[106:109], v[50:65]
	v_mfma_f32_32x32x16_bf16 v[2:17], v[114:117], v[110:113], v[2:17]
	s_mov_b32 m0, s1
	s_waitcnt vmcnt(0) lgkmcnt(0)
	s_barrier
; template <class Epi>
; DI void gemm_phase(const u16* __restrict__ A, const u16* __restrict__ B, int mtiles, int ntiles, char* lds, const Epi& epi) {
;     ...
;         for (int kt = 0; kt < 16; ++kt) {
;             if (kt + 1 < 16) GSTAGE((kt + 1) & 1, kt + 1, ga, gb);
;             const char* sa = lds + (kt & 1) * 32768; const char* sb = sa + 16384;
; #pragma unroll
;             for (int ks = 0; ks < 4; ++ks) {
;                 bf16x8 fw[2], fx[2];
; #pragma unroll
;                 for (int ct = 0; ct < 2; ++ct) fw[ct] = *(const bf16x8*)(sb + swz(wn * 64 + ct * 32 + r, 2 * ks + h));
; #pragma unroll
;                 for (int tt = 0; tt < 2; ++tt) fx[tt] = *(const bf16x8*)(sa + swz(wm * 64 + tt * 32 + r, 2 * ks + h));
; #pragma unroll
;                 for (int ct = 0; ct < 2; ++ct)
; #pragma unroll
;                     for (int tt = 0; tt < 2; ++tt) acc[ct][tt] = __builtin_amdgcn_mfma_f32_32x32x16_bf16(fw[ct], fx[tt], acc[ct][tt], 0, 0, 0);
;             }
;             __syncthreads();
	ds_read_b128 v[102:105], v74 offset:49152
	ds_read_b128 v[106:109], v96 offset:32768
	ds_read_b128 v[110:113], v96 offset:36864
	ds_read_b128 v[114:117], v74 offset:53248
	v_mfma_f32_32x32x16_bf16 v[34:49], v[238:241], v[242:245], v[34:49]
	v_mfma_f32_32x32x16_bf16 v[18:33], v[238:241], v[246:249], v[18:33]
	v_lshl_add_u64 v[254:255], v[76:77], 0, s[14:15]
	global_load_lds_dwordx4 v[254:255], off
	v_lshl_add_u64 v[254:255], v[78:79], 0, s[14:15]
	s_mov_b32 m0, s7
	s_nop 0
	global_load_lds_dwordx4 v[254:255], off
	v_mfma_f32_32x32x16_bf16 v[50:65], v[250:253], v[242:245], v[50:65]
	v_lshl_add_u64 v[254:255], v[80:81], 0, s[14:15]
	s_mov_b32 m0, s38
	s_nop 0
	global_load_lds_dwordx4 v[254:255], off
	v_mfma_f32_32x32x16_bf16 v[2:17], v[250:253], v[246:249], v[2:17]
	s_waitcnt lgkmcnt(0)
	ds_read_b128 v[238:241], v95 offset:49152
	ds_read_b128 v[242:245], v97 offset:32768
	ds_read_b128 v[246:249], v97 offset:36864
	ds_read_b128 v[250:253], v95 offset:53248
	v_mfma_f32_32x32x16_bf16 v[34:49], v[102:105], v[106:109], v[34:49]
	v_lshl_add_u64 v[254:255], v[82:83], 0, s[14:15]
	s_mov_b32 m0, s39
	s_nop 0
	global_load_lds_dwordx4 v[254:255], off
	v_mfma_f32_32x32x16_bf16 v[18:33], v[102:105], v[110:113], v[18:33]
	v_lshl_add_u64 v[254:255], v[84:85], 0, s[14:15]
	s_mov_b32 m0, s50
	s_nop 0
	global_load_lds_dwordx4 v[254:255], off
	v_mfma_f32_32x32x16_bf16 v[50:65], v[114:117], v[106:109], v[50:65]
	v_mfma_f32_32x32x16_bf16 v[2:17], v[114:117], v[110:113], v[2:17]
	s_waitcnt lgkmcnt(0)
	ds_read_b128 v[102:105], v98 offset:49152
	ds_read_b128 v[106:109], v99 offset:32768
	ds_read_b128 v[110:113], v99 offset:36864
	ds_read_b128 v[114:117], v98 offset:53248
	v_mfma_f32_32x32x16_bf16 v[34:49], v[238:241], v[242:245], v[34:49]
	v_lshl_add_u64 v[254:255], v[86:87], 0, s[14:15]
	s_mov_b32 m0, s51
	s_nop 0
	global_load_lds_dwordx4 v[254:255], off
	v_mfma_f32_32x32x16_bf16 v[18:33], v[238:241], v[246:249], v[18:33]
	v_lshl_add_u64 v[254:255], v[88:89], 0, s[14:15]
	s_mov_b32 m0, s83
	s_nop 0
	global_load_lds_dwordx4 v[254:255], off
	v_mfma_f32_32x32x16_bf16 v[50:65], v[250:253], v[242:245], v[50:65]
	v_mfma_f32_32x32x16_bf16 v[2:17], v[250:253], v[246:249], v[2:17]
	s_waitcnt lgkmcnt(0)
	ds_read_b128 v[238:241], v100 offset:49152
	ds_read_b128 v[242:245], v101 offset:32768
	ds_read_b128 v[246:249], v101 offset:36864
	ds_read_b128 v[250:253], v100 offset:53248
	v_mfma_f32_32x32x16_bf16 v[34:49], v[102:105], v[106:109], v[34:49]
	v_lshl_add_u64 v[254:255], v[90:91], 0, s[14:15]
	s_mov_b32 m0, s90
	s_nop 0
	global_load_lds_dwordx4 v[254:255], off
	v_mfma_f32_32x32x16_bf16 v[18:33], v[102:105], v[110:113], v[18:33]
	v_mfma_f32_32x32x16_bf16 v[50:65], v[114:117], v[106:109], v[50:65]
	v_mfma_f32_32x32x16_bf16 v[2:17], v[114:117], v[110:113], v[2:17]
	s_mov_b32 m0, s86
	s_waitcnt vmcnt(0) lgkmcnt(0)
	s_barrier
	ds_read_b128 v[102:105], v74 offset:16384
	ds_read_b128 v[106:109], v96
	ds_read_b128 v[110:113], v96 offset:4096
	ds_read_b128 v[114:117], v74 offset:20480
	v_mfma_f32_32x32x16_bf16 v[34:49], v[238:241], v[242:245], v[34:49]
	v_mfma_f32_32x32x16_bf16 v[18:33], v[238:241], v[246:249], v[18:33]
	v_lshl_add_u64 v[254:255], v[76:77], 0, s[16:17]
	global_load_lds_dwordx4 v[254:255], off
	v_lshl_add_u64 v[254:255], v[78:79], 0, s[16:17]
	s_mov_b32 m0, s87
	s_nop 0
	global_load_lds_dwordx4 v[254:255], off
	v_mfma_f32_32x32x16_bf16 v[50:65], v[250:253], v[242:245], v[50:65]
	v_lshl_add_u64 v[254:255], v[80:81], 0, s[16:17]
	s_mov_b32 m0, s88
	s_nop 0
	global_load_lds_dwordx4 v[254:255], off
	v_mfma_f32_32x32x16_bf16 v[2:17], v[250:253], v[246:249], v[2:17]
	s_waitcnt lgkmcnt(0)
	ds_read_b128 v[238:241], v95 offset:16384
	ds_read_b128 v[242:245], v97
	ds_read_b128 v[246:249], v97 offset:4096
	ds_read_b128 v[250:253], v95 offset:20480
	v_mfma_f32_32x32x16_bf16 v[34:49], v[102:105], v[106:109], v[34:49]
	v_lshl_add_u64 v[254:255], v[82:83], 0, s[16:17]
	s_mov_b32 m0, s89
	s_nop 0
	global_load_lds_dwordx4 v[254:255], off
	v_mfma_f32_32x32x16_bf16 v[18:33], v[102:105], v[110:113], v[18:33]
	v_lshl_add_u64 v[254:255], v[84:85], 0, s[16:17]
	s_mov_b32 m0, s91
	s_nop 0
	global_load_lds_dwordx4 v[254:255], off
	v_mfma_f32_32x32x16_bf16 v[50:65], v[114:117], v[106:109], v[50:65]
	v_mfma_f32_32x32x16_bf16 v[2:17], v[114:117], v[110:113], v[2:17]
	s_waitcnt lgkmcnt(0)
	ds_read_b128 v[102:105], v98 offset:16384
	ds_read_b128 v[106:109], v99
	ds_read_b128 v[110:113], v99 offset:4096
	ds_read_b128 v[114:117], v98 offset:20480
	v_mfma_f32_32x32x16_bf16 v[34:49], v[238:241], v[242:245], v[34:49]
	v_lshl_add_u64 v[254:255], v[86:87], 0, s[16:17]
	s_mov_b32 m0, s92
	s_nop 0
	global_load_lds_dwordx4 v[254:255], off
	v_mfma_f32_32x32x16_bf16 v[18:33], v[238:241], v[246:249], v[18:33]
	v_lshl_add_u64 v[254:255], v[88:89], 0, s[16:17]
	s_mov_b32 m0, s93
	s_nop 0
	global_load_lds_dwordx4 v[254:255], off
	v_mfma_f32_32x32x16_bf16 v[50:65], v[250:253], v[242:245], v[50:65]
	v_mfma_f32_32x32x16_bf16 v[2:17], v[250:253], v[246:249], v[2:17]
	s_waitcnt lgkmcnt(0)
	ds_read_b128 v[238:241], v100 offset:16384
	ds_read_b128 v[242:245], v101
	ds_read_b128 v[246:249], v101 offset:4096
	ds_read_b128 v[250:253], v100 offset:20480
	v_mfma_f32_32x32x16_bf16 v[34:49], v[102:105], v[106:109], v[34:49]
	v_lshl_add_u64 v[254:255], v[90:91], 0, s[16:17]
	s_mov_b32 m0, s94
	s_nop 0
	global_load_lds_dwordx4 v[254:255], off
	v_mfma_f32_32x32x16_bf16 v[18:33], v[102:105], v[110:113], v[18:33]
	v_mfma_f32_32x32x16_bf16 v[50:65], v[114:117], v[106:109], v[50:65]
	v_mfma_f32_32x32x16_bf16 v[2:17], v[114:117], v[110:113], v[2:17]
	s_mov_b32 m0, s1
	s_waitcnt vmcnt(0) lgkmcnt(0)
	s_barrier
; template <class Epi>
; DI void gemm_phase(const u16* __restrict__ A, const u16* __restrict__ B, int mtiles, int ntiles, char* lds, const Epi& epi) {
;     ...
;         for (int kt = 0; kt < 16; ++kt) {
;             if (kt + 1 < 16) GSTAGE((kt + 1) & 1, kt + 1, ga, gb);
;             const char* sa = lds + (kt & 1) * 32768; const char* sb = sa + 16384;
; #pragma unroll
;             for (int ks = 0; ks < 4; ++ks) {
;                 bf16x8 fw[2], fx[2];
; #pragma unroll
;                 for (int ct = 0; ct < 2; ++ct) fw[ct] = *(const bf16x8*)(sb + swz(wn * 64 + ct * 32 + r, 2 * ks + h));
; #pragma unroll
;                 for (int tt = 0; tt < 2; ++tt) fx[tt] = *(const bf16x8*)(sa + swz(wm * 64 + tt * 32 + r, 2 * ks + h));
; #pragma unroll
;                 for (int ct = 0; ct < 2; ++ct)
; #pragma unroll
;                     for (int tt = 0; tt < 2; ++tt) acc[ct][tt] = __builtin_amdgcn_mfma_f32_32x32x16_bf16(fw[ct], fx[tt], acc[ct][tt], 0, 0, 0);
;             }
;             __syncthreads();
	ds_read_b128 v[102:105], v74 offset:49152
	ds_read_b128 v[106:109], v96 offset:32768
	ds_read_b128 v[110:113], v96 offset:36864
	ds_read_b128 v[114:117], v74 offset:53248
	v_mfma_f32_32x32x16_bf16 v[34:49], v[238:241], v[242:245], v[34:49]
	v_mfma_f32_32x32x16_bf16 v[18:33], v[238:241], v[246:249], v[18:33]
	v_lshl_add_u64 v[254:255], v[76:77], 0, s[18:19]
	global_load_lds_dwordx4 v[254:255], off
	v_lshl_add_u64 v[254:255], v[78:79], 0, s[18:19]
	s_mov_b32 m0, s7
	s_nop 0
	global_load_lds_dwordx4 v[254:255], off
	v_mfma_f32_32x32x16_bf16 v[50:65], v[250:253], v[242:245], v[50:65]
	v_lshl_add_u64 v[254:255], v[80:81], 0, s[18:19]
	s_mov_b32 m0, s38
	s_nop 0
	global_load_lds_dwordx4 v[254:255], off
	v_mfma_f32_32x32x16_bf16 v[2:17], v[250:253], v[246:249], v[2:17]
	s_waitcnt lgkmcnt(0)
	ds_read_b128 v[238:241], v95 offset:49152
	ds_read_b128 v[242:245], v97 offset:32768
	ds_read_b128 v[246:249], v97 offset:36864
	ds_read_b128 v[250:253], v95 offset:53248
	v_mfma_f32_32x32x16_bf16 v[34:49], v[102:105], v[106:109], v[34:49]
	v_lshl_add_u64 v[254:255], v[82:83], 0, s[18:19]
	s_mov_b32 m0, s39
	s_nop 0
	global_load_lds_dwordx4 v[254:255], off
	v_mfma_f32_32x32x16_bf16 v[18:33], v[102:105], v[110:113], v[18:33]
	v_lshl_add_u64 v[254:255], v[84:85], 0, s[18:19]
	s_mov_b32 m0, s50
	s_nop 0
	global_load_lds_dwordx4 v[254:255], off
	v_mfma_f32_32x32x16_bf16 v[50:65], v[114:117], v[106:109], v[50:65]
	v_mfma_f32_32x32x16_bf16 v[2:17], v[114:117], v[110:113], v[2:17]
	s_waitcnt lgkmcnt(0)
	ds_read_b128 v[102:105], v98 offset:49152
	ds_read_b128 v[106:109], v99 offset:32768
	ds_read_b128 v[110:113], v99 offset:36864
	ds_read_b128 v[114:117], v98 offset:53248
	v_mfma_f32_32x32x16_bf16 v[34:49], v[238:241], v[242:245], v[34:49]
	v_lshl_add_u64 v[254:255], v[86:87], 0, s[18:19]
	s_mov_b32 m0, s51
	s_nop 0
	global_load_lds_dwordx4 v[254:255], off
	v_mfma_f32_32x32x16_bf16 v[18:33], v[238:241], v[246:249], v[18:33]
	v_lshl_add_u64 v[254:255], v[88:89], 0, s[18:19]
	s_mov_b32 m0, s83
	s_nop 0
	global_load_lds_dwordx4 v[254:255], off
	v_mfma_f32_32x32x16_bf16 v[50:65], v[250:253], v[242:245], v[50:65]
	v_mfma_f32_32x32x16_bf16 v[2:17], v[250:253], v[246:249], v[2:17]
	s_waitcnt lgkmcnt(0)
	ds_read_b128 v[238:241], v100 offset:49152
	ds_read_b128 v[242:245], v101 offset:32768
	ds_read_b128 v[246:249], v101 offset:36864
	ds_read_b128 v[250:253], v100 offset:53248
	v_mfma_f32_32x32x16_bf16 v[34:49], v[102:105], v[106:109], v[34:49]
	v_lshl_add_u64 v[254:255], v[90:91], 0, s[18:19]
	s_mov_b32 m0, s90
	s_nop 0
	global_load_lds_dwordx4 v[254:255], off
	v_mfma_f32_32x32x16_bf16 v[18:33], v[102:105], v[110:113], v[18:33]
	v_mfma_f32_32x32x16_bf16 v[50:65], v[114:117], v[106:109], v[50:65]
	v_mfma_f32_32x32x16_bf16 v[2:17], v[114:117], v[110:113], v[2:17]
	s_mov_b32 m0, s86
	s_waitcnt vmcnt(0) lgkmcnt(0)
	s_barrier
	ds_read_b128 v[102:105], v74 offset:16384
	ds_read_b128 v[106:109], v96
	ds_read_b128 v[110:113], v96 offset:4096
	ds_read_b128 v[114:117], v74 offset:20480
	v_mfma_f32_32x32x16_bf16 v[34:49], v[238:241], v[242:245], v[34:49]
	v_mfma_f32_32x32x16_bf16 v[18:33], v[238:241], v[246:249], v[18:33]
	v_lshl_add_u64 v[254:255], v[76:77], 0, s[20:21]
	global_load_lds_dwordx4 v[254:255], off
	v_lshl_add_u64 v[254:255], v[78:79], 0, s[20:21]
	s_mov_b32 m0, s87
	s_nop 0
	global_load_lds_dwordx4 v[254:255], off
	v_mfma_f32_32x32x16_bf16 v[50:65], v[250:253], v[242:245], v[50:65]
	v_lshl_add_u64 v[254:255], v[80:81], 0, s[20:21]
	s_mov_b32 m0, s88
	s_nop 0
	global_load_lds_dwordx4 v[254:255], off
	v_mfma_f32_32x32x16_bf16 v[2:17], v[250:253], v[246:249], v[2:17]
	s_waitcnt lgkmcnt(0)
	ds_read_b128 v[238:241], v95 offset:16384
	ds_read_b128 v[242:245], v97
	ds_read_b128 v[246:249], v97 offset:4096
	ds_read_b128 v[250:253], v95 offset:20480
	v_mfma_f32_32x32x16_bf16 v[34:49], v[102:105], v[106:109], v[34:49]
	v_lshl_add_u64 v[254:255], v[82:83], 0, s[20:21]
	s_mov_b32 m0, s89
	s_nop 0
	global_load_lds_dwordx4 v[254:255], off
	v_mfma_f32_32x32x16_bf16 v[18:33], v[102:105], v[110:113], v[18:33]
	v_lshl_add_u64 v[254:255], v[84:85], 0, s[20:21]
	s_mov_b32 m0, s91
	s_nop 0
	global_load_lds_dwordx4 v[254:255], off
	v_mfma_f32_32x32x16_bf16 v[50:65], v[114:117], v[106:109], v[50:65]
	v_mfma_f32_32x32x16_bf16 v[2:17], v[114:117], v[110:113], v[2:17]
	s_waitcnt lgkmcnt(0)
	ds_read_b128 v[102:105], v98 offset:16384
	ds_read_b128 v[106:109], v99
	ds_read_b128 v[110:113], v99 offset:4096
	ds_read_b128 v[114:117], v98 offset:20480
	v_mfma_f32_32x32x16_bf16 v[34:49], v[238:241], v[242:245], v[34:49]
	v_lshl_add_u64 v[254:255], v[86:87], 0, s[20:21]
	s_mov_b32 m0, s92
	s_nop 0
	global_load_lds_dwordx4 v[254:255], off
	v_mfma_f32_32x32x16_bf16 v[18:33], v[238:241], v[246:249], v[18:33]
	v_lshl_add_u64 v[254:255], v[88:89], 0, s[20:21]
	s_mov_b32 m0, s93
	s_nop 0
	global_load_lds_dwordx4 v[254:255], off
	v_mfma_f32_32x32x16_bf16 v[50:65], v[250:253], v[242:245], v[50:65]
	v_mfma_f32_32x32x16_bf16 v[2:17], v[250:253], v[246:249], v[2:17]
	s_waitcnt lgkmcnt(0)
	ds_read_b128 v[238:241], v100 offset:16384
	ds_read_b128 v[242:245], v101
	ds_read_b128 v[246:249], v101 offset:4096
	ds_read_b128 v[250:253], v100 offset:20480
	v_mfma_f32_32x32x16_bf16 v[34:49], v[102:105], v[106:109], v[34:49]
	v_lshl_add_u64 v[254:255], v[90:91], 0, s[20:21]
	s_mov_b32 m0, s94
	s_nop 0
	global_load_lds_dwordx4 v[254:255], off
	v_mfma_f32_32x32x16_bf16 v[18:33], v[102:105], v[110:113], v[18:33]
	v_mfma_f32_32x32x16_bf16 v[50:65], v[114:117], v[106:109], v[50:65]
	v_mfma_f32_32x32x16_bf16 v[2:17], v[114:117], v[110:113], v[2:17]
	s_mov_b32 m0, s1
	s_waitcnt vmcnt(0) lgkmcnt(0)
	s_barrier
; template <class Epi>
; DI void gemm_phase(const u16* __restrict__ A, const u16* __restrict__ B, int mtiles, int ntiles, char* lds, const Epi& epi) {
;     ...
;         for (int kt = 0; kt < 16; ++kt) {
;             if (kt + 1 < 16) GSTAGE((kt + 1) & 1, kt + 1, ga, gb);
;             const char* sa = lds + (kt & 1) * 32768; const char* sb = sa + 16384;
; #pragma unroll
;             for (int ks = 0; ks < 4; ++ks) {
;                 bf16x8 fw[2], fx[2];
; #pragma unroll
;                 for (int ct = 0; ct < 2; ++ct) fw[ct] = *(const bf16x8*)(sb + swz(wn * 64 + ct * 32 + r, 2 * ks + h));
; #pragma unroll
;                 for (int tt = 0; tt < 2; ++tt) fx[tt] = *(const bf16x8*)(sa + swz(wm * 64 + tt * 32 + r, 2 * ks + h));
; #pragma unroll
;                 for (int ct = 0; ct < 2; ++ct)
; #pragma unroll
;                     for (int tt = 0; tt < 2; ++tt) acc[ct][tt] = __builtin_amdgcn_mfma_f32_32x32x16_bf16(fw[ct], fx[tt], acc[ct][tt], 0, 0, 0);
;             }
;             __syncthreads();
	ds_read_b128 v[102:105], v74 offset:49152
	ds_read_b128 v[106:109], v96 offset:32768
	ds_read_b128 v[110:113], v96 offset:36864
	ds_read_b128 v[114:117], v74 offset:53248
	v_mfma_f32_32x32x16_bf16 v[34:49], v[238:241], v[242:245], v[34:49]
	v_mfma_f32_32x32x16_bf16 v[18:33], v[238:241], v[246:249], v[18:33]
	v_lshl_add_u64 v[254:255], v[76:77], 0, s[22:23]
	global_load_lds_dwordx4 v[254:255], off
	v_lshl_add_u64 v[254:255], v[78:79], 0, s[22:23]
	s_mov_b32 m0, s7
	s_nop 0
	global_load_lds_dwordx4 v[254:255], off
	v_mfma_f32_32x32x16_bf16 v[50:65], v[250:253], v[242:245], v[50:65]
	v_lshl_add_u64 v[254:255], v[80:81], 0, s[22:23]
	s_mov_b32 m0, s38
	s_nop 0
	global_load_lds_dwordx4 v[254:255], off
	v_mfma_f32_32x32x16_bf16 v[2:17], v[250:253], v[246:249], v[2:17]
	s_waitcnt lgkmcnt(0)
	ds_read_b128 v[238:241], v95 offset:49152
	ds_read_b128 v[242:245], v97 offset:32768
	ds_read_b128 v[246:249], v97 offset:36864
	ds_read_b128 v[250:253], v95 offset:53248
	v_mfma_f32_32x32x16_bf16 v[34:49], v[102:105], v[106:109], v[34:49]
	v_lshl_add_u64 v[254:255], v[82:83], 0, s[22:23]
	s_mov_b32 m0, s39
	s_nop 0
	global_load_lds_dwordx4 v[254:255], off
	v_mfma_f32_32x32x16_bf16 v[18:33], v[102:105], v[110:113], v[18:33]
	v_lshl_add_u64 v[254:255], v[84:85], 0, s[22:23]
	s_mov_b32 m0, s50
	s_nop 0
	global_load_lds_dwordx4 v[254:255], off
	v_mfma_f32_32x32x16_bf16 v[50:65], v[114:117], v[106:109], v[50:65]
	v_mfma_f32_32x32x16_bf16 v[2:17], v[114:117], v[110:113], v[2:17]
	s_waitcnt lgkmcnt(0)
	ds_read_b128 v[102:105], v98 offset:49152
	ds_read_b128 v[106:109], v99 offset:32768
	ds_read_b128 v[110:113], v99 offset:36864
	ds_read_b128 v[114:117], v98 offset:53248
	v_mfma_f32_32x32x16_bf16 v[34:49], v[238:241], v[242:245], v[34:49]
	v_lshl_add_u64 v[254:255], v[86:87], 0, s[22:23]
	s_mov_b32 m0, s51
	s_nop 0
	global_load_lds_dwordx4 v[254:255], off
	v_mfma_f32_32x32x16_bf16 v[18:33], v[238:241], v[246:249], v[18:33]
	v_lshl_add_u64 v[254:255], v[88:89], 0, s[22:23]
	s_mov_b32 m0, s83
	s_nop 0
	global_load_lds_dwordx4 v[254:255], off
	v_mfma_f32_32x32x16_bf16 v[50:65], v[250:253], v[242:245], v[50:65]
	v_mfma_f32_32x32x16_bf16 v[2:17], v[250:253], v[246:249], v[2:17]
	s_waitcnt lgkmcnt(0)
	ds_read_b128 v[238:241], v100 offset:49152
	ds_read_b128 v[242:245], v101 offset:32768
	ds_read_b128 v[246:249], v101 offset:36864
	ds_read_b128 v[250:253], v100 offset:53248
	v_mfma_f32_32x32x16_bf16 v[34:49], v[102:105], v[106:109], v[34:49]
	v_lshl_add_u64 v[254:255], v[90:91], 0, s[22:23]
	s_mov_b32 m0, s90
	s_nop 0
	global_load_lds_dwordx4 v[254:255], off
	v_mfma_f32_32x32x16_bf16 v[18:33], v[102:105], v[110:113], v[18:33]
	v_mfma_f32_32x32x16_bf16 v[50:65], v[114:117], v[106:109], v[50:65]
	v_mfma_f32_32x32x16_bf16 v[2:17], v[114:117], v[110:113], v[2:17]
	s_mov_b32 m0, s86
	s_waitcnt vmcnt(0) lgkmcnt(0)
	s_barrier
	ds_read_b128 v[102:105], v74 offset:16384
	ds_read_b128 v[106:109], v96
	ds_read_b128 v[110:113], v96 offset:4096
	ds_read_b128 v[114:117], v74 offset:20480
	v_mfma_f32_32x32x16_bf16 v[34:49], v[238:241], v[242:245], v[34:49]
	v_mfma_f32_32x32x16_bf16 v[18:33], v[238:241], v[246:249], v[18:33]
	v_lshl_add_u64 v[254:255], v[76:77], 0, s[24:25]
	global_load_lds_dwordx4 v[254:255], off
	v_lshl_add_u64 v[254:255], v[78:79], 0, s[24:25]
	s_mov_b32 m0, s87
	s_nop 0
	global_load_lds_dwordx4 v[254:255], off
	v_mfma_f32_32x32x16_bf16 v[50:65], v[250:253], v[242:245], v[50:65]
	v_lshl_add_u64 v[254:255], v[80:81], 0, s[24:25]
	s_mov_b32 m0, s88
	s_nop 0
	global_load_lds_dwordx4 v[254:255], off
	v_mfma_f32_32x32x16_bf16 v[2:17], v[250:253], v[246:249], v[2:17]
	s_waitcnt lgkmcnt(0)
	ds_read_b128 v[238:241], v95 offset:16384
	ds_read_b128 v[242:245], v97
	ds_read_b128 v[246:249], v97 offset:4096
	ds_read_b128 v[250:253], v95 offset:20480
	v_mfma_f32_32x32x16_bf16 v[34:49], v[102:105], v[106:109], v[34:49]
	v_lshl_add_u64 v[254:255], v[82:83], 0, s[24:25]
	s_mov_b32 m0, s89
	s_nop 0
	global_load_lds_dwordx4 v[254:255], off
	v_mfma_f32_32x32x16_bf16 v[18:33], v[102:105], v[110:113], v[18:33]
	v_lshl_add_u64 v[254:255], v[84:85], 0, s[24:25]
	s_mov_b32 m0, s91
	s_nop 0
	global_load_lds_dwordx4 v[254:255], off
	v_mfma_f32_32x32x16_bf16 v[50:65], v[114:117], v[106:109], v[50:65]
	v_mfma_f32_32x32x16_bf16 v[2:17], v[114:117], v[110:113], v[2:17]
	s_waitcnt lgkmcnt(0)
	ds_read_b128 v[102:105], v98 offset:16384
	ds_read_b128 v[106:109], v99
	ds_read_b128 v[110:113], v99 offset:4096
	ds_read_b128 v[114:117], v98 offset:20480
	v_mfma_f32_32x32x16_bf16 v[34:49], v[238:241], v[242:245], v[34:49]
	v_lshl_add_u64 v[254:255], v[86:87], 0, s[24:25]
	s_mov_b32 m0, s92
	s_nop 0
	global_load_lds_dwordx4 v[254:255], off
	v_mfma_f32_32x32x16_bf16 v[18:33], v[238:241], v[246:249], v[18:33]
	v_lshl_add_u64 v[254:255], v[88:89], 0, s[24:25]
	s_mov_b32 m0, s93
	s_nop 0
	global_load_lds_dwordx4 v[254:255], off
	v_mfma_f32_32x32x16_bf16 v[50:65], v[250:253], v[242:245], v[50:65]
	v_mfma_f32_32x32x16_bf16 v[2:17], v[250:253], v[246:249], v[2:17]
	s_waitcnt lgkmcnt(0)
	ds_read_b128 v[238:241], v100 offset:16384
	ds_read_b128 v[242:245], v101
	ds_read_b128 v[246:249], v101 offset:4096
	ds_read_b128 v[250:253], v100 offset:20480
	v_mfma_f32_32x32x16_bf16 v[34:49], v[102:105], v[106:109], v[34:49]
	v_lshl_add_u64 v[254:255], v[90:91], 0, s[24:25]
	s_mov_b32 m0, s94
	s_nop 0
	global_load_lds_dwordx4 v[254:255], off
	v_mfma_f32_32x32x16_bf16 v[18:33], v[102:105], v[110:113], v[18:33]
	v_mfma_f32_32x32x16_bf16 v[50:65], v[114:117], v[106:109], v[50:65]
	v_mfma_f32_32x32x16_bf16 v[2:17], v[114:117], v[110:113], v[2:17]
	s_mov_b32 m0, s1
	s_waitcnt vmcnt(0) lgkmcnt(0)
	s_barrier
; template <class Epi>
; DI void gemm_phase(const u16* __restrict__ A, const u16* __restrict__ B, int mtiles, int ntiles, char* lds, const Epi& epi) {
;     ...
;         for (int kt = 0; kt < 16; ++kt) {
;             if (kt + 1 < 16) GSTAGE((kt + 1) & 1, kt + 1, ga, gb);
;             const char* sa = lds + (kt & 1) * 32768; const char* sb = sa + 16384;
; #pragma unroll
;             for (int ks = 0; ks < 4; ++ks) {
;                 bf16x8 fw[2], fx[2];
; #pragma unroll
;                 for (int ct = 0; ct < 2; ++ct) fw[ct] = *(const bf16x8*)(sb + swz(wn * 64 + ct * 32 + r, 2 * ks + h));
; #pragma unroll
;                 for (int tt = 0; tt < 2; ++tt) fx[tt] = *(const bf16x8*)(sa + swz(wm * 64 + tt * 32 + r, 2 * ks + h));
; #pragma unroll
;                 for (int ct = 0; ct < 2; ++ct)
; #pragma unroll
;                     for (int tt = 0; tt < 2; ++tt) acc[ct][tt] = __builtin_amdgcn_mfma_f32_32x32x16_bf16(fw[ct], fx[tt], acc[ct][tt], 0, 0, 0);
;             }
;             __syncthreads();
	ds_read_b128 v[102:105], v74 offset:49152
	ds_read_b128 v[106:109], v96 offset:32768
	ds_read_b128 v[110:113], v96 offset:36864
	ds_read_b128 v[114:117], v74 offset:53248
	v_mfma_f32_32x32x16_bf16 v[34:49], v[238:241], v[242:245], v[34:49]
	v_mfma_f32_32x32x16_bf16 v[18:33], v[238:241], v[246:249], v[18:33]
	v_lshl_add_u64 v[254:255], v[76:77], 0, s[26:27]
	global_load_lds_dwordx4 v[254:255], off
	v_lshl_add_u64 v[254:255], v[78:79], 0, s[26:27]
	s_mov_b32 m0, s7
	s_nop 0
	global_load_lds_dwordx4 v[254:255], off
	v_mfma_f32_32x32x16_bf16 v[50:65], v[250:253], v[242:245], v[50:65]
	v_lshl_add_u64 v[254:255], v[80:81], 0, s[26:27]
	s_mov_b32 m0, s38
	s_nop 0
	global_load_lds_dwordx4 v[254:255], off
	v_mfma_f32_32x32x16_bf16 v[2:17], v[250:253], v[246:249], v[2:17]
	s_waitcnt lgkmcnt(0)
	ds_read_b128 v[238:241], v95 offset:49152
	ds_read_b128 v[242:245], v97 offset:32768
	ds_read_b128 v[246:249], v97 offset:36864
	ds_read_b128 v[250:253], v95 offset:53248
	v_mfma_f32_32x32x16_bf16 v[34:49], v[102:105], v[106:109], v[34:49]
	v_lshl_add_u64 v[254:255], v[82:83], 0, s[26:27]
	s_mov_b32 m0, s39
	s_nop 0
	global_load_lds_dwordx4 v[254:255], off
	v_mfma_f32_32x32x16_bf16 v[18:33], v[102:105], v[110:113], v[18:33]
	v_lshl_add_u64 v[254:255], v[84:85], 0, s[26:27]
	s_mov_b32 m0, s50
	s_nop 0
	global_load_lds_dwordx4 v[254:255], off
	v_mfma_f32_32x32x16_bf16 v[50:65], v[114:117], v[106:109], v[50:65]
	v_mfma_f32_32x32x16_bf16 v[2:17], v[114:117], v[110:113], v[2:17]
	s_waitcnt lgkmcnt(0)
	ds_read_b128 v[102:105], v98 offset:49152
	ds_read_b128 v[106:109], v99 offset:32768
	ds_read_b128 v[110:113], v99 offset:36864
	ds_read_b128 v[114:117], v98 offset:53248
	v_mfma_f32_32x32x16_bf16 v[34:49], v[238:241], v[242:245], v[34:49]
	v_lshl_add_u64 v[254:255], v[86:87], 0, s[26:27]
	s_mov_b32 m0, s51
	s_nop 0
	global_load_lds_dwordx4 v[254:255], off
	v_mfma_f32_32x32x16_bf16 v[18:33], v[238:241], v[246:249], v[18:33]
	v_lshl_add_u64 v[254:255], v[88:89], 0, s[26:27]
	s_mov_b32 m0, s83
	s_nop 0
	global_load_lds_dwordx4 v[254:255], off
	v_mfma_f32_32x32x16_bf16 v[50:65], v[250:253], v[242:245], v[50:65]
	v_mfma_f32_32x32x16_bf16 v[2:17], v[250:253], v[246:249], v[2:17]
	s_waitcnt lgkmcnt(0)
	ds_read_b128 v[238:241], v100 offset:49152
	ds_read_b128 v[242:245], v101 offset:32768
	ds_read_b128 v[246:249], v101 offset:36864
	ds_read_b128 v[250:253], v100 offset:53248
	v_mfma_f32_32x32x16_bf16 v[34:49], v[102:105], v[106:109], v[34:49]
	v_lshl_add_u64 v[254:255], v[90:91], 0, s[26:27]
	s_mov_b32 m0, s90
	s_nop 0
	global_load_lds_dwordx4 v[254:255], off
	v_mfma_f32_32x32x16_bf16 v[18:33], v[102:105], v[110:113], v[18:33]
	v_mfma_f32_32x32x16_bf16 v[50:65], v[114:117], v[106:109], v[50:65]
	v_mfma_f32_32x32x16_bf16 v[2:17], v[114:117], v[110:113], v[2:17]
	s_mov_b32 m0, s86
	s_waitcnt vmcnt(0) lgkmcnt(0)
	s_barrier
	ds_read_b128 v[102:105], v74 offset:16384
	ds_read_b128 v[106:109], v96
	ds_read_b128 v[110:113], v96 offset:4096
	ds_read_b128 v[114:117], v74 offset:20480
	v_mfma_f32_32x32x16_bf16 v[34:49], v[238:241], v[242:245], v[34:49]
	v_mfma_f32_32x32x16_bf16 v[18:33], v[238:241], v[246:249], v[18:33]
	v_lshl_add_u64 v[254:255], v[76:77], 0, s[28:29]
	global_load_lds_dwordx4 v[254:255], off
	v_lshl_add_u64 v[254:255], v[78:79], 0, s[28:29]
	s_mov_b32 m0, s87
	s_nop 0
	global_load_lds_dwordx4 v[254:255], off
	v_mfma_f32_32x32x16_bf16 v[50:65], v[250:253], v[242:245], v[50:65]
	v_lshl_add_u64 v[254:255], v[80:81], 0, s[28:29]
	s_mov_b32 m0, s88
	s_nop 0
	global_load_lds_dwordx4 v[254:255], off
	v_mfma_f32_32x32x16_bf16 v[2:17], v[250:253], v[246:249], v[2:17]
	s_waitcnt lgkmcnt(0)
	ds_read_b128 v[238:241], v95 offset:16384
	ds_read_b128 v[242:245], v97
	ds_read_b128 v[246:249], v97 offset:4096
	ds_read_b128 v[250:253], v95 offset:20480
	v_mfma_f32_32x32x16_bf16 v[34:49], v[102:105], v[106:109], v[34:49]
	v_lshl_add_u64 v[254:255], v[82:83], 0, s[28:29]
	s_mov_b32 m0, s89
	s_nop 0
	global_load_lds_dwordx4 v[254:255], off
	v_mfma_f32_32x32x16_bf16 v[18:33], v[102:105], v[110:113], v[18:33]
	v_lshl_add_u64 v[254:255], v[84:85], 0, s[28:29]
	s_mov_b32 m0, s91
	s_nop 0
	global_load_lds_dwordx4 v[254:255], off
	v_mfma_f32_32x32x16_bf16 v[50:65], v[114:117], v[106:109], v[50:65]
	v_mfma_f32_32x32x16_bf16 v[2:17], v[114:117], v[110:113], v[2:17]
	s_waitcnt lgkmcnt(0)
	ds_read_b128 v[102:105], v98 offset:16384
	ds_read_b128 v[106:109], v99
	ds_read_b128 v[110:113], v99 offset:4096
	ds_read_b128 v[114:117], v98 offset:20480
	v_mfma_f32_32x32x16_bf16 v[34:49], v[238:241], v[242:245], v[34:49]
	v_lshl_add_u64 v[254:255], v[86:87], 0, s[28:29]
	s_mov_b32 m0, s92
	s_nop 0
	global_load_lds_dwordx4 v[254:255], off
	v_mfma_f32_32x32x16_bf16 v[18:33], v[238:241], v[246:249], v[18:33]
	v_lshl_add_u64 v[254:255], v[88:89], 0, s[28:29]
	s_mov_b32 m0, s93
	s_nop 0
	global_load_lds_dwordx4 v[254:255], off
	v_mfma_f32_32x32x16_bf16 v[50:65], v[250:253], v[242:245], v[50:65]
	v_mfma_f32_32x32x16_bf16 v[2:17], v[250:253], v[246:249], v[2:17]
	s_waitcnt lgkmcnt(0)
	ds_read_b128 v[238:241], v100 offset:16384
	ds_read_b128 v[242:245], v101
	ds_read_b128 v[246:249], v101 offset:4096
	ds_read_b128 v[250:253], v100 offset:20480
	v_mfma_f32_32x32x16_bf16 v[34:49], v[102:105], v[106:109], v[34:49]
	v_lshl_add_u64 v[254:255], v[90:91], 0, s[28:29]
	s_mov_b32 m0, s94
	s_nop 0
	global_load_lds_dwordx4 v[254:255], off
	v_mfma_f32_32x32x16_bf16 v[18:33], v[102:105], v[110:113], v[18:33]
	v_mfma_f32_32x32x16_bf16 v[50:65], v[114:117], v[106:109], v[50:65]
	v_mfma_f32_32x32x16_bf16 v[2:17], v[114:117], v[110:113], v[2:17]
	s_mov_b32 m0, s1
	s_waitcnt vmcnt(0) lgkmcnt(0)
	s_barrier
; template <class Epi>
; DI void gemm_phase(const u16* __restrict__ A, const u16* __restrict__ B, int mtiles, int ntiles, char* lds, const Epi& epi) {
;     ...
;         for (int kt = 0; kt < 16; ++kt) {
;             if (kt + 1 < 16) GSTAGE((kt + 1) & 1, kt + 1, ga, gb);
;             const char* sa = lds + (kt & 1) * 32768; const char* sb = sa + 16384;
; #pragma unroll
;             for (int ks = 0; ks < 4; ++ks) {
;                 bf16x8 fw[2], fx[2];
; #pragma unroll
;                 for (int ct = 0; ct < 2; ++ct) fw[ct] = *(const bf16x8*)(sb + swz(wn * 64 + ct * 32 + r, 2 * ks + h));
; #pragma unroll
;                 for (int tt = 0; tt < 2; ++tt) fx[tt] = *(const bf16x8*)(sa + swz(wm * 64 + tt * 32 + r, 2 * ks + h));
; #pragma unroll
;                 for (int ct = 0; ct < 2; ++ct)
; #pragma unroll
;                     for (int tt = 0; tt < 2; ++tt) acc[ct][tt] = __builtin_amdgcn_mfma_f32_32x32x16_bf16(fw[ct], fx[tt], acc[ct][tt], 0, 0, 0);
;             }
;             __syncthreads();
	ds_read_b128 v[102:105], v74 offset:49152
	ds_read_b128 v[106:109], v96 offset:32768
	ds_read_b128 v[110:113], v96 offset:36864
	ds_read_b128 v[114:117], v74 offset:53248
	v_mfma_f32_32x32x16_bf16 v[34:49], v[238:241], v[242:245], v[34:49]
	v_mfma_f32_32x32x16_bf16 v[18:33], v[238:241], v[246:249], v[18:33]
	v_lshl_add_u64 v[254:255], v[76:77], 0, s[30:31]
	global_load_lds_dwordx4 v[254:255], off
	v_lshl_add_u64 v[254:255], v[78:79], 0, s[30:31]
	s_mov_b32 m0, s7
	s_nop 0
	global_load_lds_dwordx4 v[254:255], off
	v_mfma_f32_32x32x16_bf16 v[50:65], v[250:253], v[242:245], v[50:65]
	v_lshl_add_u64 v[254:255], v[80:81], 0, s[30:31]
	s_mov_b32 m0, s38
	s_nop 0
	global_load_lds_dwordx4 v[254:255], off
	v_mfma_f32_32x32x16_bf16 v[2:17], v[250:253], v[246:249], v[2:17]
	s_waitcnt lgkmcnt(0)
	ds_read_b128 v[238:241], v95 offset:49152
	ds_read_b128 v[242:245], v97 offset:32768
	ds_read_b128 v[246:249], v97 offset:36864
	ds_read_b128 v[250:253], v95 offset:53248
	v_mfma_f32_32x32x16_bf16 v[34:49], v[102:105], v[106:109], v[34:49]
	v_lshl_add_u64 v[254:255], v[82:83], 0, s[30:31]
	s_mov_b32 m0, s39
	s_nop 0
	global_load_lds_dwordx4 v[254:255], off
	v_mfma_f32_32x32x16_bf16 v[18:33], v[102:105], v[110:113], v[18:33]
	v_lshl_add_u64 v[254:255], v[84:85], 0, s[30:31]
	s_mov_b32 m0, s50
	s_nop 0
	global_load_lds_dwordx4 v[254:255], off
	v_mfma_f32_32x32x16_bf16 v[50:65], v[114:117], v[106:109], v[50:65]
	v_mfma_f32_32x32x16_bf16 v[2:17], v[114:117], v[110:113], v[2:17]
	s_waitcnt lgkmcnt(0)
	ds_read_b128 v[102:105], v98 offset:49152
	ds_read_b128 v[106:109], v99 offset:32768
	ds_read_b128 v[110:113], v99 offset:36864
	ds_read_b128 v[114:117], v98 offset:53248
	v_mfma_f32_32x32x16_bf16 v[34:49], v[238:241], v[242:245], v[34:49]
	v_lshl_add_u64 v[254:255], v[86:87], 0, s[30:31]
	s_mov_b32 m0, s51
	s_nop 0
	global_load_lds_dwordx4 v[254:255], off
	v_mfma_f32_32x32x16_bf16 v[18:33], v[238:241], v[246:249], v[18:33]
	v_lshl_add_u64 v[254:255], v[88:89], 0, s[30:31]
	s_mov_b32 m0, s83
	s_nop 0
	global_load_lds_dwordx4 v[254:255], off
	v_mfma_f32_32x32x16_bf16 v[50:65], v[250:253], v[242:245], v[50:65]
	v_mfma_f32_32x32x16_bf16 v[2:17], v[250:253], v[246:249], v[2:17]
	s_waitcnt lgkmcnt(0)
	ds_read_b128 v[238:241], v100 offset:49152
	ds_read_b128 v[242:245], v101 offset:32768
	ds_read_b128 v[246:249], v101 offset:36864
	ds_read_b128 v[250:253], v100 offset:53248
	v_mfma_f32_32x32x16_bf16 v[34:49], v[102:105], v[106:109], v[34:49]
	v_lshl_add_u64 v[254:255], v[90:91], 0, s[30:31]
	s_mov_b32 m0, s90
	s_nop 0
	global_load_lds_dwordx4 v[254:255], off
	v_mfma_f32_32x32x16_bf16 v[18:33], v[102:105], v[110:113], v[18:33]
	v_mfma_f32_32x32x16_bf16 v[50:65], v[114:117], v[106:109], v[50:65]
	v_mfma_f32_32x32x16_bf16 v[2:17], v[114:117], v[110:113], v[2:17]
	s_mov_b32 m0, s86
	s_waitcnt vmcnt(0) lgkmcnt(0)
	s_barrier
	ds_read_b128 v[102:105], v74 offset:16384
	ds_read_b128 v[106:109], v96
	ds_read_b128 v[110:113], v96 offset:4096
	ds_read_b128 v[114:117], v74 offset:20480
	v_mfma_f32_32x32x16_bf16 v[34:49], v[238:241], v[242:245], v[34:49]
	v_mfma_f32_32x32x16_bf16 v[18:33], v[238:241], v[246:249], v[18:33]
	v_lshl_add_u64 v[254:255], v[76:77], 0, s[36:37]
	global_load_lds_dwordx4 v[254:255], off
	v_lshl_add_u64 v[254:255], v[78:79], 0, s[36:37]
	s_mov_b32 m0, s87
	s_nop 0
	global_load_lds_dwordx4 v[254:255], off
	v_mfma_f32_32x32x16_bf16 v[50:65], v[250:253], v[242:245], v[50:65]
	v_lshl_add_u64 v[254:255], v[80:81], 0, s[36:37]
	s_mov_b32 m0, s88
	s_nop 0
	global_load_lds_dwordx4 v[254:255], off
	v_mfma_f32_32x32x16_bf16 v[2:17], v[250:253], v[246:249], v[2:17]
	s_waitcnt lgkmcnt(0)
	ds_read_b128 v[238:241], v95 offset:16384
	ds_read_b128 v[242:245], v97
	ds_read_b128 v[246:249], v97 offset:4096
	ds_read_b128 v[250:253], v95 offset:20480
	v_mfma_f32_32x32x16_bf16 v[34:49], v[102:105], v[106:109], v[34:49]
	v_lshl_add_u64 v[254:255], v[82:83], 0, s[36:37]
	s_mov_b32 m0, s89
	s_nop 0
	global_load_lds_dwordx4 v[254:255], off
	v_mfma_f32_32x32x16_bf16 v[18:33], v[102:105], v[110:113], v[18:33]
	v_lshl_add_u64 v[254:255], v[84:85], 0, s[36:37]
	s_mov_b32 m0, s91
	s_nop 0
	global_load_lds_dwordx4 v[254:255], off
	v_mfma_f32_32x32x16_bf16 v[50:65], v[114:117], v[106:109], v[50:65]
	v_mfma_f32_32x32x16_bf16 v[2:17], v[114:117], v[110:113], v[2:17]
	s_waitcnt lgkmcnt(0)
	ds_read_b128 v[102:105], v98 offset:16384
	ds_read_b128 v[106:109], v99
	ds_read_b128 v[110:113], v99 offset:4096
	ds_read_b128 v[114:117], v98 offset:20480
	v_mfma_f32_32x32x16_bf16 v[34:49], v[238:241], v[242:245], v[34:49]
	v_lshl_add_u64 v[254:255], v[86:87], 0, s[36:37]
	s_mov_b32 m0, s92
	s_nop 0
	global_load_lds_dwordx4 v[254:255], off
	v_mfma_f32_32x32x16_bf16 v[18:33], v[238:241], v[246:249], v[18:33]
	v_lshl_add_u64 v[254:255], v[88:89], 0, s[36:37]
	s_mov_b32 m0, s93
	s_nop 0
	global_load_lds_dwordx4 v[254:255], off
	v_mfma_f32_32x32x16_bf16 v[50:65], v[250:253], v[242:245], v[50:65]
	v_mfma_f32_32x32x16_bf16 v[2:17], v[250:253], v[246:249], v[2:17]
	s_waitcnt lgkmcnt(0)
	ds_read_b128 v[238:241], v100 offset:16384
	ds_read_b128 v[242:245], v101
	ds_read_b128 v[246:249], v101 offset:4096
	ds_read_b128 v[250:253], v100 offset:20480
	v_mfma_f32_32x32x16_bf16 v[34:49], v[102:105], v[106:109], v[34:49]
	v_lshl_add_u64 v[254:255], v[90:91], 0, s[36:37]
	s_mov_b32 m0, s94
	s_nop 0
	global_load_lds_dwordx4 v[254:255], off
	v_mfma_f32_32x32x16_bf16 v[18:33], v[102:105], v[110:113], v[18:33]
	v_mfma_f32_32x32x16_bf16 v[50:65], v[114:117], v[106:109], v[50:65]
	v_mfma_f32_32x32x16_bf16 v[2:17], v[114:117], v[110:113], v[2:17]
	s_mov_b32 m0, s1
	s_waitcnt vmcnt(0) lgkmcnt(0)
	s_barrier
; template <class Epi>
; DI void gemm_phase(const u16* __restrict__ A, const u16* __restrict__ B, int mtiles, int ntiles, char* lds, const Epi& epi) {
;     ...
;         for (int kt = 0; kt < 16; ++kt) {
;             if (kt + 1 < 16) GSTAGE((kt + 1) & 1, kt + 1, ga, gb);
;             const char* sa = lds + (kt & 1) * 32768; const char* sb = sa + 16384;
; #pragma unroll
;             for (int ks = 0; ks < 4; ++ks) {
;                 bf16x8 fw[2], fx[2];
; #pragma unroll
;                 for (int ct = 0; ct < 2; ++ct) fw[ct] = *(const bf16x8*)(sb + swz(wn * 64 + ct * 32 + r, 2 * ks + h));
; #pragma unroll
;                 for (int tt = 0; tt < 2; ++tt) fx[tt] = *(const bf16x8*)(sa + swz(wm * 64 + tt * 32 + r, 2 * ks + h));
; #pragma unroll
;                 for (int ct = 0; ct < 2; ++ct)
; #pragma unroll
;                     for (int tt = 0; tt < 2; ++tt) acc[ct][tt] = __builtin_amdgcn_mfma_f32_32x32x16_bf16(fw[ct], fx[tt], acc[ct][tt], 0, 0, 0);
;             }
;             __syncthreads();
	ds_read_b128 v[102:105], v74 offset:49152
	ds_read_b128 v[106:109], v96 offset:32768
	ds_read_b128 v[110:113], v96 offset:36864
	ds_read_b128 v[114:117], v74 offset:53248
	v_mfma_f32_32x32x16_bf16 v[34:49], v[238:241], v[242:245], v[34:49]
	v_mfma_f32_32x32x16_bf16 v[18:33], v[238:241], v[246:249], v[18:33]
	v_lshl_add_u64 v[254:255], v[76:77], 0, s[68:69]
	global_load_lds_dwordx4 v[254:255], off
	v_lshl_add_u64 v[254:255], v[78:79], 0, s[68:69]
	s_mov_b32 m0, s7
	v_lshl_add_u64 v[76:77], v[76:77], 0, s[70:71]
	global_load_lds_dwordx4 v[254:255], off
	v_mfma_f32_32x32x16_bf16 v[50:65], v[250:253], v[242:245], v[50:65]
	v_lshl_add_u64 v[254:255], v[80:81], 0, s[68:69]
	s_mov_b32 m0, s38
	s_nop 0
	global_load_lds_dwordx4 v[254:255], off
	v_mfma_f32_32x32x16_bf16 v[2:17], v[250:253], v[246:249], v[2:17]
	s_waitcnt lgkmcnt(0)
	ds_read_b128 v[238:241], v95 offset:49152
	ds_read_b128 v[242:245], v97 offset:32768
	ds_read_b128 v[246:249], v97 offset:36864
	ds_read_b128 v[250:253], v95 offset:53248
	v_mfma_f32_32x32x16_bf16 v[34:49], v[102:105], v[106:109], v[34:49]
	v_lshl_add_u64 v[254:255], v[82:83], 0, s[68:69]
	s_mov_b32 m0, s39
	s_nop 0
	global_load_lds_dwordx4 v[254:255], off
	v_mfma_f32_32x32x16_bf16 v[18:33], v[102:105], v[110:113], v[18:33]
	v_lshl_add_u64 v[254:255], v[84:85], 0, s[68:69]
	s_mov_b32 m0, s50
	s_nop 0
	global_load_lds_dwordx4 v[254:255], off
	v_mfma_f32_32x32x16_bf16 v[50:65], v[114:117], v[106:109], v[50:65]
	v_mfma_f32_32x32x16_bf16 v[2:17], v[114:117], v[110:113], v[2:17]
	s_waitcnt lgkmcnt(0)
	ds_read_b128 v[102:105], v98 offset:49152
	ds_read_b128 v[106:109], v99 offset:32768
	ds_read_b128 v[110:113], v99 offset:36864
	ds_read_b128 v[114:117], v98 offset:53248
	v_mfma_f32_32x32x16_bf16 v[34:49], v[238:241], v[242:245], v[34:49]
	v_lshl_add_u64 v[254:255], v[86:87], 0, s[68:69]
	s_mov_b32 m0, s51
	s_nop 0
	global_load_lds_dwordx4 v[254:255], off
	v_mfma_f32_32x32x16_bf16 v[18:33], v[238:241], v[246:249], v[18:33]
	v_lshl_add_u64 v[254:255], v[88:89], 0, s[68:69]
	s_mov_b32 m0, s83
	s_nop 0
	global_load_lds_dwordx4 v[254:255], off
	v_mfma_f32_32x32x16_bf16 v[50:65], v[250:253], v[242:245], v[50:65]
	v_mfma_f32_32x32x16_bf16 v[2:17], v[250:253], v[246:249], v[2:17]
	s_waitcnt lgkmcnt(0)
	ds_read_b128 v[238:241], v100 offset:49152
	ds_read_b128 v[242:245], v101 offset:32768
	ds_read_b128 v[246:249], v101 offset:36864
	ds_read_b128 v[250:253], v100 offset:53248
	v_mfma_f32_32x32x16_bf16 v[34:49], v[102:105], v[106:109], v[34:49]
	v_lshl_add_u64 v[254:255], v[90:91], 0, s[68:69]
	s_mov_b32 m0, s90
	s_nop 0
	global_load_lds_dwordx4 v[254:255], off
	v_mfma_f32_32x32x16_bf16 v[18:33], v[102:105], v[110:113], v[18:33]
	v_mfma_f32_32x32x16_bf16 v[50:65], v[114:117], v[106:109], v[50:65]
	v_mfma_f32_32x32x16_bf16 v[2:17], v[114:117], v[110:113], v[2:17]
	s_mov_b32 m0, s86
	s_mov_b32 s86, 0
	s_waitcnt vmcnt(0) lgkmcnt(0)
	s_barrier
; #define TILE_MN(t, M0, N0) do { int pan_ = (t) / (mtiles * 8); if (pan_ >= npan) pan_ = npan - 1; const int pw_ = (pan_ == npan - 1) ? ntiles - 8 * pan_ : 8; const int loc_ = (t) - pan_ * mtiles * 8; \
;         M0 = (loc_ / pw_) * 128; N0 = (8 * pan_ + loc_ % pw_) * 128; } while (0)
; template <class Epi>
; DI void gemm_phase(const u16* __restrict__ A, const u16* __restrict__ B, int mtiles, int ntiles, char* lds, const Epi& epi) {
;     ...
;         for (int kt = 0; kt < 16; ++kt) {
;             if (kt + 1 < 16) GSTAGE((kt + 1) & 1, kt + 1, ga, gb);
;             const char* sa = lds + (kt & 1) * 32768; const char* sb = sa + 16384;
; #pragma unroll
;             for (int ks = 0; ks < 4; ++ks) {
;                 bf16x8 fw[2], fx[2];
; #pragma unroll
;                 for (int ct = 0; ct < 2; ++ct) fw[ct] = *(const bf16x8*)(sb + swz(wn * 64 + ct * 32 + r, 2 * ks + h));
; #pragma unroll
;                 for (int tt = 0; tt < 2; ++tt) fx[tt] = *(const bf16x8*)(sa + swz(wm * 64 + tt * 32 + r, 2 * ks + h));
; #pragma unroll
;                 for (int ct = 0; ct < 2; ++ct)
; #pragma unroll
;                     for (int tt = 0; tt < 2; ++tt) acc[ct][tt] = __builtin_amdgcn_mfma_f32_32x32x16_bf16(fw[ct], fx[tt], acc[ct][tt], 0, 0, 0);
;             }
;             __syncthreads();
;         }
;         const int nxt = tile + (int)gridDim.x; int m1 = 0, n1 = 0;
;         if (nxt < ntile) { TILE_MN(nxt, m1, n1); GSTAGE(0, 0, A + (size_t)m1 * 1024, B + (size_t)n1 * 1024); }
	global_load_lds_dwordx4 v[76:77], off
	v_lshl_add_u64 v[76:77], v[78:79], 0, s[70:71]
	s_mov_b32 m0, s87
	v_mfma_f32_32x32x16_bf16 v[34:49], v[238:241], v[242:245], v[34:49]
	global_load_lds_dwordx4 v[76:77], off
	v_lshl_add_u64 v[76:77], v[80:81], 0, s[70:71]
	s_mov_b32 m0, s88
	s_mov_b32 s88, 0
	global_load_lds_dwordx4 v[76:77], off
	v_lshl_add_u64 v[76:77], v[82:83], 0, s[70:71]
	s_mov_b32 m0, s89
	v_mfma_f32_32x32x16_bf16 v[18:33], v[238:241], v[246:249], v[18:33]
	global_load_lds_dwordx4 v[76:77], off
	v_lshl_add_u64 v[76:77], v[84:85], 0, s[70:71]
	s_mov_b32 m0, s91
	s_nop 0
	global_load_lds_dwordx4 v[76:77], off
	v_lshl_add_u64 v[76:77], v[86:87], 0, s[70:71]
	s_mov_b32 m0, s92
	v_mfma_f32_32x32x16_bf16 v[50:65], v[250:253], v[242:245], v[50:65]
	global_load_lds_dwordx4 v[76:77], off
	v_lshl_add_u64 v[76:77], v[88:89], 0, s[70:71]
	s_mov_b32 m0, s93
	s_nop 0
	global_load_lds_dwordx4 v[76:77], off
	v_lshl_add_u64 v[76:77], v[90:91], 0, s[70:71]
	s_mov_b32 m0, s94
	v_mfma_f32_32x32x16_bf16 v[2:17], v[250:253], v[246:249], v[2:17]
	global_load_lds_dwordx4 v[76:77], off
	ds_read_b128 v[76:79], v74 offset:16384
	ds_read_b128 v[80:83], v96
	ds_read_b128 v[84:87], v96 offset:4096
	ds_read_b128 v[88:91], v74 offset:20480
	s_waitcnt lgkmcnt(0)
	v_mfma_f32_32x32x16_bf16 v[34:49], v[76:79], v[80:83], v[34:49]
	v_mfma_f32_32x32x16_bf16 v[18:33], v[76:79], v[84:87], v[18:33]
	v_mfma_f32_32x32x16_bf16 v[50:65], v[88:91], v[80:83], v[50:65]
	v_mfma_f32_32x32x16_bf16 v[2:17], v[88:91], v[84:87], v[2:17]
	ds_read_b128 v[76:79], v95 offset:16384
	ds_read_b128 v[80:83], v97
	ds_read_b128 v[84:87], v97 offset:4096
	ds_read_b128 v[88:91], v95 offset:20480
	s_waitcnt lgkmcnt(0)
	v_mfma_f32_32x32x16_bf16 v[34:49], v[76:79], v[80:83], v[34:49]
	v_mfma_f32_32x32x16_bf16 v[18:33], v[76:79], v[84:87], v[18:33]
	v_mfma_f32_32x32x16_bf16 v[50:65], v[88:91], v[80:83], v[50:65]
	v_mfma_f32_32x32x16_bf16 v[2:17], v[88:91], v[84:87], v[2:17]
	ds_read_b128 v[76:79], v98 offset:16384
	ds_read_b128 v[80:83], v99
	ds_read_b128 v[84:87], v99 offset:4096
	ds_read_b128 v[88:91], v98 offset:20480
	s_waitcnt lgkmcnt(0)
	v_mfma_f32_32x32x16_bf16 v[34:49], v[76:79], v[80:83], v[34:49]
	v_mfma_f32_32x32x16_bf16 v[18:33], v[76:79], v[84:87], v[18:33]
	v_mfma_f32_32x32x16_bf16 v[50:65], v[88:91], v[80:83], v[50:65]
	v_mfma_f32_32x32x16_bf16 v[2:17], v[88:91], v[84:87], v[2:17]
	ds_read_b128 v[76:79], v100 offset:16384
	ds_read_b128 v[80:83], v101
	ds_read_b128 v[84:87], v101 offset:4096
	ds_read_b128 v[88:91], v100 offset:20480
	s_waitcnt vmcnt(0) lgkmcnt(0)
	s_barrier
	v_mfma_f32_32x32x16_bf16 v[34:49], v[76:79], v[80:83], v[34:49]
	v_mfma_f32_32x32x16_bf16 v[18:33], v[76:79], v[84:87], v[18:33]
	v_mfma_f32_32x32x16_bf16 v[50:65], v[88:91], v[80:83], v[50:65]
	v_mfma_f32_32x32x16_bf16 v[2:17], v[88:91], v[84:87], v[2:17]
	ds_read_b128 v[76:79], v96 offset:32768
	ds_read_b128 v[80:83], v96 offset:36864
	ds_read_b128 v[84:87], v74 offset:49152
	ds_read_b128 v[88:91], v74 offset:53248
	s_waitcnt lgkmcnt(1)
	v_mfma_f32_32x32x16_bf16 v[34:49], v[84:87], v[76:79], v[34:49]
	v_mfma_f32_32x32x16_bf16 v[18:33], v[84:87], v[80:83], v[18:33]
	s_waitcnt lgkmcnt(0)
	v_mfma_f32_32x32x16_bf16 v[50:65], v[88:91], v[76:79], v[50:65]
	v_mfma_f32_32x32x16_bf16 v[2:17], v[88:91], v[80:83], v[2:17]
	ds_read_b128 v[76:79], v95 offset:49152
	ds_read_b128 v[80:83], v97 offset:32768
	ds_read_b128 v[84:87], v97 offset:36864
	ds_read_b128 v[88:91], v95 offset:53248
	s_waitcnt lgkmcnt(2)
	v_mfma_f32_32x32x16_bf16 v[34:49], v[76:79], v[80:83], v[34:49]
	s_waitcnt lgkmcnt(1)
	v_mfma_f32_32x32x16_bf16 v[18:33], v[76:79], v[84:87], v[18:33]
	s_waitcnt lgkmcnt(0)
	v_mfma_f32_32x32x16_bf16 v[50:65], v[88:91], v[80:83], v[50:65]
	v_mfma_f32_32x32x16_bf16 v[2:17], v[88:91], v[84:87], v[2:17]
	ds_read_b128 v[76:79], v98 offset:49152
	ds_read_b128 v[80:83], v99 offset:32768
	ds_read_b128 v[84:87], v99 offset:36864
	ds_read_b128 v[88:91], v98 offset:53248
	s_waitcnt lgkmcnt(2)
	v_mfma_f32_32x32x16_bf16 v[34:49], v[76:79], v[80:83], v[34:49]
	s_waitcnt lgkmcnt(1)
	v_mfma_f32_32x32x16_bf16 v[18:33], v[76:79], v[84:87], v[18:33]
	s_waitcnt lgkmcnt(0)
	v_mfma_f32_32x32x16_bf16 v[50:65], v[88:91], v[80:83], v[50:65]
	v_mfma_f32_32x32x16_bf16 v[2:17], v[88:91], v[84:87], v[2:17]
	ds_read_b128 v[76:79], v100 offset:49152
	ds_read_b128 v[80:83], v101 offset:32768
	ds_read_b128 v[84:87], v101 offset:36864
	ds_read_b128 v[88:91], v100 offset:53248
	s_waitcnt lgkmcnt(0)
	s_barrier
	v_mfma_f32_32x32x16_bf16 v[34:49], v[76:79], v[80:83], v[34:49]
	v_mfma_f32_32x32x16_bf16 v[18:33], v[76:79], v[84:87], v[18:33]
	v_mfma_f32_32x32x16_bf16 v[50:65], v[88:91], v[80:83], v[50:65]
	v_mfma_f32_32x32x16_bf16 v[2:17], v[88:91], v[84:87], v[2:17]
	s_cbranch_scc1 .Llt_99
	s_mov_b32 m0, s1
	s_mov_b32 s96, s33
	s_cmpk_lt_i32 s33, 0xe97
	s_cbranch_scc1 .Lrm_done_l1
	s_cmpk_lt_i32 s33, 0x1000
	s_cbranch_scc0 .Lrm_def_l1
	s_add_i32 s96, s33, 0x104
	s_cmpk_lt_i32 s33, 0xfdc
	s_cbranch_scc0 .Lrm_done_l1
	s_sub_i32 s97, s33, 0xe97
	s_mul_i32 s97, s97, 0x3334
	s_lshr_b32 s97, s97, 16
	s_lshl_b32 s97, s97, 2
	s_add_i32 s96, s33, s97
	s_branch .Lrm_done_l1

; #define TILE_MN(t, M0, N0) do { int pan_ = (t) / (mtiles * 8); if (pan_ >= npan) pan_ = npan - 1; const int pw_ = (pan_ == npan - 1) ? ntiles - 8 * pan_ : 8; const int loc_ = (t) - pan_ * mtiles * 8; \
;         M0 = (loc_ / pw_) * 128; N0 = (8 * pan_ + loc_ % pw_) * 128; } while (0)
; template <class Epi>
; DI void gemm_phase(const u16* __restrict__ A, const u16* __restrict__ B, int mtiles, int ntiles, char* lds, const Epi& epi) {
;     ...
;         if (nxt < ntile) { TILE_MN(nxt, m1, n1); GSTAGE(0, 0, A + (size_t)m1 * 1024, B + (size_t)n1 * 1024); }
.Lrm_done_l1:
	s_mul_hi_i32 s1, s96, 0x3e0f83e1
	s_lshr_b32 s86, s1, 31
	s_ashr_i32 s1, s1, 8
	s_add_i32 s1, s1, s86
	s_cmpk_lt_i32 s96, 0x1080
	s_cselect_b32 s1, s1, 3
	s_cmp_eq_u32 s1, 3
	s_cselect_b32 s87, 9, 8
	v_cvt_f32_ubyte0_e32 v74, s87
	v_rcp_iflag_f32_e32 v74, v74
	s_sub_i32 s91, 0, s87
	s_mul_i32 s86, s1, 0xfffffbe0
	s_add_i32 s88, s96, s86
	v_mul_f32_e32 v74, 0x4f7ffffe, v74
	v_cvt_u32_f32_e32 v74, v74
	s_abs_i32 s89, s88
	s_ashr_i32 s86, s88, 31
	v_readfirstlane_b32 s92, v74
	s_mul_i32 s91, s91, s92
	s_mul_hi_u32 s91, s92, s91
	s_add_i32 s92, s92, s91
	s_mul_hi_u32 s91, s89, s92
	s_mul_i32 s92, s91, s87
	s_sub_i32 s89, s89, s92
	s_add_i32 s92, s91, 1
	s_sub_i32 s93, s89, s87
	s_cmp_ge_u32 s89, s87
	s_cselect_b32 s91, s92, s91
	s_cselect_b32 s89, s93, s89
	s_add_i32 s92, s91, 1
	s_cmp_ge_u32 s89, s87
	s_cselect_b32 s89, s92, s91
	s_xor_b32 s89, s89, s86
	s_sub_i32 s89, s89, s86
	s_lshl_b32 s86, s89, 7
	s_mul_i32 s89, s89, s87
	s_sub_i32 s87, s88, s89
	s_lshl_b32 s1, s1, 10
	s_lshl_b32 s87, s87, 7
	s_add_i32 s88, s87, s1
	s_ashr_i32 s87, s86, 31
	s_lshl_b64 s[92:93], s[86:87], 11
	v_readlane_b32 s98, v237, 4
	v_readlane_b32 s99, v237, 5
	s_add_u32 s92, s98, s92
	s_addc_u32 s93, s99, s93
	s_ashr_i32 s89, s88, 31
	s_lshl_b64 s[94:95], s[88:89], 11
	v_readlane_b32 s1, v236, 9
	s_add_u32 s94, s1, s94
	v_readlane_b32 s1, v236, 11
	s_addc_u32 s95, s1, s95
	v_lshl_add_u64 v[76:77], s[92:93], 0, v[66:67]
	global_load_lds_dwordx4 v[76:77], off
	v_lshl_add_u64 v[66:67], s[94:95], 0, v[66:67]
	s_mov_b32 m0, s7
	s_nop 0
	global_load_lds_dwordx4 v[66:67], off
	v_lshl_add_u64 v[66:67], s[92:93], 0, v[68:69]
	s_mov_b32 m0, s38
	s_nop 0
	global_load_lds_dwordx4 v[66:67], off
	v_lshl_add_u64 v[66:67], s[94:95], 0, v[68:69]
	s_mov_b32 m0, s39
	s_nop 0
	global_load_lds_dwordx4 v[66:67], off
	v_lshl_add_u64 v[66:67], s[92:93], 0, v[70:71]
	s_mov_b32 m0, s50
	s_nop 0
	global_load_lds_dwordx4 v[66:67], off
	v_lshl_add_u64 v[66:67], s[94:95], 0, v[70:71]
	s_mov_b32 m0, s51
	s_nop 0
	global_load_lds_dwordx4 v[66:67], off
	v_lshl_add_u64 v[66:67], s[92:93], 0, v[72:73]
	s_mov_b32 m0, s83
	s_nop 0
	global_load_lds_dwordx4 v[66:67], off
	v_lshl_add_u64 v[66:67], s[94:95], 0, v[72:73]
	s_mov_b32 m0, s90
	s_nop 0
	global_load_lds_dwordx4 v[66:67], off

;     DI void operator()(f32x16 (&acc)[2][2], int mrow0, int ncol0, int lane) const {
;     ...
;             if (cb >= 8 && cb < 24) {
;                 const int hh = cb & 7;
;                 if (row < NTP) { const int b = row >> 13, t = row & 8191; if (t >= 7680) dst = out + (cb < 16 ? O_KP : O_VP) + ((size_t)(b * 8 + hh) * 512 + (t - 7680)) * 64; }
;                 else { const int s = row - NTP; const int b = s >> 4, t = s & 15; dst = out + (cb < 16 ? O_KS : O_VS) + ((size_t)(b * 8 + hh) * 16 + t) * 64; }
.Llt_125:
	s_andn2_b64 vcc, exec, s[6:7]
	s_movk_i32 s95, 0x200
	s_cbranch_vccnz .Llt_133
	s_movk_i32 s0, 0x3fdf
	v_cmp_lt_i32_e32 vcc, s0, v76
	s_and_saveexec_b64 s[0:1], vcc
	s_xor_b64 s[0:1], exec, s[0:1]
	v_add_u32_e32 v10, 0xffffc020, v76
	v_lshrrev_b32_e32 v10, 1, v10
	v_and_b32_e32 v10, 0x7ffffff8, v10
	v_or_b32_e32 v74, s4, v10
	v_lshlrev_b64 v[10:11], 12, v[74:75]
	v_lshlrev_b32_e32 v12, 8, v80
	v_lshl_add_u64 v[10:11], s[90:91], 0, v[10:11]
	v_and_b32_e32 v74, 0xf00, v12
	v_lshl_add_u64 v[12:13], v[10:11], 0, v[74:75]
	s_andn2_saveexec_b64 s[0:1], s[0:1]
	s_cbranch_execz .Llt_132
	v_and_b32_e32 v11, 0x1fff, v10
	s_movk_i32 s6, 0x1dff
	v_cmp_lt_u32_e32 vcc, s6, v11
	v_mov_b64_e32 v[12:13], 0
	s_and_saveexec_b64 s[6:7], vcc
	v_ashrrev_i32_e32 v10, 10, v10
	v_and_or_b32 v12, v10, -8, s4
	v_ashrrev_i32_e32 v13, 31, v12
	v_add_u32_e32 v74, 0xffffe200, v11
	v_lshlrev_b64 v[10:11], 17, v[12:13]
	v_lshl_add_u64 v[10:11], s[82:83], 0, v[10:11]
	v_lshlrev_b64 v[12:13], 8, v[74:75]
	v_lshl_add_u64 v[12:13], v[10:11], 0, v[12:13]
	s_or_b64 exec, exec, s[6:7]

; DI void phase_rwkv_prep(const Params& p, char* lds) {
;     ...
;     for (int u = blockIdx.x; u < NUNIT; u += gridDim.x) {
;         int tid = threadIdx.x; asm volatile("" : "+v"(tid));
;         const int lane = tid & 63, wave = __builtin_amdgcn_readfirstlane(tid >> 6); const int qm = wave >> 1, qn = wave & 1; const int r = lane & 31, h5 = lane >> 5;
;         int b, h, c, row0, ntok; bool prm = u < 2048;
;         if (prm) { b = u >> 10; h = (u >> 7) & 7; c = u & 127; row0 = b * 8192 + c * 64; ntok = 64; }
;         else { const int s = u - 2048; b = s >> 3; h = s & 7; c = 0; row0 = NTP + b * 16; ntok = 16; }
;         const int mode0 = prm ? (c > 0 ? 0 : 1) : 2;
.Llt_done:
	v_readlane_b32 s33, v236, 3
	v_readlane_b32 s95, v236, 8
	s_add_u32 s68, s54, 0x2bf4800
	s_addc_u32 s69, s55, 0
	s_cmp_eq_u32 s100, 2
	s_cbranch_scc1 .Llt_ret3
	s_and_saveexec_b64 s[0:1], s[34:35]
	s_add_u32 s12, s54, 0xfc14808
	s_addc_u32 s13, s55, 0
	v_mov_b32_e32 v240, 0
	v_mov_b32_e32 v241, 1
	global_atomic_add v240, v241, s[12:13]
	s_or_b64 exec, exec, s[0:1]
	s_branch .Lp2_entry
.Llt_ret3:
	s_mov_b32 s100, 3
	s_branch .Lp3_ret
.Llt_skip:
	s_bitcmp1_b32 s33, 7
	s_cbranch_scc1 .Llt_nopoll
	s_and_b32 s3, s33, 0x7f
	s_cmp_lt_u32 s3, 0x7e
	s_cbranch_scc1 .Llt_nopoll
	s_and_saveexec_b64 s[0:1], s[34:35]
	s_cbranch_execz .Lpl_end_e
	s_add_u32 s12, s54, 0xfc14808
	s_addc_u32 s13, s55, 0
	v_mov_b32_e32 v240, 0
	s_mov_b32 s5, 0
.Lpl_e:
	global_load_dword v241, v240, s[12:13] sc1
	s_waitcnt vmcnt(0)
	v_readfirstlane_b32 s3, v241
	s_cmp_ge_u32 s3, 0x104
	s_cbranch_scc1 .Lpl_end_e
	s_sleep 2
	s_add_i32 s5, s5, 1
	s_cmp_lt_u32 s5, 0x10000
	s_cbranch_scc1 .Lpl_e
.Lpl_end_e:
	s_or_b64 exec, exec, s[0:1]
	s_barrier
.Llt_nopoll:
	s_mov_b32 s101, 0
	s_add_u32 s0, s78, 0x1800
	s_addc_u32 s1, s79, 0
	v_writelane_b32 v236, s0, 18
	s_mov_b32 s9, 0
	v_mov_b32_e32 v71, 0
	v_writelane_b32 v236, s1, 19
	s_add_u32 s0, s78, 0x1900
	s_addc_u32 s1, s79, 0
	v_writelane_b32 v236, s0, 20
	s_movk_i32 s7, 0x2100
	s_mov_b32 s99, 0xbfb8aa3b
	v_writelane_b32 v236, s1, 21
	s_add_u32 s0, s54, 0x2b40000
	s_addc_u32 s1, s55, 0
	v_writelane_b32 v236, s0, 22
	s_mov_b32 s88, 0x800000
	s_mov_b32 s89, 0x3f317217
	v_writelane_b32 v236, s1, 23
	s_add_u32 s0, s54, 0x2b50000
	s_addc_u32 s1, s55, 0
	v_writelane_b32 v236, s0, 24
	s_mov_b32 s38, 0x7f800000
	v_mov_b32_e32 v73, 0x41b17218
	v_writelane_b32 v236, s1, 25
	s_add_u32 s0, s54, 0xfc18000
	v_writelane_b32 v236, s0, 26
	s_addc_u32 s0, s55, 0
	v_writelane_b32 v236, s0, 27
	s_add_u32 s0, s54, 0xb414800
	v_writelane_b32 v236, s0, 28
	s_addc_u32 s0, s55, 0
	v_writelane_b32 v236, s0, 29
	s_add_u32 s0, s54, 0xd814800
	v_writelane_b32 v236, s0, 30
	s_addc_u32 s0, s55, 0
	v_writelane_b32 v236, s0, 31
	s_add_u32 s0, s54, 0xc614800
	v_writelane_b32 v236, s0, 32
	s_addc_u32 s0, s55, 0
	v_writelane_b32 v236, s0, 33
	s_add_i32 s0, 0, 0x12000
	s_mov_b32 s90, s33
	s_and_b32 s2, s33, 0x7f
	s_lshr_b32 s3, s33, 8
	s_lshl_b32 s3, s3, 7
	s_or_b32 s2, s2, s3
	s_addk_i32 s2, 0x800
	s_bitcmp0_b32 s33, 7
	s_cselect_b32 s90, s33, s2
	v_writelane_b32 v236, s0, 34
	s_branch .LBB0_199
.LBB0_198:
	s_or_b64 exec, exec, s[0:1]
	s_add_i32 s101, s101, 1
	v_readlane_b32 s2, v236, 3
	s_bitcmp0_b32 s2, 7
	s_cselect_b32 s4, 4, 5
	s_cselect_b32 s3, 0, 1
	s_sub_i32 s3, s101, s3
	s_lshl_b32 s3, s3, 9
	s_add_i32 s90, s2, s3
	s_cmp_lt_u32 s101, s4
	s_cselect_b32 s90, s90, 0x7fff
	s_cmpk_ge_i32 s90, 0x800
	s_cbranch_scc1 .Lp2_nopoll
	s_and_b32 s3, s90, 0x7f
	s_cmp_ge_u32 s3, 0x7e
	s_cselect_b32 s3, 1, 0
	s_cmpk_ge_i32 s90, 0x400
	s_cselect_b32 s3, 1, s3
	s_cmp_eq_u32 s3, 0
	s_cbranch_scc1 .Lp2_nopoll
	s_and_saveexec_b64 s[0:1], s[34:35]
	s_cbranch_execz .Lpl_end_n
	s_add_u32 s12, s54, 0xfc14808
	s_addc_u32 s13, s55, 0
	v_mov_b32_e32 v240, 0
	s_mov_b32 s5, 0

; DI void phase_rwkv_prep(const Params& p, char* lds) {
;     ...
;     for (int u = blockIdx.x; u < NUNIT; u += gridDim.x) {
.Lp2_nopoll:
	s_cmpk_lt_i32 s90, 0x900
	s_barrier
	s_cbranch_scc0 .LBB0_315

; #define LAS __attribute__((address_space(3)))
; DI void phase_scan_attn(const Params& p, char* lds) {
;     const int tid = threadIdx.x, lane = tid & 63, wave = __builtin_amdgcn_readfirstlane(tid >> 6);
;     if (blockIdx.x < 64) {
;         if (wave == 0) { const int x_ = blockIdx.x & 7, k_ = blockIdx.x >> 3;
;             scan_item(p, (x_ + 8 * (k_ >> 2)) * 4 + (k_ & 3), lane); }
;         return;
;     }
;     unsigned* ctr = (unsigned*)(p.ws + W_BAR) + 3456;
;     volatile LAS int* slot = (volatile LAS int*)(lds + 75264);
;     const int q0 = (int)((unsigned)__builtin_amdgcn_s_getreg((3 << 11) | 20) & 7u);
.Lp3_ret:
	v_readfirstlane_b32 s11, v0
	s_mov_b64 s[0:1], -1
	s_cmp_gt_u32 s33, 63
	v_and_b32_e32 v223, 15, v0
	v_and_b32_e32 v220, 48, v218
	s_waitcnt lgkmcnt(0)
	s_barrier
	s_cmp_eq_u32 s100, 3
	s_cbranch_scc1 .Lp3_skip
	s_cmp_lt_u32 s33, 0x1fc
	s_cbranch_scc1 .Lp3_skip
	s_mov_b32 s100, 2
	s_sub_u32 s96, s52, 0xfc0000
	s_subb_u32 s97, s53, 0
	v_writelane_b32 v237, s96, 4
	s_add_i32 s33, s33, 0xf04
	v_writelane_b32 v237, s97, 5
	s_branch .Llt_common
.Lp3_skip:
	s_cmp_gt_u32 s33, 63
	s_cbranch_scc0 .LBB0_435
	s_lshr_b32 s41, s11, 6
	s_add_u32 s38, s54, 0xfc17e00
	s_addc_u32 s39, s55, 0
	s_lshr_b32 s0, s11, 2
	v_and_or_b32 v6, s0, 48, v223
	v_lshlrev_b32_e32 v158, 8, v6
	v_mov_b32_e32 v159, 0
	v_lshl_add_u64 v[2:3], s[64:65], 0, v[158:159]
	v_mov_b32_e32 v221, v159
	v_lshl_add_u64 v[160:161], v[2:3], 0, v[220:221]
	v_lshl_add_u64 v[2:3], s[54:55], 0, v[220:221]
	v_lshlrev_b32_e32 v4, 7, v223
	v_mov_b32_e32 v5, v159
	v_lshl_add_u64 v[2:3], v[2:3], 0, v[4:5]
	s_mov_b64 s[0:1], 0xb414800
	v_lshl_add_u64 v[162:163], v[2:3], 0, s[0:1]
	v_lshlrev_b32_e32 v2, 7, v6
	v_mov_b32_e32 v3, v159
	v_lshl_add_u64 v[2:3], s[54:55], 0, v[2:3]
	v_lshl_add_u64 v[2:3], v[2:3], 0, v[220:221]
	s_mov_b64 s[0:1], 0xc614800
	v_lshl_add_u64 v[164:165], v[2:3], 0, s[0:1]
	s_mov_b64 s[0:1], 0xea14800
	v_lshl_add_u64 v[166:167], v[2:3], 0, s[0:1]
	v_lshl_add_u64 v[2:3], s[52:53], 0, v[158:159]
	s_getreg_b32 s40, hwreg(HW_REG_XCC_ID, 0, 4)
	v_lshl_add_u64 v[2:3], v[2:3], 0, v[220:221]
	s_mov_b64 s[0:1], 0x4840000
	s_add_i32 s44, 0, 0x12600
	s_addk_i32 s41, 0xfd80
	v_lshl_add_u64 v[168:169], v[2:3], 0, s[0:1]
	s_mov_b32 s5, 0
	s_movk_i32 s42, 0x2000
	s_movk_i32 s43, 0x2100
	s_movk_i32 s45, 0x1000
	s_add_i32 s50, 0, 0xc000
	s_mov_b64 s[0:1], 0x400
	s_mov_b64 s[8:9], 0x800
	s_movk_i32 s51, 0x3000
	s_movk_i32 s64, 0xff80
	s_mov_b32 s10, 0x3e38aa3b
	s_mov_b32 s65, 0xff800000
	s_mov_b64 s[12:13], 0x2bf5400
	s_movk_i32 s70, 0xe700
	s_mov_b64 s[14:15], 0x1000
	s_mov_b64 s[16:17], 0x1800
	s_mov_b64 s[18:19], 0x2000
	s_mov_b64 s[20:21], 0x2800
	s_mov_b64 s[22:23], 0x3000
	s_mov_b64 s[24:25], 0x3800
	s_movk_i32 s71, 0x70
	s_movk_i32 s72, 0xfc
	s_movk_i32 s73, 0xff04
	v_mov_b32_e32 v186, s44
	v_mov_b32_e32 v187, 0x80
	s_mov_b32 s74, s40
	s_mov_b32 s75, 0
	s_branch .LBB0_371
